# packed fp32 VOP3P ops (v_pk_mul/add/fma_f32, 567 sites) split into the two scalar ops they stand for, bit-identical
# speedup vs baseline: 1.0005x; 1.0004x over previous
.LBB0_85:
	v_ashrrev_i32_e32 v41, 31, v40
	v_add_u32_e32 v0, s10, v40
	v_lshlrev_b64 v[22:23], 11, v[40:41]
	v_min_i32_e32 v46, 0x801f, v0
	v_lshl_add_u64 v[22:23], v[18:19], 0, v[22:23]
	v_ashrrev_i32_e32 v47, 31, v46
	global_load_dwordx2 v[24:25], v[22:23], off
	global_load_dwordx2 v[26:27], v[22:23], off offset:512
	global_load_dwordx2 v[28:29], v[22:23], off offset:1024
	global_load_dwordx2 v[30:31], v[22:23], off offset:1536
	v_lshlrev_b64 v[22:23], 11, v[46:47]
	v_lshl_add_u64 v[22:23], v[18:19], 0, v[22:23]
	global_load_dwordx2 v[32:33], v[22:23], off
	global_load_dwordx2 v[42:43], v[22:23], off offset:512
	global_load_dwordx2 v[54:55], v[22:23], off offset:1024
	global_load_dwordx2 v[56:57], v[22:23], off offset:1536
	v_add_u32_e32 v22, s11, v40
	v_min_i32_e32 v22, 0x801f, v22
	v_ashrrev_i32_e32 v23, 31, v22
	v_lshlrev_b64 v[34:35], 11, v[22:23]
	v_lshl_add_u64 v[58:59], v[18:19], 0, v[34:35]
	global_load_dwordx2 v[44:45], v[58:59], off
	s_mov_b32 s2, 0x358637bd
	v_lshlrev_b64 v[46:47], 12, v[46:47]
	v_lshl_add_u64 v[46:47], v[20:21], 0, v[46:47]
	v_lshlrev_b64 v[22:23], 12, v[22:23]
	s_waitcnt vmcnt(8)
	v_and_b32_e32 v61, 0xffff0000, v24
	s_waitcnt vmcnt(7)
	v_and_b32_e32 v65, 0xffff0000, v26
	v_lshlrev_b32_e32 v60, 16, v24
	v_lshlrev_b32_e32 v62, 16, v25
	v_and_b32_e32 v63, 0xffff0000, v25
	v_lshlrev_b32_e32 v64, 16, v26
	v_mov_b32_e32 v24, v61
	v_mov_b32_e32 v25, v65
	s_waitcnt vmcnt(6)
	v_and_b32_e32 v69, 0xffff0000, v28
	s_waitcnt vmcnt(5)
	v_and_b32_e32 v73, 0xffff0000, v30
	v_mov_b32_e32 v76, v60
	v_mov_b32_e32 v77, v64
	v_mul_f32_e32 v88, v24, v24
	v_mul_f32_e32 v89, v25, v25
	s_waitcnt vmcnt(4)
	v_and_b32_e32 v39, 0xffff0000, v32
	s_waitcnt vmcnt(3)
	v_and_b32_e32 v35, 0xffff0000, v42
	v_lshlrev_b32_e32 v66, 16, v27
	v_and_b32_e32 v67, 0xffff0000, v27
	v_mov_b32_e32 v26, v69
	v_mov_b32_e32 v27, v73
	v_lshlrev_b32_e32 v38, 16, v32
	v_lshlrev_b32_e32 v36, 16, v33
	v_and_b32_e32 v37, 0xffff0000, v33
	v_lshlrev_b32_e32 v34, 16, v42
	v_lshlrev_b32_e32 v32, 16, v43
	v_and_b32_e32 v33, 0xffff0000, v43
	v_fma_f32 v42, v76, v76, v88
	v_fma_f32 v43, v77, v77, v89
	v_mov_b32_e32 v76, v39
	v_mov_b32_e32 v77, v35
	v_lshlrev_b32_e32 v68, 16, v28
	v_lshlrev_b32_e32 v72, 16, v30
	v_lshlrev_b32_e32 v74, 16, v31
	v_and_b32_e32 v75, 0xffff0000, v31
	v_mul_f32_e32 v90, v26, v26
	v_mul_f32_e32 v91, v27, v27
	s_waitcnt vmcnt(2)
	v_and_b32_e32 v31, 0xffff0000, v54
	s_waitcnt vmcnt(1)
	v_lshlrev_b32_e32 v26, 16, v56
	v_and_b32_e32 v27, 0xffff0000, v56
	v_lshlrev_b32_e32 v24, 16, v57
	v_and_b32_e32 v25, 0xffff0000, v57
	v_mov_b32_e32 v56, v38
	v_mov_b32_e32 v57, v34
	v_mul_f32_e32 v76, v76, v76
	v_mul_f32_e32 v77, v77, v77
	v_mov_b32_e32 v82, v68
	v_mov_b32_e32 v83, v72
	v_lshlrev_b32_e32 v30, 16, v54
	v_fma_f32 v56, v56, v56, v76
	v_fma_f32 v57, v57, v57, v77
	v_mov_b32_e32 v76, v31
	v_mov_b32_e32 v77, v27
	v_lshlrev_b32_e32 v70, 16, v29
	v_and_b32_e32 v71, 0xffff0000, v29
	v_mov_b32_e32 v78, v62
	v_mov_b32_e32 v79, v66
	v_lshlrev_b32_e32 v28, 16, v55
	v_and_b32_e32 v29, 0xffff0000, v55
	v_fma_f32 v54, v82, v82, v90
	v_fma_f32 v55, v83, v83, v91
	v_mov_b32_e32 v82, v36
	v_mov_b32_e32 v83, v32
	v_mov_b32_e32 v90, v30
	v_mov_b32_e32 v91, v26
	v_mul_f32_e32 v76, v76, v76
	v_mul_f32_e32 v77, v77, v77
	v_mov_b32_e32 v80, v63
	v_mov_b32_e32 v81, v67
	v_mov_b32_e32 v84, v70
	v_mov_b32_e32 v85, v74
	v_mov_b32_e32 v88, v37
	v_mov_b32_e32 v89, v33
	v_fma_f32 v42, v78, v78, v42
	v_fma_f32 v43, v79, v79, v43
	v_fma_f32 v56, v82, v82, v56
	v_fma_f32 v57, v83, v83, v57
	v_fma_f32 v76, v90, v90, v76
	v_fma_f32 v77, v91, v91, v77
	v_mov_b32_e32 v78, v28
	v_mov_b32_e32 v79, v24
	v_mov_b32_e32 v86, v71
	v_mov_b32_e32 v87, v75
	v_fma_f32 v54, v84, v84, v54
	v_fma_f32 v55, v85, v85, v55
	v_fma_f32 v42, v80, v80, v42
	v_fma_f32 v43, v81, v81, v43
	v_fma_f32 v56, v88, v88, v56
	v_fma_f32 v57, v89, v89, v57
	v_mov_b32_e32 v80, v29
	v_mov_b32_e32 v81, v25
	v_fma_f32 v76, v78, v78, v76
	v_fma_f32 v77, v79, v79, v77
	v_fma_f32 v54, v86, v86, v54
	v_fma_f32 v55, v87, v87, v55
	v_fma_f32 v76, v80, v80, v76
	v_fma_f32 v77, v81, v81, v77
	v_mov_b32_e32 v78, v56
	v_mov_b32_e32 v79, v42
	v_mov_b32_e32 v42, v57
	v_add_f32_e32 v42, v78, v42
	v_add_f32_e32 v43, v79, v43
	v_mov_b32_e32 v56, v76
	v_mov_b32_e32 v57, v54
	v_add_f32_e32 v42, v42, v56
	v_add_f32_e32 v43, v43, v57
	v_mov_b32_e32 v54, v77
	v_add_f32_e32 v42, v42, v54
	v_add_f32_e32 v43, v43, v55
	ds_bpermute_b32 v55, v48, v43
	ds_bpermute_b32 v54, v48, v42
	global_load_dwordx2 v[76:77], v[58:59], off offset:512
	global_load_dwordx2 v[78:79], v[58:59], off offset:1024
	v_add_u32_e32 v80, s12, v40
	global_load_dwordx2 v[58:59], v[58:59], off offset:1536
	v_lshlrev_b64 v[88:89], 12, v[40:41]
	s_waitcnt lgkmcnt(0)
	v_add_f32_e32 v42, v42, v54
	v_add_f32_e32 v43, v43, v55
	ds_bpermute_b32 v55, v49, v43
	ds_bpermute_b32 v54, v49, v42
	v_mov_b64_e32 v[40:41], s[2:3]
	v_lshl_add_u64 v[88:89], v[20:21], 0, v[88:89]
	s_add_i32 s2, s10, s10
	s_add_i32 s2, s2, s10
	s_waitcnt lgkmcnt(0)
	v_add_f32_e32 v42, v42, v54
	v_add_f32_e32 v43, v43, v55
	ds_bpermute_b32 v55, v50, v43
	ds_bpermute_b32 v54, v50, v42
	s_waitcnt lgkmcnt(0)
	v_add_f32_e32 v42, v42, v54
	v_add_f32_e32 v43, v43, v55
	ds_bpermute_b32 v55, v51, v43
	ds_bpermute_b32 v54, v51, v42
	s_waitcnt lgkmcnt(0)
	v_add_f32_e32 v54, v42, v54
	v_add_f32_e32 v55, v43, v55
	v_min_i32_e32 v42, 0x801f, v80
	v_ashrrev_i32_e32 v43, 31, v42
	v_lshlrev_b64 v[80:81], 11, v[42:43]
	v_lshl_add_u64 v[80:81], v[18:19], 0, v[80:81]
	global_load_dwordx2 v[82:83], v[80:81], off
	global_load_dwordx2 v[84:85], v[80:81], off offset:512
	global_load_dwordx2 v[86:87], v[80:81], off offset:1024
	s_nop 0
	global_load_dwordx2 v[80:81], v[80:81], off offset:1536
	ds_bpermute_b32 v57, v52, v55
	ds_bpermute_b32 v56, v52, v54
	s_waitcnt lgkmcnt(0)
	v_add_f32_e32 v54, v54, v56
	v_add_f32_e32 v55, v55, v57
	ds_bpermute_b32 v57, v53, v55
	ds_bpermute_b32 v56, v53, v54
	s_waitcnt lgkmcnt(0)
	v_add_f32_e32 v54, v54, v56
	v_add_f32_e32 v55, v55, v57
	s_nop 0
	v_fma_f32 v90, v54, s16, v40
	v_fma_f32 v91, v55, s16, v40
	s_nop 0
	v_mul_f32_e32 v54, 0x4b800000, v91
	v_cmp_gt_f32_e32 vcc, s14, v91
	s_nop 1
	v_cndmask_b32_e32 v54, v91, v54, vcc
	v_rsq_f32_e32 v54, v54
	s_waitcnt vmcnt(1)
	v_and_b32_e32 v91, 0xffff0000, v86
	v_mul_f32_e32 v55, 0x45800000, v54
	v_cndmask_b32_e32 v92, v54, v55, vcc
	v_mul_f32_e32 v54, v92, v60
	v_mul_f32_e32 v55, v92, v61
	v_mul_f32_e32 v56, v92, v62
	v_mul_f32_e32 v57, v92, v63
	v_mul_f32_e32 v54, v2, v54
	v_mul_f32_e32 v55, v3, v55
	v_mul_f32_e32 v56, v4, v56
	v_mul_f32_e32 v57, v5, v57
	global_store_dwordx4 v[88:89], v[54:57], off
	v_mul_f32_e32 v60, 0x4b800000, v90
	v_cmp_gt_f32_e32 vcc, s14, v90
	v_mul_f32_e32 v54, v92, v64
	v_mul_f32_e32 v55, v92, v65
	v_mul_f32_e32 v56, v92, v66
	v_mul_f32_e32 v57, v92, v67
	v_mul_f32_e32 v54, v6, v54
	v_mul_f32_e32 v55, v7, v55
	v_mul_f32_e32 v56, v8, v56
	v_mul_f32_e32 v57, v9, v57
	global_store_dwordx4 v[88:89], v[54:57], off offset:1024
	v_cndmask_b32_e32 v60, v90, v60, vcc
	v_and_b32_e32 v61, 0xffff0000, v44
	v_mul_f32_e32 v54, v92, v68
	v_mul_f32_e32 v55, v92, v69
	v_mul_f32_e32 v56, v92, v70
	v_mul_f32_e32 v57, v92, v71
	v_mul_f32_e32 v54, v10, v54
	v_mul_f32_e32 v55, v11, v55
	v_mul_f32_e32 v56, v12, v56
	v_mul_f32_e32 v57, v13, v57
	v_and_b32_e32 v63, 0xffff0000, v76
	global_store_dwordx4 v[88:89], v[54:57], off offset:2048
	v_rsq_f32_e32 v102, v60
	v_lshlrev_b32_e32 v60, 16, v44
	v_mul_f32_e32 v56, v92, v74
	v_mul_f32_e32 v57, v92, v75
	v_lshlrev_b32_e32 v62, 16, v76
	v_mov_b32_e32 v74, v61
	v_mov_b32_e32 v75, v63
	v_mul_f32_e32 v54, v92, v72
	v_mul_f32_e32 v55, v92, v73
	v_lshlrev_b32_e32 v44, 16, v45
	v_lshlrev_b32_e32 v64, 16, v77
	v_mov_b32_e32 v72, v60
	v_mov_b32_e32 v73, v62
	v_mul_f32_e32 v74, v74, v74
	v_mul_f32_e32 v75, v75, v75
	v_and_b32_e32 v45, 0xffff0000, v45
	v_and_b32_e32 v65, 0xffff0000, v77
	v_fma_f32 v72, v72, v72, v74
	v_fma_f32 v73, v73, v73, v75
	v_mov_b32_e32 v74, v44
	v_mov_b32_e32 v75, v64
	v_and_b32_e32 v67, 0xffff0000, v78
	v_and_b32_e32 v71, 0xffff0000, v58
	v_mov_b32_e32 v76, v45
	v_mov_b32_e32 v77, v65
	v_fma_f32 v72, v74, v74, v72
	v_fma_f32 v73, v75, v75, v73
	v_lshlrev_b32_e32 v66, 16, v78
	v_lshlrev_b32_e32 v70, 16, v58
	v_fma_f32 v72, v76, v76, v72
	v_fma_f32 v73, v77, v77, v73
	v_mov_b32_e32 v76, v67
	v_mov_b32_e32 v77, v71
	v_lshlrev_b32_e32 v68, 16, v79
	v_lshlrev_b32_e32 v58, 16, v59
	v_mov_b32_e32 v74, v66
	v_mov_b32_e32 v75, v70
	v_mul_f32_e32 v76, v76, v76
	v_mul_f32_e32 v77, v77, v77
	v_and_b32_e32 v69, 0xffff0000, v79
	v_and_b32_e32 v59, 0xffff0000, v59
	v_fma_f32 v74, v74, v74, v76
	v_fma_f32 v75, v75, v75, v77
	v_mov_b32_e32 v76, v68
	v_mov_b32_e32 v77, v58
	v_mov_b32_e32 v78, v69
	v_mov_b32_e32 v79, v59
	v_fma_f32 v74, v76, v76, v74
	v_fma_f32 v75, v77, v77, v75
	v_and_b32_e32 v77, 0xffff0000, v82
	v_fma_f32 v74, v78, v78, v74
	v_fma_f32 v75, v79, v79, v75
	v_lshlrev_b32_e32 v78, 16, v83
	v_and_b32_e32 v79, 0xffff0000, v83
	v_and_b32_e32 v83, 0xffff0000, v84
	v_lshlrev_b32_e32 v76, 16, v82
	v_lshlrev_b32_e32 v82, 16, v84
	v_mov_b32_e32 v96, v77
	v_mov_b32_e32 v97, v83
	v_lshlrev_b32_e32 v84, 16, v85
	v_mov_b32_e32 v94, v76
	v_mov_b32_e32 v95, v82
	v_mul_f32_e32 v96, v96, v96
	v_mul_f32_e32 v97, v97, v97
	v_and_b32_e32 v85, 0xffff0000, v85
	v_fma_f32 v94, v94, v94, v96
	v_fma_f32 v95, v95, v95, v97
	v_mov_b32_e32 v96, v78
	v_mov_b32_e32 v97, v84
	s_waitcnt vmcnt(3)
	v_and_b32_e32 v93, 0xffff0000, v80
	v_mov_b32_e32 v98, v79
	v_mov_b32_e32 v99, v85
	v_fma_f32 v94, v96, v96, v94
	v_fma_f32 v95, v97, v97, v95
	v_lshlrev_b32_e32 v90, 16, v86
	v_lshlrev_b32_e32 v92, 16, v80
	v_fma_f32 v94, v98, v98, v94
	v_fma_f32 v95, v99, v99, v95
	v_mov_b32_e32 v98, v91
	v_mov_b32_e32 v99, v93
	v_lshlrev_b32_e32 v86, 16, v87
	v_lshlrev_b32_e32 v80, 16, v81
	v_mov_b32_e32 v96, v90
	v_mov_b32_e32 v97, v92
	v_mul_f32_e32 v98, v98, v98
	v_mul_f32_e32 v99, v99, v99
	v_and_b32_e32 v87, 0xffff0000, v87
	v_and_b32_e32 v81, 0xffff0000, v81
	v_fma_f32 v96, v96, v96, v98
	v_fma_f32 v97, v97, v97, v99
	v_mov_b32_e32 v98, v86
	v_mov_b32_e32 v99, v80
	v_mov_b32_e32 v100, v87
	v_mov_b32_e32 v101, v81
	v_fma_f32 v96, v98, v98, v96
	v_fma_f32 v97, v99, v99, v97
	v_mov_b32_e32 v98, v94
	v_fma_f32 v96, v100, v100, v96
	v_fma_f32 v97, v101, v101, v97
	v_mov_b32_e32 v99, v72
	v_mov_b32_e32 v72, v95
	v_add_f32_e32 v72, v98, v72
	v_add_f32_e32 v73, v99, v73
	v_mov_b32_e32 v94, v96
	v_mov_b32_e32 v95, v74
	v_add_f32_e32 v72, v72, v94
	v_add_f32_e32 v73, v73, v95
	v_mov_b32_e32 v74, v97
	v_add_f32_e32 v72, v72, v74
	v_add_f32_e32 v73, v73, v75
	ds_bpermute_b32 v75, v48, v73
	ds_bpermute_b32 v74, v48, v72
	v_mul_f32_e32 v54, v14, v54
	v_mul_f32_e32 v55, v15, v55
	v_mul_f32_e32 v56, v16, v56
	v_mul_f32_e32 v57, v17, v57
	global_store_dwordx4 v[88:89], v[54:57], off offset:3072
	s_waitcnt lgkmcnt(0)
	v_add_f32_e32 v72, v72, v74
	v_add_f32_e32 v73, v73, v75
	ds_bpermute_b32 v75, v49, v73
	ds_bpermute_b32 v74, v49, v72
	v_mul_f32_e32 v54, 0x45800000, v102
	v_cndmask_b32_e32 v88, v102, v54, vcc
	v_mul_f32_e32 v38, v88, v38
	v_mul_f32_e32 v39, v88, v39
	v_mul_f32_e32 v36, v88, v36
	v_mul_f32_e32 v37, v88, v37
	v_mul_f32_e32 v54, v2, v38
	v_mul_f32_e32 v55, v3, v39
	v_mul_f32_e32 v56, v4, v36
	v_mul_f32_e32 v57, v5, v37
	s_waitcnt lgkmcnt(0)
	v_add_f32_e32 v38, v72, v74
	v_add_f32_e32 v39, v73, v75
	global_store_dwordx4 v[46:47], v[54:57], off
	ds_bpermute_b32 v55, v50, v39
	ds_bpermute_b32 v54, v50, v38
	v_mul_f32_e32 v32, v88, v32
	v_mul_f32_e32 v33, v88, v33
	v_mul_f32_e32 v36, v8, v32
	v_mul_f32_e32 v37, v9, v33
	v_mul_f32_e32 v34, v88, v34
	v_mul_f32_e32 v35, v88, v35
	v_mul_f32_e32 v34, v6, v34
	v_mul_f32_e32 v35, v7, v35
	s_waitcnt lgkmcnt(0)
	v_add_f32_e32 v32, v38, v54
	v_add_f32_e32 v33, v39, v55
	ds_bpermute_b32 v39, v51, v33
	ds_bpermute_b32 v38, v51, v32
	global_store_dwordx4 v[46:47], v[34:37], off offset:1024
	v_mul_f32_e32 v30, v88, v30
	v_mul_f32_e32 v31, v88, v31
	v_mul_f32_e32 v28, v88, v28
	v_mul_f32_e32 v29, v88, v29
	v_mul_f32_e32 v30, v10, v30
	v_mul_f32_e32 v31, v11, v31
	s_waitcnt lgkmcnt(0)
	v_add_f32_e32 v34, v32, v38
	v_add_f32_e32 v35, v33, v39
	ds_bpermute_b32 v37, v52, v35
	ds_bpermute_b32 v36, v52, v34
	v_mul_f32_e32 v32, v12, v28
	v_mul_f32_e32 v33, v13, v29
	global_store_dwordx4 v[46:47], v[30:33], off offset:2048
	v_mul_f32_e32 v26, v88, v26
	v_mul_f32_e32 v27, v88, v27
	v_mul_f32_e32 v24, v88, v24
	v_mul_f32_e32 v25, v88, v25
	s_waitcnt lgkmcnt(0)
	v_add_f32_e32 v30, v34, v36
	v_add_f32_e32 v31, v35, v37
	ds_bpermute_b32 v33, v53, v31
	ds_bpermute_b32 v32, v53, v30
	v_mul_f32_e32 v26, v14, v26
	v_mul_f32_e32 v27, v15, v27
	v_mul_f32_e32 v28, v16, v24
	v_mul_f32_e32 v29, v17, v25
	global_store_dwordx4 v[46:47], v[26:29], off offset:3072
	s_waitcnt lgkmcnt(0)
	v_add_f32_e32 v24, v30, v32
	v_add_f32_e32 v25, v31, v33
	s_nop 0
	v_fma_f32 v26, v24, s16, v40
	v_fma_f32 v27, v25, s16, v40
	v_lshl_add_u64 v[28:29], v[20:21], 0, v[22:23]
	v_mul_f32_e32 v24, 0x4b800000, v27
	v_cmp_gt_f32_e32 vcc, s14, v27
	v_lshlrev_b64 v[22:23], 12, v[42:43]
	v_lshl_add_u64 v[30:31], v[20:21], 0, v[22:23]
	v_cndmask_b32_e32 v24, v27, v24, vcc
	v_rsq_f32_e32 v24, v24
	v_add_u32_e32 v40, s2, v0
	v_mul_f32_e32 v22, 0x45800000, v24
	v_cndmask_b32_e32 v32, v24, v22, vcc
	v_mul_f32_e32 v22, v32, v60
	v_mul_f32_e32 v23, v32, v61
	v_mul_f32_e32 v24, v32, v44
	v_mul_f32_e32 v25, v32, v45
	v_mul_f32_e32 v22, v2, v22
	v_mul_f32_e32 v23, v3, v23
	v_mul_f32_e32 v24, v4, v24
	v_mul_f32_e32 v25, v5, v25
	global_store_dwordx4 v[28:29], v[22:25], off
	v_cmp_gt_f32_e32 vcc, s14, v26
	s_nop 0
	v_mul_f32_e32 v22, v32, v62
	v_mul_f32_e32 v23, v32, v63
	v_mul_f32_e32 v24, v32, v64
	v_mul_f32_e32 v25, v32, v65
	v_mul_f32_e32 v22, v6, v22
	v_mul_f32_e32 v23, v7, v23
	v_mul_f32_e32 v24, v8, v24
	v_mul_f32_e32 v25, v9, v25
	global_store_dwordx4 v[28:29], v[22:25], off offset:1024
	s_nop 1
	v_mul_f32_e32 v22, v32, v66
	v_mul_f32_e32 v23, v32, v67
	v_mul_f32_e32 v24, v32, v68
	v_mul_f32_e32 v25, v32, v69
	v_mul_f32_e32 v22, v10, v22
	v_mul_f32_e32 v23, v11, v23
	v_mul_f32_e32 v24, v12, v24
	v_mul_f32_e32 v25, v13, v25
	global_store_dwordx4 v[28:29], v[22:25], off offset:2048
	s_nop 1
	v_mul_f32_e32 v24, 0x4b800000, v26
	v_cndmask_b32_e32 v24, v26, v24, vcc
	v_rsq_f32_e32 v26, v24
	v_mul_f32_e32 v22, v32, v70
	v_mul_f32_e32 v23, v32, v71
	v_mul_f32_e32 v24, v32, v58
	v_mul_f32_e32 v25, v32, v59
	v_mul_f32_e32 v22, v14, v22
	v_mul_f32_e32 v23, v15, v23
	v_mul_f32_e32 v24, v16, v24
	v_mul_f32_e32 v25, v17, v25
	global_store_dwordx4 v[28:29], v[22:25], off offset:3072
	s_nop 1
	v_mul_f32_e32 v22, 0x45800000, v26
	v_cndmask_b32_e32 v26, v26, v22, vcc
	v_mul_f32_e32 v22, v26, v76
	v_mul_f32_e32 v23, v26, v77
	v_mul_f32_e32 v24, v26, v78
	v_mul_f32_e32 v25, v26, v79
	v_mul_f32_e32 v22, v2, v22
	v_mul_f32_e32 v23, v3, v23
	v_mul_f32_e32 v24, v4, v24
	v_mul_f32_e32 v25, v5, v25
	global_store_dwordx4 v[30:31], v[22:25], off
	v_cmp_lt_i32_e32 vcc, s13, v40
	s_or_b64 s[8:9], vcc, s[8:9]
	v_mul_f32_e32 v22, v26, v82
	v_mul_f32_e32 v23, v26, v83
	v_mul_f32_e32 v24, v26, v84
	v_mul_f32_e32 v25, v26, v85
	v_mul_f32_e32 v22, v6, v22
	v_mul_f32_e32 v23, v7, v23
	v_mul_f32_e32 v24, v8, v24
	v_mul_f32_e32 v25, v9, v25
	global_store_dwordx4 v[30:31], v[22:25], off offset:1024
	s_nop 1
	v_mul_f32_e32 v22, v26, v90
	v_mul_f32_e32 v23, v26, v91
	v_mul_f32_e32 v24, v26, v86
	v_mul_f32_e32 v25, v26, v87
	v_mul_f32_e32 v22, v10, v22
	v_mul_f32_e32 v23, v11, v23
	v_mul_f32_e32 v24, v12, v24
	v_mul_f32_e32 v25, v13, v25
	global_store_dwordx4 v[30:31], v[22:25], off offset:2048
	s_nop 1
	v_mul_f32_e32 v22, v26, v92
	v_mul_f32_e32 v23, v26, v93
	v_mul_f32_e32 v24, v26, v80
	v_mul_f32_e32 v25, v26, v81
	v_mul_f32_e32 v22, v14, v22
	v_mul_f32_e32 v23, v15, v23
	v_mul_f32_e32 v24, v16, v24
	v_mul_f32_e32 v25, v17, v25
	global_store_dwordx4 v[30:31], v[22:25], off offset:3072
	s_andn2_b64 exec, exec, s[8:9]
	s_cbranch_execnz .LBB0_85

.LBB0_138:
	s_cmpk_gt_i32 s37, 0x1ff
	s_mov_b64 s[4:5], -1
	s_cbranch_scc0 .LBB0_140
	v_mov_b32_e32 v60, v201
	s_lshl_b32 s2, s37, 6
	v_lshrrev_b32_e32 v0, 1, v60
	v_readlane_b32 s4, v254, 7
	v_ashrrev_i32_e32 v4, 5, v60
	s_addk_i32 s2, 0x8000
	v_and_b32_e32 v0, 12, v0
	v_readlane_b32 s5, v254, 8
	v_ashrrev_i32_e32 v5, 31, v4
	v_lshl_add_u64 v[56:57], v[4:5], 0, s[2:3]
	v_lshl_add_u64 v[2:3], s[4:5], 0, v[0:1]
	s_mov_b64 s[4:5], 0x8000
	s_mov_b64 s[6:7], 0x10000
	v_lshl_add_u64 v[4:5], v[56:57], 4, v[2:3]
	v_lshl_add_u64 v[6:7], v[56:57], 0, s[4:5]
	v_lshl_add_u64 v[10:11], v[56:57], 0, s[6:7]
	v_lshl_add_u64 v[8:9], v[6:7], 4, v[2:3]
	v_lshl_add_u64 v[12:13], v[10:11], 4, v[2:3]
	global_load_dword v61, v[4:5], off
	global_load_dword v62, v[8:9], off
	global_load_dword v63, v[12:13], off
	v_and_b32_e32 v0, 31, v60
	v_readlane_b32 s8, v254, 5
	v_lshlrev_b32_e32 v0, 4, v0
	v_readlane_b32 s9, v254, 6
	v_lshlrev_b64 v[4:5], 9, v[56:57]
	s_nop 0
	v_lshl_add_u64 v[8:9], s[8:9], 0, v[0:1]
	v_lshl_add_u64 v[4:5], v[8:9], 0, v[4:5]
	global_load_dwordx4 v[44:47], v[4:5], off
	v_lshlrev_b64 v[4:5], 9, v[6:7]
	v_lshl_add_u64 v[4:5], v[8:9], 0, v[4:5]
	v_lshlrev_b64 v[6:7], 9, v[10:11]
	v_lshl_add_u64 v[6:7], v[8:9], 0, v[6:7]
	global_load_dwordx4 v[48:51], v[4:5], off
	global_load_dwordx4 v[52:55], v[6:7], off
	v_add_u32_e32 v0, 0x200, v60
	v_ashrrev_i32_e32 v4, 5, v0
	v_ashrrev_i32_e32 v5, 31, v4
	v_lshl_add_u64 v[42:43], v[4:5], 0, s[2:3]
	v_lshl_add_u64 v[4:5], v[42:43], 4, v[2:3]
	v_lshl_add_u64 v[6:7], v[42:43], 0, s[4:5]
	v_lshl_add_u64 v[12:13], v[42:43], 0, s[6:7]
	v_lshlrev_b64 v[16:17], 9, v[42:43]
	v_lshl_add_u64 v[10:11], v[6:7], 4, v[2:3]
	v_lshl_add_u64 v[14:15], v[12:13], 4, v[2:3]
	v_lshl_add_u64 v[16:17], v[8:9], 0, v[16:17]
	global_load_dword v0, v[4:5], off
	global_load_dword v64, v[10:11], off
	global_load_dword v65, v[14:15], off
	global_load_dwordx4 v[26:29], v[16:17], off
	v_lshlrev_b64 v[4:5], 9, v[6:7]
	v_lshl_add_u64 v[4:5], v[8:9], 0, v[4:5]
	v_lshlrev_b64 v[6:7], 9, v[12:13]
	v_lshl_add_u64 v[6:7], v[8:9], 0, v[6:7]
	global_load_dwordx4 v[34:37], v[4:5], off
	global_load_dwordx4 v[30:33], v[6:7], off
	v_add_u32_e32 v4, 0x400, v60
	v_ashrrev_i32_e32 v4, 5, v4
	v_ashrrev_i32_e32 v5, 31, v4
	v_lshl_add_u64 v[40:41], v[4:5], 0, s[2:3]
	v_lshl_add_u64 v[12:13], v[40:41], 0, s[6:7]
	v_lshlrev_b64 v[16:17], 9, v[40:41]
	v_lshl_add_u64 v[4:5], v[40:41], 4, v[2:3]
	v_lshl_add_u64 v[6:7], v[40:41], 0, s[4:5]
	v_lshl_add_u64 v[14:15], v[12:13], 4, v[2:3]
	v_lshl_add_u64 v[16:17], v[8:9], 0, v[16:17]
	v_lshl_add_u64 v[10:11], v[6:7], 4, v[2:3]
	global_load_dword v66, v[4:5], off
	global_load_dword v67, v[10:11], off
	global_load_dword v68, v[14:15], off
	s_nop 0
	global_load_dwordx4 v[14:17], v[16:17], off
	v_lshlrev_b64 v[4:5], 9, v[6:7]
	v_lshl_add_u64 v[4:5], v[8:9], 0, v[4:5]
	v_lshlrev_b64 v[6:7], 9, v[12:13]
	v_lshl_add_u64 v[6:7], v[8:9], 0, v[6:7]
	global_load_dwordx4 v[22:25], v[4:5], off
	global_load_dwordx4 v[18:21], v[6:7], off
	v_add_u32_e32 v4, 0x600, v60
	v_ashrrev_i32_e32 v4, 5, v4
	v_ashrrev_i32_e32 v5, 31, v4
	v_lshl_add_u64 v[38:39], v[4:5], 0, s[2:3]
	v_lshl_add_u64 v[6:7], v[38:39], 0, s[4:5]
	v_lshl_add_u64 v[12:13], v[38:39], 0, s[6:7]
	v_lshl_add_u64 v[4:5], v[38:39], 4, v[2:3]
	v_lshl_add_u64 v[10:11], v[6:7], 4, v[2:3]
	v_lshl_add_u64 v[2:3], v[12:13], 4, v[2:3]
	v_lshlrev_b64 v[58:59], 9, v[38:39]
	v_lshl_add_u64 v[58:59], v[8:9], 0, v[58:59]
	global_load_dword v69, v[4:5], off
	global_load_dword v70, v[10:11], off
	global_load_dword v71, v[2:3], off
	s_nop 0
	global_load_dwordx4 v[2:5], v[58:59], off
	v_readlane_b32 s6, v254, 3
	v_readlane_b32 s7, v254, 4
	v_lshlrev_b64 v[6:7], 9, v[6:7]
	v_lshl_add_u64 v[6:7], v[8:9], 0, v[6:7]
	s_waitcnt vmcnt(19)
	v_max3_f32 v10, v61, v62, v63
	v_sub_f32_e32 v11, v61, v10
	v_mul_f32_e32 v11, 0x3fb8aa3b, v11
	v_exp_f32_e32 v58, v11
	v_sub_f32_e32 v11, v62, v10
	v_mul_f32_e32 v11, 0x3fb8aa3b, v11
	v_sub_f32_e32 v10, v63, v10
	v_exp_f32_e32 v59, v11
	v_mul_f32_e32 v10, 0x3fb8aa3b, v10
	v_exp_f32_e32 v61, v10
	v_lshlrev_b64 v[10:11], 9, v[12:13]
	v_add_f32_e32 v12, v58, v59
	v_lshl_add_u64 v[10:11], v[8:9], 0, v[10:11]
	v_add_f32_e32 v62, v61, v12
	v_div_scale_f32 v63, s[4:5], v62, v62, 1.0
	v_rcp_f32_e32 v72, v63
	global_load_dwordx4 v[6:9], v[6:7], off
	s_nop 0
	global_load_dwordx4 v[10:13], v[10:11], off
	v_fma_f32 v73, -v63, v72, 1.0
	v_fmac_f32_e32 v72, v73, v72
	v_div_scale_f32 v73, vcc, 1.0, v62, 1.0
	v_mul_f32_e32 v74, v73, v72
	v_fma_f32 v75, -v63, v74, v73
	v_fmac_f32_e32 v74, v75, v72
	v_fma_f32 v63, -v63, v74, v73
	v_div_fmas_f32 v63, v63, v72, v74
	v_div_fixup_f32 v62, v63, v62, 1.0
	v_mul_f32_e32 v59, v59, v62
	s_waitcnt vmcnt(19)
	v_lshlrev_b32_e32 v63, 16, v48
	v_and_b32_e32 v48, 0xffff0000, v48
	v_mul_f32_e32 v58, v58, v62
	v_mul_f32_e32 v61, v61, v62
	v_lshlrev_b32_e32 v62, 16, v44
	v_and_b32_e32 v44, 0xffff0000, v44
	v_mul_f32_e32 v48, v59, v48
	v_mul_f32_e32 v63, v59, v63
	v_fmac_f32_e32 v48, v58, v44
	s_waitcnt vmcnt(18)
	v_and_b32_e32 v44, 0xffff0000, v52
	v_fmac_f32_e32 v63, v58, v62
	v_lshlrev_b32_e32 v62, 16, v52
	v_fmac_f32_e32 v48, v61, v44
	v_lshlrev_b32_e32 v52, 16, v49
	v_fmac_f32_e32 v63, v61, v62
	v_cvt_pk_bf16_f32 v44, v63, v48
	v_lshlrev_b32_e32 v48, 16, v45
	v_mul_f32_e32 v52, v59, v52
	v_fmac_f32_e32 v52, v58, v48
	v_lshlrev_b32_e32 v48, 16, v53
	v_fmac_f32_e32 v52, v61, v48
	v_and_b32_e32 v48, 0xffff0000, v49
	v_and_b32_e32 v45, 0xffff0000, v45
	v_mul_f32_e32 v48, v59, v48
	v_fmac_f32_e32 v48, v58, v45
	v_and_b32_e32 v45, 0xffff0000, v53
	v_fmac_f32_e32 v48, v61, v45
	v_lshlrev_b32_e32 v49, 16, v50
	v_cvt_pk_bf16_f32 v45, v52, v48
	v_lshlrev_b32_e32 v48, 16, v46
	v_mul_f32_e32 v49, v59, v49
	v_fmac_f32_e32 v49, v58, v48
	v_lshlrev_b32_e32 v48, 16, v54
	v_fmac_f32_e32 v49, v61, v48
	v_and_b32_e32 v48, 0xffff0000, v50
	v_and_b32_e32 v46, 0xffff0000, v46
	v_mul_f32_e32 v48, v59, v48
	v_fmac_f32_e32 v48, v58, v46
	v_and_b32_e32 v46, 0xffff0000, v54
	v_fmac_f32_e32 v48, v61, v46
	v_cvt_pk_bf16_f32 v46, v49, v48
	v_lshlrev_b32_e32 v49, 16, v51
	s_waitcnt vmcnt(15)
	v_max3_f32 v50, v0, v64, v65
	v_lshlrev_b32_e32 v48, 16, v47
	v_mul_f32_e32 v49, v59, v49
	v_sub_f32_e32 v0, v0, v50
	v_fmac_f32_e32 v49, v58, v48
	v_lshlrev_b32_e32 v48, 16, v55
	v_mul_f32_e32 v0, 0x3fb8aa3b, v0
	v_fmac_f32_e32 v49, v61, v48
	v_and_b32_e32 v48, 0xffff0000, v51
	v_exp_f32_e32 v51, v0
	v_sub_f32_e32 v0, v64, v50
	v_mul_f32_e32 v0, 0x3fb8aa3b, v0
	v_exp_f32_e32 v52, v0
	v_sub_f32_e32 v0, v65, v50
	v_mul_f32_e32 v0, 0x3fb8aa3b, v0
	v_exp_f32_e32 v50, v0
	v_add_f32_e32 v53, v51, v52
	v_and_b32_e32 v47, 0xffff0000, v47
	v_mul_f32_e32 v48, v59, v48
	v_add_f32_e32 v53, v50, v53
	v_fmac_f32_e32 v48, v58, v47
	v_and_b32_e32 v47, 0xffff0000, v55
	v_div_scale_f32 v54, s[4:5], v53, v53, 1.0
	v_fmac_f32_e32 v48, v61, v47
	v_rcp_f32_e32 v55, v54
	v_cvt_pk_bf16_f32 v47, v49, v48
	v_lshlrev_b64 v[48:49], 11, v[56:57]
	v_lshlrev_b32_e32 v0, 4, v60
	v_lshl_add_u64 v[48:49], s[6:7], 0, v[48:49]
	v_and_b32_e32 v0, 0x1f0, v0
	v_lshl_add_u64 v[48:49], v[48:49], 0, v[0:1]
	global_store_dwordx4 v[48:49], v[44:47], off offset:512
	s_waitcnt vmcnt(14)
	v_lshlrev_b32_e32 v48, 16, v34
	v_and_b32_e32 v34, 0xffff0000, v34
	v_fma_f32 v44, -v54, v55, 1.0
	v_fmac_f32_e32 v55, v44, v55
	v_div_scale_f32 v44, vcc, 1.0, v53, 1.0
	v_mul_f32_e32 v45, v44, v55
	v_fma_f32 v46, -v54, v45, v44
	v_fmac_f32_e32 v45, v46, v55
	v_fma_f32 v44, -v54, v45, v44
	v_div_fmas_f32 v44, v44, v55, v45
	v_div_fixup_f32 v44, v44, v53, 1.0
	v_mul_f32_e32 v46, v52, v44
	v_mul_f32_e32 v45, v51, v44
	v_lshlrev_b32_e32 v47, 16, v26
	v_and_b32_e32 v26, 0xffff0000, v26
	v_mul_f32_e32 v34, v46, v34
	v_mul_f32_e32 v44, v50, v44
	v_mul_f32_e32 v48, v46, v48
	v_fmac_f32_e32 v34, v45, v26
	s_waitcnt vmcnt(13)
	v_and_b32_e32 v26, 0xffff0000, v30
	v_fmac_f32_e32 v48, v45, v47
	v_lshlrev_b32_e32 v47, 16, v30
	v_fmac_f32_e32 v34, v44, v26
	v_fmac_f32_e32 v48, v44, v47
	v_cvt_pk_bf16_f32 v26, v48, v34
	v_lshlrev_b32_e32 v34, 16, v35
	v_lshlrev_b32_e32 v30, 16, v27
	v_mul_f32_e32 v34, v46, v34
	v_fmac_f32_e32 v34, v45, v30
	v_lshlrev_b32_e32 v30, 16, v31
	v_fmac_f32_e32 v34, v44, v30
	v_and_b32_e32 v30, 0xffff0000, v35
	v_and_b32_e32 v27, 0xffff0000, v27
	v_mul_f32_e32 v30, v46, v30
	v_fmac_f32_e32 v30, v45, v27
	v_and_b32_e32 v27, 0xffff0000, v31
	v_fmac_f32_e32 v30, v44, v27
	v_lshlrev_b32_e32 v31, 16, v36
	v_cvt_pk_bf16_f32 v27, v34, v30
	v_lshlrev_b32_e32 v30, 16, v28
	v_mul_f32_e32 v31, v46, v31
	v_fmac_f32_e32 v31, v45, v30
	v_lshlrev_b32_e32 v30, 16, v32
	v_fmac_f32_e32 v31, v44, v30
	v_and_b32_e32 v30, 0xffff0000, v36
	v_and_b32_e32 v28, 0xffff0000, v28
	v_mul_f32_e32 v30, v46, v30
	v_fmac_f32_e32 v30, v45, v28
	v_and_b32_e32 v28, 0xffff0000, v32
	v_fmac_f32_e32 v30, v44, v28
	v_cvt_pk_bf16_f32 v28, v31, v30
	v_lshlrev_b32_e32 v31, 16, v37
	v_lshlrev_b32_e32 v30, 16, v29
	v_mul_f32_e32 v31, v46, v31
	v_fmac_f32_e32 v31, v45, v30
	v_lshlrev_b32_e32 v30, 16, v33
	v_fmac_f32_e32 v31, v44, v30
	v_and_b32_e32 v30, 0xffff0000, v37
	v_and_b32_e32 v29, 0xffff0000, v29
	v_mul_f32_e32 v30, v46, v30
	v_fmac_f32_e32 v30, v45, v29
	v_and_b32_e32 v29, 0xffff0000, v33
	v_fmac_f32_e32 v30, v44, v29
	s_waitcnt vmcnt(10)
	v_max3_f32 v29, v66, v67, v68
	v_sub_f32_e32 v32, v66, v29
	v_sub_f32_e32 v33, v67, v29
	v_mul_f32_e32 v32, 0x3fb8aa3b, v32
	v_mul_f32_e32 v33, 0x3fb8aa3b, v33
	v_sub_f32_e32 v29, v68, v29
	v_exp_f32_e32 v32, v32
	v_exp_f32_e32 v33, v33
	v_mul_f32_e32 v29, 0x3fb8aa3b, v29
	v_exp_f32_e32 v34, v29
	v_cvt_pk_bf16_f32 v29, v31, v30
	v_add_f32_e32 v35, v32, v33
	v_lshlrev_b64 v[30:31], 11, v[42:43]
	v_add_f32_e32 v35, v34, v35
	v_div_scale_f32 v36, s[4:5], v35, v35, 1.0
	v_rcp_f32_e32 v37, v36
	v_lshl_add_u64 v[30:31], s[6:7], 0, v[30:31]
	v_lshl_add_u64 v[30:31], v[30:31], 0, v[0:1]
	global_store_dwordx4 v[30:31], v[26:29], off offset:512
	s_waitcnt vmcnt(9)
	v_lshlrev_b32_e32 v30, 16, v22
	v_and_b32_e32 v22, 0xffff0000, v22
	v_fma_f32 v26, -v36, v37, 1.0
	v_fmac_f32_e32 v37, v26, v37
	v_div_scale_f32 v26, vcc, 1.0, v35, 1.0
	v_mul_f32_e32 v27, v26, v37
	v_fma_f32 v28, -v36, v27, v26
	v_fmac_f32_e32 v27, v28, v37
	v_fma_f32 v26, -v36, v27, v26
	v_div_fmas_f32 v26, v26, v37, v27
	v_div_fixup_f32 v26, v26, v35, 1.0
	v_mul_f32_e32 v28, v33, v26
	v_mul_f32_e32 v27, v32, v26
	v_lshlrev_b32_e32 v29, 16, v14
	v_and_b32_e32 v14, 0xffff0000, v14
	v_mul_f32_e32 v22, v28, v22
	v_mul_f32_e32 v26, v34, v26
	v_mul_f32_e32 v30, v28, v30
	v_fmac_f32_e32 v22, v27, v14
	s_waitcnt vmcnt(8)
	v_and_b32_e32 v14, 0xffff0000, v18
	v_fmac_f32_e32 v30, v27, v29
	v_lshlrev_b32_e32 v29, 16, v18
	v_fmac_f32_e32 v22, v26, v14
	v_fmac_f32_e32 v30, v26, v29
	v_cvt_pk_bf16_f32 v14, v30, v22
	v_lshlrev_b32_e32 v22, 16, v23
	v_lshlrev_b32_e32 v18, 16, v15
	v_mul_f32_e32 v22, v28, v22
	v_fmac_f32_e32 v22, v27, v18
	v_lshlrev_b32_e32 v18, 16, v19
	v_fmac_f32_e32 v22, v26, v18
	v_and_b32_e32 v18, 0xffff0000, v23
	v_and_b32_e32 v15, 0xffff0000, v15
	v_mul_f32_e32 v18, v28, v18
	v_fmac_f32_e32 v18, v27, v15
	v_and_b32_e32 v15, 0xffff0000, v19
	v_fmac_f32_e32 v18, v26, v15
	v_lshlrev_b32_e32 v19, 16, v24
	v_cvt_pk_bf16_f32 v15, v22, v18
	v_lshlrev_b32_e32 v18, 16, v16
	v_mul_f32_e32 v19, v28, v19
	v_fmac_f32_e32 v19, v27, v18
	v_lshlrev_b32_e32 v18, 16, v20
	v_fmac_f32_e32 v19, v26, v18
	v_and_b32_e32 v18, 0xffff0000, v24
	v_and_b32_e32 v16, 0xffff0000, v16
	v_mul_f32_e32 v18, v28, v18
	v_fmac_f32_e32 v18, v27, v16
	v_and_b32_e32 v16, 0xffff0000, v20
	v_fmac_f32_e32 v18, v26, v16
	v_cvt_pk_bf16_f32 v16, v19, v18
	v_lshlrev_b32_e32 v19, 16, v25
	v_lshlrev_b32_e32 v18, 16, v17
	v_mul_f32_e32 v20, v28, v19
	v_fmac_f32_e32 v20, v27, v18
	v_lshlrev_b32_e32 v18, 16, v21
	v_fmac_f32_e32 v20, v26, v18
	v_and_b32_e32 v18, 0xffff0000, v25
	v_and_b32_e32 v17, 0xffff0000, v17
	v_mul_f32_e32 v22, v28, v18
	v_fmac_f32_e32 v22, v27, v17
	v_and_b32_e32 v17, 0xffff0000, v21
	v_fmac_f32_e32 v22, v26, v17
	s_waitcnt vmcnt(5)
	v_max3_f32 v17, v69, v70, v71
	v_sub_f32_e32 v18, v69, v17
	v_sub_f32_e32 v19, v70, v17
	v_mul_f32_e32 v18, 0x3fb8aa3b, v18
	v_mul_f32_e32 v19, 0x3fb8aa3b, v19
	v_sub_f32_e32 v17, v71, v17
	v_exp_f32_e32 v18, v18
	v_exp_f32_e32 v23, v19
	v_mul_f32_e32 v17, 0x3fb8aa3b, v17
	v_exp_f32_e32 v19, v17
	v_cvt_pk_bf16_f32 v17, v20, v22
	v_add_f32_e32 v22, v18, v23
	v_lshlrev_b64 v[20:21], 11, v[40:41]
	v_add_f32_e32 v22, v19, v22
	v_div_scale_f32 v24, s[4:5], v22, v22, 1.0
	v_rcp_f32_e32 v25, v24
	v_lshl_add_u64 v[20:21], s[6:7], 0, v[20:21]
	v_lshl_add_u64 v[20:21], v[20:21], 0, v[0:1]
	global_store_dwordx4 v[20:21], v[14:17], off offset:512
	s_waitcnt vmcnt(3)
	v_lshlrev_b32_e32 v20, 16, v10
	v_and_b32_e32 v10, 0xffff0000, v10
	v_fma_f32 v14, -v24, v25, 1.0
	v_fmac_f32_e32 v25, v14, v25
	v_div_scale_f32 v14, vcc, 1.0, v22, 1.0
	v_mul_f32_e32 v15, v14, v25
	v_fma_f32 v16, -v24, v15, v14
	v_fmac_f32_e32 v15, v16, v25
	v_fma_f32 v14, -v24, v15, v14
	v_div_fmas_f32 v14, v14, v25, v15
	v_div_fixup_f32 v14, v14, v22, 1.0
	v_mul_f32_e32 v16, v23, v14
	v_lshlrev_b32_e32 v15, 16, v2
	v_lshlrev_b32_e32 v17, 16, v6
	v_and_b32_e32 v6, 0xffff0000, v6
	v_mul_f32_e32 v17, v16, v17
	v_mul_f32_e32 v21, v16, v6
	v_lshlrev_b32_e32 v22, 16, v7
	v_and_b32_e32 v23, 0xffff0000, v7
	v_mul_f32_e32 v6, v18, v14
	v_mul_f32_e32 v7, v19, v14
	v_and_b32_e32 v2, 0xffff0000, v2
	v_fmac_f32_e32 v17, v6, v15
	v_lshlrev_b32_e32 v14, 16, v3
	v_lshlrev_b32_e32 v15, 16, v11
	v_fmac_f32_e32 v21, v6, v2
	v_mul_f32_e32 v14, v6, v14
	v_mul_f32_e32 v15, v7, v15
	v_fmac_f32_e32 v21, v7, v10
	v_fma_f32 v2, v16, v22, v14
	v_and_b32_e32 v11, 0xffff0000, v11
	v_and_b32_e32 v10, 0xffff0000, v3
	v_add_f32_e32 v14, v2, v15
	v_mul_f32_e32 v2, v6, v10
	v_mul_f32_e32 v3, v7, v11
	v_lshlrev_b32_e32 v10, 16, v4
	v_lshlrev_b32_e32 v11, 16, v12
	v_lshlrev_b32_e32 v24, 16, v8
	v_fma_f32 v2, v16, v23, v2
	v_mul_f32_e32 v10, v6, v10
	v_mul_f32_e32 v11, v7, v11
	v_add_f32_e32 v2, v2, v3
	v_fma_f32 v3, v16, v24, v10
	v_add_f32_e32 v3, v3, v11
	v_and_b32_e32 v11, 0xffff0000, v12
	v_and_b32_e32 v10, 0xffff0000, v4
	v_and_b32_e32 v8, 0xffff0000, v8
	v_mul_f32_e32 v10, v6, v10
	v_mul_f32_e32 v11, v7, v11
	v_lshlrev_b32_e32 v25, 16, v9
	v_fma_f32 v4, v16, v8, v10
	v_add_f32_e32 v4, v4, v11
	v_lshlrev_b32_e32 v10, 16, v5
	v_lshlrev_b32_e32 v11, 16, v13
	v_mul_f32_e32 v10, v6, v10
	v_mul_f32_e32 v11, v7, v11
	v_cvt_pk_bf16_f32 v3, v3, v4
	v_and_b32_e32 v8, 0xffff0000, v5
	v_fma_f32 v4, v16, v25, v10
	v_add_f32_e32 v10, v4, v11
	v_and_b32_e32 v11, 0xffff0000, v9
	v_and_b32_e32 v9, 0xffff0000, v13
	v_fmac_f32_e32 v17, v7, v20
	v_mul_f32_e32 v4, v6, v8
	v_mul_f32_e32 v5, v7, v9
	v_lshlrev_b64 v[6:7], 11, v[38:39]
	v_fma_f32 v4, v16, v11, v4
	v_lshl_add_u64 v[6:7], s[6:7], 0, v[6:7]
	v_add_f32_e32 v4, v4, v5
	v_lshl_add_u64 v[8:9], v[6:7], 0, v[0:1]
	s_mov_b64 s[4:5], 0x200
	v_cvt_pk_bf16_f32 v17, v17, v21
	v_cvt_pk_bf16_f32 v2, v14, v2
	v_cvt_pk_bf16_f32 v4, v10, v4
	v_lshl_add_u64 v[6:7], v[8:9], 0, s[4:5]
	global_store_dword v[8:9], v17, off offset:512
	s_mov_b64 s[4:5], 0

.Ls3m_cd:
.LBB0_266:
	s_or_b64 exec, exec, s[28:29]
	s_waitcnt lgkmcnt(0)
	s_barrier
	ds_read_b128 v[154:157], v109
	ds_read_b128 v[170:173], v142
	ds_read_b128 v[174:177], v142 offset:4352
	ds_read_b128 v[178:181], v142 offset:8704
	ds_read_b128 v[182:185], v142 offset:13056
	ds_read_b128 v[158:161], v109 offset:64
	ds_read_b128 v[186:189], v142 offset:64
	ds_read_b128 v[190:193], v142 offset:4416
	ds_read_b128 v[196:199], v142 offset:8768
	ds_read_b128 v[202:205], v142 offset:13120
	v_mul_f32_e32 v0, 0x3fb8aa3b, v0
	v_exp_f32_e32 v0, v0
	s_waitcnt lgkmcnt(5)
	v_mfma_f32_16x16x32_bf16 v[104:107], v[170:173], v[154:157], 0
	v_mfma_f32_16x16x32_bf16 v[100:103], v[174:177], v[154:157], 0
	v_mfma_f32_16x16x32_bf16 v[96:99], v[178:181], v[154:157], 0
	v_mfma_f32_16x16x32_bf16 v[92:95], v[182:185], v[154:157], 0
	ds_read_b128 v[162:165], v109 offset:128
	ds_read_b128 v[206:209], v142 offset:128
	ds_read_b128 v[210:213], v142 offset:4480
	ds_read_b128 v[214:217], v142 offset:8832
	ds_read_b128 v[218:221], v142 offset:13184
	s_waitcnt lgkmcnt(5)
	v_mfma_f32_16x16x32_bf16 v[104:107], v[186:189], v[158:161], v[104:107]
	v_mfma_f32_16x16x32_bf16 v[100:103], v[190:193], v[158:161], v[100:103]
	v_mfma_f32_16x16x32_bf16 v[96:99], v[196:199], v[158:161], v[96:99]
	v_mfma_f32_16x16x32_bf16 v[92:95], v[202:205], v[158:161], v[92:95]
	ds_read_b128 v[166:169], v109 offset:192
	ds_read_b128 v[222:225], v142 offset:192
	ds_read_b128 v[226:229], v142 offset:4544
	ds_read_b128 v[230:233], v142 offset:8896
	ds_read_b128 v[234:237], v142 offset:13248
	s_waitcnt lgkmcnt(5)
	v_mfma_f32_16x16x32_bf16 v[104:107], v[206:209], v[162:165], v[104:107]
	v_mfma_f32_16x16x32_bf16 v[100:103], v[210:213], v[162:165], v[100:103]
	v_mfma_f32_16x16x32_bf16 v[96:99], v[214:217], v[162:165], v[96:99]
	v_mfma_f32_16x16x32_bf16 v[92:95], v[218:221], v[162:165], v[92:95]
	s_waitcnt lgkmcnt(0)
	v_mfma_f32_16x16x32_bf16 v[104:107], v[222:225], v[166:169], v[104:107]
	v_mfma_f32_16x16x32_bf16 v[100:103], v[226:229], v[166:169], v[100:103]
	v_mfma_f32_16x16x32_bf16 v[96:99], v[230:233], v[166:169], v[96:99]
	v_mfma_f32_16x16x32_bf16 v[92:95], v[234:237], v[166:169], v[92:95]
	s_nop 7
	v_mul_f32_e32 v104, v0, v104
	v_mul_f32_e32 v105, v0, v105
	v_mul_f32_e32 v106, v0, v106
	v_mul_f32_e32 v107, v0, v107
	v_mul_f32_e32 v100, v0, v100
	v_mul_f32_e32 v101, v0, v101
	v_mul_f32_e32 v102, v0, v102
	v_mul_f32_e32 v103, v0, v103
	v_mul_f32_e32 v96, v0, v96
	v_mul_f32_e32 v97, v0, v97
	v_mul_f32_e32 v98, v0, v98
	v_mul_f32_e32 v99, v0, v99
	v_mul_f32_e32 v92, v0, v92
	v_mul_f32_e32 v93, v0, v93
	v_mul_f32_e32 v94, v0, v94
	v_mul_f32_e32 v95, v0, v95
	v_add_u32_e32 v0, v133, v121
	s_and_saveexec_b64 s[28:29], vcc
	s_cbranch_execnz .LBB0_273
	s_or_b64 exec, exec, s[28:29]
	s_and_saveexec_b64 s[28:29], s[4:5]
	s_cbranch_execnz .LBB0_274

.LBB0_271:
	s_or_b64 exec, exec, s[28:29]
	s_cmpk_eq_i32 s33, 0x200
	s_cselect_b32 s10, s41, s40
	s_cmpk_eq_i32 s33, 0x400
	s_cselect_b32 s10, s42, s10
	s_cmpk_eq_i32 s33, 0x600
	s_cselect_b32 s10, s43, s10
	v_lshlrev_b32_e32 v145, 16, v72
	v_lshlrev_b32_e32 v147, 16, v68
	v_and_b32_e32 v68, 0xffff0000, v68
	v_and_b32_e32 v72, 0xffff0000, v72
	v_mov_b32_e32 v0, s10
	v_lshlrev_b32_e32 v148, 16, v69
	v_lshlrev_b32_e32 v146, 16, v73
	v_and_b32_e32 v73, 0xffff0000, v73
	v_and_b32_e32 v69, 0xffff0000, v69
	s_addk_i32 s33, 0x200
	v_fma_f32 v104, v0, v145, v104
	v_mul_f32_e32 v145, 0xbfb8aa3b, v147
	v_exp_f32_e32 v145, v145
	v_fma_f32 v72, v0, v72, v105
	v_fmac_f32_e32 v107, v0, v73
	v_and_b32_e32 v73, 0xffff0000, v70
	v_add_f32_e32 v145, 1.0, v145
	v_rcp_f32_e32 v145, v145
	s_nop 0
	v_mul_f32_e32 v145, v145, v147
	v_mul_f32_e32 v145, v145, v104
	v_mul_f32_e32 v104, 0xbfb8aa3b, v68
	v_exp_f32_e32 v104, v104
	v_fmac_f32_e32 v144, v145, v145
	v_add_f32_e32 v104, 1.0, v104
	v_rcp_f32_e32 v104, v104
	s_nop 0
	v_mul_f32_e32 v68, v104, v68
	v_mul_f32_e32 v147, v68, v72
	v_mul_f32_e32 v72, 0xbfb8aa3b, v148
	v_exp_f32_e32 v72, v72
	v_fma_f32 v68, v0, v146, v106
	v_fmac_f32_e32 v144, v147, v147
	v_add_f32_e32 v72, 1.0, v72
	v_rcp_f32_e32 v72, v72
	s_nop 0
	v_mul_f32_e32 v72, v72, v148
	v_mul_f32_e32 v106, v72, v68
	v_lshlrev_b32_e32 v72, 16, v70
	v_mul_f32_e32 v70, 0xbfb8aa3b, v72
	v_exp_f32_e32 v70, v70
	v_mul_f32_e32 v68, 0xbfb8aa3b, v69
	v_exp_f32_e32 v68, v68
	v_fmac_f32_e32 v144, v106, v106
	v_add_f32_e32 v70, 1.0, v70
	v_rcp_f32_e32 v104, v70
	v_mul_f32_e32 v70, 0xbfb8aa3b, v73
	v_exp_f32_e32 v70, v70
	v_add_f32_e32 v68, 1.0, v68
	v_rcp_f32_e32 v68, v68
	v_add_f32_e32 v70, 1.0, v70
	v_rcp_f32_e32 v105, v70
	v_mul_f32_e32 v68, v68, v69
	v_mul_f32_e32 v107, v68, v107
	v_and_b32_e32 v69, 0xffff0000, v74
	v_lshlrev_b32_e32 v68, 16, v74
	v_fma_f32 v68, v0, v68, v100
	v_fma_f32 v69, v0, v69, v101
	v_mul_f32_e32 v72, v104, v72
	v_mul_f32_e32 v73, v105, v73
	v_fmac_f32_e32 v144, v107, v107
	v_mul_f32_e32 v68, v72, v68
	v_mul_f32_e32 v69, v73, v69
	v_lshlrev_b32_e32 v74, 16, v71
	v_mul_f32_e32 v72, v68, v68
	v_mul_f32_e32 v73, v69, v69
	s_nop 0
	v_add_f32_e32 v70, v72, v144
	v_add_f32_e32 v100, v73, v70
	v_and_b32_e32 v73, 0xffff0000, v75
	v_lshlrev_b32_e32 v72, 16, v75
	v_and_b32_e32 v75, 0xffff0000, v71
	v_mul_f32_e32 v70, 0xbfb8aa3b, v74
	v_mul_f32_e32 v71, 0xbfb8aa3b, v75
	v_exp_f32_e32 v70, v70
	v_exp_f32_e32 v71, v71
	v_fma_f32 v72, v0, v72, v102
	v_fma_f32 v73, v0, v73, v103
	v_add_f32_e32 v70, 1.0, v70
	v_add_f32_e32 v71, 1.0, v71
	v_rcp_f32_e32 v70, v70
	v_rcp_f32_e32 v71, v71
	s_nop 0
	v_mul_f32_e32 v70, v70, v74
	v_mul_f32_e32 v71, v71, v75
	s_nop 0
	v_mul_f32_e32 v74, v70, v72
	v_mul_f32_e32 v75, v71, v73
	v_cvt_pk_bf16_f32 v72, v68, v69
	v_lshl_add_u64 v[68:69], v[126:127], 0, s[34:35]
	v_mul_f32_e32 v70, v74, v74
	v_mul_f32_e32 v71, v75, v75
	v_cvt_pk_bf16_f32 v73, v74, v75
	s_add_u32 s34, s34, 0x80
	v_add_f32_e32 v70, v70, v100
	v_add_f32_e32 v100, v71, v70
	v_cvt_pk_bf16_f32 v70, v145, v147
	v_cvt_pk_bf16_f32 v71, v106, v107
	global_store_dwordx4 v[68:69], v[70:73], off offset:-64
	s_addc_u32 s35, s35, 0
	s_add_u32 s38, s38, 4
	v_lshlrev_b32_e32 v70, 16, v28
	v_and_b32_e32 v71, 0xffff0000, v28
	v_mul_f32_e32 v28, 0xbfb8aa3b, v70
	v_exp_f32_e32 v28, v28
	v_and_b32_e32 v73, 0xffff0000, v32
	v_lshlrev_b32_e32 v72, 16, v32
	v_fma_f32 v72, v0, v72, v96
	v_fma_f32 v73, v0, v73, v97
	v_add_f32_e32 v28, 1.0, v28
	v_rcp_f32_e32 v74, v28
	v_mul_f32_e32 v28, 0xbfb8aa3b, v71
	v_exp_f32_e32 v28, v28
	v_lshlrev_b32_e32 v32, 16, v29
	s_addc_u32 s39, s39, 0
	s_add_i32 s36, s36, 1
	v_add_f32_e32 v28, 1.0, v28
	v_rcp_f32_e32 v75, v28
	s_cmpk_lg_i32 s33, 0x800
	v_mul_f32_e32 v70, v74, v70
	v_mul_f32_e32 v71, v75, v71
	s_nop 0
	v_mul_f32_e32 v70, v70, v72
	v_mul_f32_e32 v71, v71, v73
	s_nop 0
	v_mul_f32_e32 v72, v70, v70
	v_mul_f32_e32 v73, v71, v71
	s_nop 0
	v_add_f32_e32 v28, v72, v100
	v_add_f32_e32 v74, v73, v28
	v_and_b32_e32 v73, 0xffff0000, v33
	v_lshlrev_b32_e32 v72, 16, v33
	v_and_b32_e32 v33, 0xffff0000, v29
	v_mul_f32_e32 v28, 0xbfb8aa3b, v32
	v_mul_f32_e32 v29, 0xbfb8aa3b, v33
	v_exp_f32_e32 v28, v28
	v_exp_f32_e32 v29, v29
	v_fma_f32 v72, v0, v72, v98
	v_fma_f32 v73, v0, v73, v99
	v_add_f32_e32 v28, 1.0, v28
	v_add_f32_e32 v29, 1.0, v29
	v_rcp_f32_e32 v28, v28
	v_rcp_f32_e32 v29, v29
	s_nop 0
	v_mul_f32_e32 v28, v28, v32
	v_mul_f32_e32 v29, v29, v33
	s_nop 0
	v_mul_f32_e32 v32, v28, v72
	v_mul_f32_e32 v33, v29, v73
	v_lshlrev_b32_e32 v72, 16, v30
	v_and_b32_e32 v73, 0xffff0000, v30
	v_mul_f32_e32 v30, 0xbfb8aa3b, v72
	v_exp_f32_e32 v30, v30
	v_mul_f32_e32 v28, v32, v32
	v_mul_f32_e32 v29, v33, v33
	v_add_f32_e32 v30, 1.0, v30
	v_add_f32_e32 v28, v28, v74
	v_rcp_f32_e32 v74, v30
	v_mul_f32_e32 v30, 0xbfb8aa3b, v73
	v_exp_f32_e32 v30, v30
	v_add_f32_e32 v96, v29, v28
	v_and_b32_e32 v29, 0xffff0000, v34
	v_lshlrev_b32_e32 v28, 16, v34
	v_add_f32_e32 v30, 1.0, v30
	v_rcp_f32_e32 v75, v30
	v_fma_f32 v28, v0, v28, v92
	v_fma_f32 v29, v0, v29, v93
	v_lshlrev_b32_e32 v34, 16, v31
	v_mul_f32_e32 v30, 0xbfb8aa3b, v34
	v_mul_f32_e32 v72, v74, v72
	v_mul_f32_e32 v73, v75, v73
	v_exp_f32_e32 v30, v30
	v_mul_f32_e32 v72, v72, v28
	v_mul_f32_e32 v73, v73, v29
	v_add_f32_e32 v30, 1.0, v30
	v_mul_f32_e32 v28, v72, v72
	v_mul_f32_e32 v29, v73, v73
	v_rcp_f32_e32 v30, v30
	v_add_f32_e32 v28, v28, v96
	v_add_f32_e32 v74, v29, v28
	v_and_b32_e32 v29, 0xffff0000, v35
	v_lshlrev_b32_e32 v28, 16, v35
	v_and_b32_e32 v35, 0xffff0000, v31
	v_fma_f32 v28, v0, v28, v94
	v_fma_f32 v29, v0, v29, v95
	v_mul_f32_e32 v0, 0xbfb8aa3b, v35
	v_exp_f32_e32 v0, v0
	s_nop 0
	v_add_f32_e32 v0, 1.0, v0
	v_rcp_f32_e32 v31, v0
	s_nop 0
	v_mul_f32_e32 v30, v30, v34
	v_mul_f32_e32 v31, v31, v35
	s_nop 0
	v_mul_f32_e32 v34, v30, v28
	v_mul_f32_e32 v35, v31, v29
	v_cvt_pk_bf16_f32 v30, v72, v73
	s_nop 0
	v_mul_f32_e32 v28, v34, v34
	v_mul_f32_e32 v29, v35, v35
	v_cvt_pk_bf16_f32 v31, v34, v35
	s_nop 0
	v_add_f32_e32 v0, v28, v74
	v_add_f32_e32 v144, v29, v0
	v_cvt_pk_bf16_f32 v28, v70, v71
	v_cvt_pk_bf16_f32 v29, v32, v33
	global_store_dwordx4 v[68:69], v[28:31], off
	s_waitcnt lgkmcnt(0)
	s_barrier
	s_cbranch_scc0 .LBB0_136
	s_waitcnt vmcnt(2)
	v_mov_b64_e32 v[68:69], v[84:85]
	v_mov_b64_e32 v[70:71], v[86:87]
	v_mov_b64_e32 v[28:29], v[88:89]
	v_mov_b64_e32 v[30:31], v[90:91]
	v_mov_b64_e32 v[72:73], v[76:77]
	v_mov_b64_e32 v[74:75], v[78:79]
	v_mov_b64_e32 v[32:33], v[80:81]
	v_mov_b64_e32 v[34:35], v[82:83]
	s_branch .LBB0_186
	s_nop 0
	s_nop 0
	s_nop 0
	s_nop 0
	s_nop 0
	s_nop 0
	s_nop 0
	s_nop 0
	s_nop 0
	s_nop 0
	s_nop 0
	s_nop 0
	s_nop 0
	s_nop 0
	s_nop 0
	s_nop 0
	s_nop 0
	s_nop 0

.LBB0_303:
	s_nop 0
	v_lshl_add_u64 v[22:23], s[18:19], 0, v[2:3]
	v_add_co_u32_e32 v24, vcc, 0x1f3e0000, v22
	v_lshl_add_u64 v[18:19], s[18:19], 0, v[4:5]
	s_mov_b64 s[10:11], 0x1b3e0000
	v_addc_co_u32_e32 v25, vcc, 0, v23, vcc
	s_mov_b64 s[16:17], 0x40000
	global_load_dword v26, v[24:25], off
	global_load_dword v28, v[24:25], off offset:32
	global_load_dword v30, v[24:25], off offset:64
	global_load_dword v32, v[24:25], off offset:96
	global_load_dword v34, v[24:25], off offset:128
	global_load_dword v36, v[24:25], off offset:160
	global_load_dword v38, v[24:25], off offset:192
	global_load_dword v40, v[24:25], off offset:224
	global_load_dword v22, v[24:25], off offset:256
	global_load_dword v16, v[24:25], off offset:288
	global_load_dword v14, v[24:25], off offset:320
	global_load_dword v12, v[24:25], off offset:352
	global_load_dword v10, v[24:25], off offset:384
	global_load_dword v8, v[24:25], off offset:416
	global_load_dword v6, v[24:25], off offset:448
	global_load_dword v0, v[24:25], off offset:480
	v_lshl_add_u64 v[80:81], v[18:19], 0, s[10:11]
	v_lshl_add_u64 v[82:83], v[80:81], 0, s[16:17]
	v_lshl_add_u64 v[84:85], v[82:83], 0, s[16:17]
	v_lshl_add_u64 v[86:87], v[84:85], 0, s[16:17]
	v_lshl_add_u64 v[88:89], v[86:87], 0, s[16:17]
	v_lshl_add_u64 v[90:91], v[88:89], 0, s[16:17]
	v_lshl_add_u64 v[92:93], v[90:91], 0, s[16:17]
	v_lshl_add_u64 v[94:95], v[92:93], 0, s[16:17]
	v_lshl_add_u64 v[96:97], v[94:95], 0, s[16:17]
	v_lshl_add_u64 v[98:99], v[96:97], 0, s[16:17]
	v_lshl_add_u64 v[100:101], v[98:99], 0, s[16:17]
	v_lshl_add_u64 v[102:103], v[100:101], 0, s[16:17]
	v_lshl_add_u64 v[104:105], v[102:103], 0, s[16:17]
	v_lshl_add_u64 v[106:107], v[104:105], 0, s[16:17]
	v_lshl_add_u64 v[108:109], v[106:107], 0, s[16:17]
	v_lshl_add_u64 v[110:111], v[108:109], 0, s[16:17]
	global_load_dwordx2 v[48:49], v[80:81], off
	global_load_dwordx2 v[50:51], v[82:83], off
	global_load_dwordx2 v[52:53], v[84:85], off
	global_load_dwordx2 v[54:55], v[86:87], off
	global_load_dwordx2 v[56:57], v[88:89], off
	global_load_dwordx2 v[58:59], v[90:91], off
	global_load_dwordx2 v[60:61], v[92:93], off
	global_load_dwordx2 v[62:63], v[94:95], off
	global_load_dwordx2 v[64:65], v[96:97], off
	global_load_dwordx2 v[66:67], v[98:99], off
	global_load_dwordx2 v[68:69], v[100:101], off
	global_load_dwordx2 v[70:71], v[102:103], off
	global_load_dwordx2 v[72:73], v[104:105], off
	global_load_dwordx2 v[74:75], v[106:107], off
	global_load_dwordx2 v[76:77], v[108:109], off
	global_load_dwordx2 v[78:79], v[110:111], off
	s_mov_b64 s[10:11], 0x400000
	v_lshl_add_u64 v[2:3], v[2:3], 0, s[12:13]
	v_lshl_add_u64 v[4:5], v[4:5], 0, s[10:11]
	s_add_i32 s2, s2, 16
	s_cmp_gt_u32 s2, 47
	s_waitcnt vmcnt(15)
	global_store_dwordx2 v[80:81], v[20:21], off
	v_fma_f32 v20, v20, v26, v48
	v_fma_f32 v21, v21, v26, v49
	s_waitcnt vmcnt(15)
	global_store_dwordx2 v[82:83], v[20:21], off
	v_fma_f32 v20, v20, v28, v50
	v_fma_f32 v21, v21, v28, v51
	s_waitcnt vmcnt(15)
	global_store_dwordx2 v[84:85], v[20:21], off
	v_fma_f32 v20, v20, v30, v52
	v_fma_f32 v21, v21, v30, v53
	s_waitcnt vmcnt(15)
	global_store_dwordx2 v[86:87], v[20:21], off
	v_fma_f32 v20, v20, v32, v54
	v_fma_f32 v21, v21, v32, v55
	s_waitcnt vmcnt(15)
	global_store_dwordx2 v[88:89], v[20:21], off
	v_fma_f32 v20, v20, v34, v56
	v_fma_f32 v21, v21, v34, v57
	s_waitcnt vmcnt(15)
	global_store_dwordx2 v[90:91], v[20:21], off
	v_fma_f32 v20, v20, v36, v58
	v_fma_f32 v21, v21, v36, v59
	s_waitcnt vmcnt(15)
	global_store_dwordx2 v[92:93], v[20:21], off
	v_fma_f32 v20, v20, v38, v60
	v_fma_f32 v21, v21, v38, v61
	s_waitcnt vmcnt(15)
	global_store_dwordx2 v[94:95], v[20:21], off
	v_fma_f32 v20, v20, v40, v62
	v_fma_f32 v21, v21, v40, v63
	s_waitcnt vmcnt(15)
	global_store_dwordx2 v[96:97], v[20:21], off
	v_fma_f32 v20, v20, v22, v64
	v_fma_f32 v21, v21, v22, v65
	s_waitcnt vmcnt(15)
	global_store_dwordx2 v[98:99], v[20:21], off
	v_fma_f32 v20, v20, v16, v66
	v_fma_f32 v21, v21, v16, v67
	s_waitcnt vmcnt(15)
	global_store_dwordx2 v[100:101], v[20:21], off
	v_fma_f32 v20, v20, v14, v68
	v_fma_f32 v21, v21, v14, v69
	s_waitcnt vmcnt(15)
	global_store_dwordx2 v[102:103], v[20:21], off
	v_fma_f32 v20, v20, v12, v70
	v_fma_f32 v21, v21, v12, v71
	s_waitcnt vmcnt(15)
	global_store_dwordx2 v[104:105], v[20:21], off
	v_fma_f32 v20, v20, v10, v72
	v_fma_f32 v21, v21, v10, v73
	s_waitcnt vmcnt(15)
	global_store_dwordx2 v[106:107], v[20:21], off
	v_fma_f32 v20, v20, v8, v74
	v_fma_f32 v21, v21, v8, v75
	s_waitcnt vmcnt(15)
	global_store_dwordx2 v[108:109], v[20:21], off
	v_fma_f32 v20, v20, v6, v76
	v_fma_f32 v21, v21, v6, v77
	s_waitcnt vmcnt(15)
	global_store_dwordx2 v[110:111], v[20:21], off
	v_fma_f32 v20, v20, v0, v78
	v_fma_f32 v21, v21, v0, v79
	s_cbranch_scc0 .LBB0_303
	v_readlane_b32 s10, v253, 63
	v_and_b32_e32 v4, 7, v13
	v_and_b32_e32 v0, 63, v15
	v_add_u32_e32 v2, s10, v17
	v_ashrrev_i32_e32 v3, 31, v2
	v_lshlrev_b64 v[2:3], 9, v[2:3]
	v_lshlrev_b32_e32 v4, 6, v4
	v_or3_b32 v2, v2, v4, v0
	v_readlane_b32 s2, v252, 26
	v_lshlrev_b64 v[2:3], 9, v[2:3]
	v_lshl_add_u64 v[2:3], s[6:7], 0, v[2:3]
	v_add_u32_e32 v7, s2, v7
	s_mov_b32 s2, 0x1ffff
	v_and_b32_e32 v0, 0x1f8, v11
	v_cmp_lt_i32_e32 vcc, s2, v7
	v_readlane_b32 s2, v253, 12
	v_lshl_add_u64 v[2:3], v[2:3], 0, v[0:1]
	s_or_b64 s[8:9], vcc, s[8:9]
	v_add_u32_e32 v9, s2, v9
	v_readlane_b32 s11, v254, 0
	global_store_dwordx2 v[2:3], v[20:21], off
	s_andn2_b64 exec, exec, s[8:9]
	s_cbranch_execnz .LBB0_302

.LBB0_334:
	s_lshl_b32 s2, s17, 7
	s_lshl_b64 s[10:11], s[2:3], 2
	s_waitcnt lgkmcnt(0)
	v_lshl_add_u64 v[18:19], v[14:15], 0, s[10:11]
	global_load_dwordx2 v[72:73], v[18:19], off offset:2048
	global_load_dwordx2 v[70:71], v[18:19], off offset:2560
	global_load_dwordx2 v[68:69], v[18:19], off offset:3072
	global_load_dwordx2 v[64:65], v[18:19], off offset:3584
	global_load_dwordx2 v[78:79], v[18:19], off offset:512
	global_load_dwordx2 v[76:77], v[18:19], off offset:1024
	global_load_dwordx2 v[74:75], v[18:19], off offset:1536
	global_load_dwordx2 v[88:89], v[18:19], off
	v_add_co_u32_e32 v20, vcc, 0x1000, v18
	s_movk_i32 s18, 0x2000
	s_nop 0
	v_addc_co_u32_e32 v21, vcc, 0, v19, vcc
	global_load_dwordx2 v[66:67], v[20:21], off
	global_load_dwordx2 v[62:63], v[20:21], off offset:512
	global_load_dwordx2 v[60:61], v[20:21], off offset:1024
	global_load_dwordx2 v[58:59], v[20:21], off offset:1536
	global_load_dwordx2 v[56:57], v[20:21], off offset:2048
	global_load_dwordx2 v[54:55], v[20:21], off offset:2560
	global_load_dwordx2 v[52:53], v[20:21], off offset:3072
	global_load_dwordx2 v[50:51], v[20:21], off offset:3584
	v_add_co_u32_e32 v20, vcc, s18, v18
	s_movk_i32 s18, 0x3000
	s_nop 0
	v_addc_co_u32_e32 v21, vcc, 0, v19, vcc
	v_add_co_u32_e32 v18, vcc, s18, v18
	v_or_b32_e32 v87, s17, v9
	s_nop 0
	v_addc_co_u32_e32 v19, vcc, 0, v19, vcc
	global_load_dwordx2 v[46:47], v[20:21], off offset:512
	global_load_dwordx2 v[44:45], v[20:21], off offset:1024
	global_load_dwordx2 v[42:43], v[20:21], off offset:1536
	global_load_dwordx2 v[40:41], v[20:21], off offset:2048
	global_load_dwordx2 v[48:49], v[18:19], off offset:-4096
	global_load_dwordx2 v[38:39], v[20:21], off offset:2560
	global_load_dwordx2 v[36:37], v[20:21], off offset:3072
	global_load_dwordx2 v[34:35], v[20:21], off offset:3584
	global_load_dwordx2 v[32:33], v[18:19], off
	global_load_dwordx2 v[30:31], v[18:19], off offset:512
	global_load_dwordx2 v[28:29], v[18:19], off offset:1024
	global_load_dwordx2 v[26:27], v[18:19], off offset:1536
	global_load_dwordx2 v[24:25], v[18:19], off offset:2048
	global_load_dwordx2 v[22:23], v[18:19], off offset:2560
	global_load_dwordx2 v[20:21], v[18:19], off offset:3072
	s_nop 0
	global_load_dwordx2 v[18:19], v[18:19], off offset:3584
	v_lshl_add_u32 v87, v87, 2, 0
	s_waitcnt vmcnt(0)
	ds_read_b32 v96, v87
	ds_read_b32 v97, v87 offset:4
	ds_read_b32 v98, v87 offset:8
	ds_read_b32 v99, v87 offset:12
	ds_read_b32 v100, v87 offset:16
	ds_read_b32 v101, v87 offset:20
	ds_read_b32 v102, v87 offset:24
	ds_read_b32 v103, v87 offset:28
	ds_read_b32 v104, v87 offset:32
	ds_read_b32 v105, v87 offset:36
	ds_read_b32 v106, v87 offset:40
	ds_read_b32 v107, v87 offset:44
	ds_read_b32 v108, v87 offset:48
	ds_read_b32 v109, v87 offset:52
	ds_read_b32 v110, v87 offset:56
	ds_read_b32 v111, v87 offset:60
	s_waitcnt lgkmcnt(0)
	ds_read_b32 v112, v87 offset:64
	ds_read_b32 v113, v87 offset:68
	ds_read_b32 v114, v87 offset:72
	ds_read_b32 v115, v87 offset:76
	ds_read_b32 v116, v87 offset:80
	ds_read_b32 v117, v87 offset:84
	ds_read_b32 v118, v87 offset:88
	ds_read_b32 v119, v87 offset:92
	ds_read_b32 v120, v87 offset:96
	ds_read_b32 v121, v87 offset:100
	ds_read_b32 v122, v87 offset:104
	ds_read_b32 v123, v87 offset:108
	ds_read_b32 v124, v87 offset:112
	ds_read_b32 v125, v87 offset:116
	ds_read_b32 v126, v87 offset:120
	ds_read_b32 v127, v87 offset:124
	s_waitcnt lgkmcnt(0)
	v_mul_f32_e32 v128, v81, v96
	s_lshl_b64 s[10:11], s[2:3], 2
	v_lshl_add_u64 v[92:93], v[16:17], 0, s[10:11]
	v_mul_f32_e32 v129, v3, v128
	v_mul_f32_e32 v128, v2, v128
	s_nop 0
	v_fma_f32 v128, v12, v88, v128
	v_fma_f32 v129, v13, v89, v129
	global_store_dwordx2 v[92:93], v[128:129], off
	v_mul_f32_e32 v96, v5, v129
	v_fmac_f32_e32 v96, v4, v128
	v_mul_f32_e32 v130, v81, v97
	s_or_b32 s10, s2, 0x80
	s_mov_b32 s11, s3
	v_lshl_add_u64 v[92:93], s[10:11], 2, v[16:17]
	v_mul_f32_e32 v131, v3, v130
	v_mul_f32_e32 v130, v2, v130
	s_nop 0
	v_fma_f32 v130, v12, v78, v130
	v_fma_f32 v131, v13, v79, v131
	global_store_dwordx2 v[92:93], v[130:131], off
	v_mul_f32_e32 v97, v5, v131
	v_fmac_f32_e32 v97, v4, v130
	v_mul_f32_e32 v132, v81, v98
	s_or_b32 s10, s2, 0x100
	s_mov_b32 s11, s3
	v_lshl_add_u64 v[92:93], s[10:11], 2, v[16:17]
	v_mul_f32_e32 v133, v3, v132
	v_mul_f32_e32 v132, v2, v132
	s_nop 0
	v_fma_f32 v132, v12, v76, v132
	v_fma_f32 v133, v13, v77, v133
	global_store_dwordx2 v[92:93], v[132:133], off
	v_mul_f32_e32 v98, v5, v133
	v_fmac_f32_e32 v98, v4, v132
	v_mul_f32_e32 v134, v81, v99
	s_or_b32 s10, s2, 0x180
	s_mov_b32 s11, s3
	v_lshl_add_u64 v[92:93], s[10:11], 2, v[16:17]
	v_mul_f32_e32 v135, v3, v134
	v_mul_f32_e32 v134, v2, v134
	s_nop 0
	v_fma_f32 v134, v12, v74, v134
	v_fma_f32 v135, v13, v75, v135
	global_store_dwordx2 v[92:93], v[134:135], off
	v_mul_f32_e32 v99, v5, v135
	v_fmac_f32_e32 v99, v4, v134
	v_mul_f32_e32 v136, v81, v100
	s_or_b32 s10, s2, 0x200
	s_mov_b32 s11, s3
	v_lshl_add_u64 v[92:93], s[10:11], 2, v[16:17]
	v_mul_f32_e32 v137, v3, v136
	v_mul_f32_e32 v136, v2, v136
	s_nop 0
	v_fma_f32 v136, v12, v72, v136
	v_fma_f32 v137, v13, v73, v137
	global_store_dwordx2 v[92:93], v[136:137], off
	v_mul_f32_e32 v100, v5, v137
	v_fmac_f32_e32 v100, v4, v136
	v_mul_f32_e32 v138, v81, v101
	s_or_b32 s10, s2, 0x280
	s_mov_b32 s11, s3
	v_lshl_add_u64 v[92:93], s[10:11], 2, v[16:17]
	v_mul_f32_e32 v139, v3, v138
	v_mul_f32_e32 v138, v2, v138
	s_nop 0
	v_fma_f32 v138, v12, v70, v138
	v_fma_f32 v139, v13, v71, v139
	global_store_dwordx2 v[92:93], v[138:139], off
	v_mul_f32_e32 v101, v5, v139
	v_fmac_f32_e32 v101, v4, v138
	v_mul_f32_e32 v140, v81, v102
	s_or_b32 s10, s2, 0x300
	s_mov_b32 s11, s3
	v_lshl_add_u64 v[92:93], s[10:11], 2, v[16:17]
	v_mul_f32_e32 v141, v3, v140
	v_mul_f32_e32 v140, v2, v140
	s_nop 0
	v_fma_f32 v140, v12, v68, v140
	v_fma_f32 v141, v13, v69, v141
	global_store_dwordx2 v[92:93], v[140:141], off
	v_mul_f32_e32 v102, v5, v141
	v_fmac_f32_e32 v102, v4, v140
	v_mul_f32_e32 v142, v81, v103
	s_or_b32 s10, s2, 0x380
	s_mov_b32 s11, s3
	v_lshl_add_u64 v[92:93], s[10:11], 2, v[16:17]
	v_mul_f32_e32 v143, v3, v142
	v_mul_f32_e32 v142, v2, v142
	s_nop 0
	v_fma_f32 v142, v12, v64, v142
	v_fma_f32 v143, v13, v65, v143
	global_store_dwordx2 v[92:93], v[142:143], off
	v_mul_f32_e32 v103, v5, v143
	v_fmac_f32_e32 v103, v4, v142
	v_mul_f32_e32 v144, v81, v104
	s_or_b32 s10, s2, 0x400
	s_mov_b32 s11, s3
	v_lshl_add_u64 v[92:93], s[10:11], 2, v[16:17]
	v_mul_f32_e32 v145, v3, v144
	v_mul_f32_e32 v144, v2, v144
	s_nop 0
	v_fma_f32 v144, v12, v66, v144
	v_fma_f32 v145, v13, v67, v145
	global_store_dwordx2 v[92:93], v[144:145], off
	v_mul_f32_e32 v104, v5, v145
	v_fmac_f32_e32 v104, v4, v144
	v_mul_f32_e32 v146, v81, v105
	s_or_b32 s10, s2, 0x480
	s_mov_b32 s11, s3
	v_lshl_add_u64 v[92:93], s[10:11], 2, v[16:17]
	v_mul_f32_e32 v147, v3, v146
	v_mul_f32_e32 v146, v2, v146
	s_nop 0
	v_fma_f32 v146, v12, v62, v146
	v_fma_f32 v147, v13, v63, v147
	global_store_dwordx2 v[92:93], v[146:147], off
	v_mul_f32_e32 v105, v5, v147
	v_fmac_f32_e32 v105, v4, v146
	v_mul_f32_e32 v148, v81, v106
	s_or_b32 s10, s2, 0x500
	s_mov_b32 s11, s3
	v_lshl_add_u64 v[92:93], s[10:11], 2, v[16:17]
	v_mul_f32_e32 v149, v3, v148
	v_mul_f32_e32 v148, v2, v148
	s_nop 0
	v_fma_f32 v148, v12, v60, v148
	v_fma_f32 v149, v13, v61, v149
	global_store_dwordx2 v[92:93], v[148:149], off
	v_mul_f32_e32 v106, v5, v149
	v_fmac_f32_e32 v106, v4, v148
	v_mul_f32_e32 v150, v81, v107
	s_or_b32 s10, s2, 0x580
	s_mov_b32 s11, s3
	v_lshl_add_u64 v[92:93], s[10:11], 2, v[16:17]
	v_mul_f32_e32 v151, v3, v150
	v_mul_f32_e32 v150, v2, v150
	s_nop 0
	v_fma_f32 v150, v12, v58, v150
	v_fma_f32 v151, v13, v59, v151
	global_store_dwordx2 v[92:93], v[150:151], off
	v_mul_f32_e32 v107, v5, v151
	v_fmac_f32_e32 v107, v4, v150
	v_mul_f32_e32 v152, v81, v108
	s_or_b32 s10, s2, 0x600
	s_mov_b32 s11, s3
	v_lshl_add_u64 v[92:93], s[10:11], 2, v[16:17]
	v_mul_f32_e32 v153, v3, v152
	v_mul_f32_e32 v152, v2, v152
	s_nop 0
	v_fma_f32 v152, v12, v56, v152
	v_fma_f32 v153, v13, v57, v153
	global_store_dwordx2 v[92:93], v[152:153], off
	v_mul_f32_e32 v108, v5, v153
	v_fmac_f32_e32 v108, v4, v152
	v_mul_f32_e32 v154, v81, v109
	s_or_b32 s10, s2, 0x680
	s_mov_b32 s11, s3
	v_lshl_add_u64 v[92:93], s[10:11], 2, v[16:17]
	v_mul_f32_e32 v155, v3, v154
	v_mul_f32_e32 v154, v2, v154
	s_nop 0
	v_fma_f32 v154, v12, v54, v154
	v_fma_f32 v155, v13, v55, v155
	global_store_dwordx2 v[92:93], v[154:155], off
	v_mul_f32_e32 v109, v5, v155
	v_fmac_f32_e32 v109, v4, v154
	v_mul_f32_e32 v156, v81, v110
	s_or_b32 s10, s2, 0x700
	s_mov_b32 s11, s3
	v_lshl_add_u64 v[92:93], s[10:11], 2, v[16:17]
	v_mul_f32_e32 v157, v3, v156
	v_mul_f32_e32 v156, v2, v156
	s_nop 0
	v_fma_f32 v156, v12, v52, v156
	v_fma_f32 v157, v13, v53, v157
	global_store_dwordx2 v[92:93], v[156:157], off
	v_mul_f32_e32 v110, v5, v157
	v_fmac_f32_e32 v110, v4, v156
	v_mul_f32_e32 v158, v81, v111
	s_or_b32 s10, s2, 0x780
	s_mov_b32 s11, s3
	v_lshl_add_u64 v[92:93], s[10:11], 2, v[16:17]
	v_mul_f32_e32 v159, v3, v158
	v_mul_f32_e32 v158, v2, v158
	s_nop 0
	v_fma_f32 v158, v12, v50, v158
	v_fma_f32 v159, v13, v51, v159
	global_store_dwordx2 v[92:93], v[158:159], off
	v_mul_f32_e32 v111, v5, v159
	v_fmac_f32_e32 v111, v4, v158
	v_mul_f32_e32 v160, v81, v112
	s_or_b32 s10, s2, 0x800
	s_mov_b32 s11, s3
	v_lshl_add_u64 v[92:93], s[10:11], 2, v[16:17]
	v_mul_f32_e32 v161, v3, v160
	v_mul_f32_e32 v160, v2, v160
	s_nop 0
	v_fma_f32 v160, v12, v48, v160
	v_fma_f32 v161, v13, v49, v161
	global_store_dwordx2 v[92:93], v[160:161], off
	v_mul_f32_e32 v112, v5, v161
	v_fmac_f32_e32 v112, v4, v160
	v_mul_f32_e32 v162, v81, v113
	s_or_b32 s10, s2, 0x880
	s_mov_b32 s11, s3
	v_lshl_add_u64 v[92:93], s[10:11], 2, v[16:17]
	v_mul_f32_e32 v163, v3, v162
	v_mul_f32_e32 v162, v2, v162
	s_nop 0
	v_fma_f32 v162, v12, v46, v162
	v_fma_f32 v163, v13, v47, v163
	global_store_dwordx2 v[92:93], v[162:163], off
	v_mul_f32_e32 v113, v5, v163
	v_fmac_f32_e32 v113, v4, v162
	v_mul_f32_e32 v164, v81, v114
	s_or_b32 s10, s2, 0x900
	s_mov_b32 s11, s3
	v_lshl_add_u64 v[92:93], s[10:11], 2, v[16:17]
	v_mul_f32_e32 v165, v3, v164
	v_mul_f32_e32 v164, v2, v164
	s_nop 0
	v_fma_f32 v164, v12, v44, v164
	v_fma_f32 v165, v13, v45, v165
	global_store_dwordx2 v[92:93], v[164:165], off
	v_mul_f32_e32 v114, v5, v165
	v_fmac_f32_e32 v114, v4, v164
	v_mul_f32_e32 v166, v81, v115
	s_or_b32 s10, s2, 0x980
	s_mov_b32 s11, s3
	v_lshl_add_u64 v[92:93], s[10:11], 2, v[16:17]
	v_mul_f32_e32 v167, v3, v166
	v_mul_f32_e32 v166, v2, v166
	s_nop 0
	v_fma_f32 v166, v12, v42, v166
	v_fma_f32 v167, v13, v43, v167
	global_store_dwordx2 v[92:93], v[166:167], off
	v_mul_f32_e32 v115, v5, v167
	v_fmac_f32_e32 v115, v4, v166
	v_mul_f32_e32 v168, v81, v116
	s_or_b32 s10, s2, 0xa00
	s_mov_b32 s11, s3
	v_lshl_add_u64 v[92:93], s[10:11], 2, v[16:17]
	v_mul_f32_e32 v169, v3, v168
	v_mul_f32_e32 v168, v2, v168
	s_nop 0
	v_fma_f32 v168, v12, v40, v168
	v_fma_f32 v169, v13, v41, v169
	global_store_dwordx2 v[92:93], v[168:169], off
	v_mul_f32_e32 v116, v5, v169
	v_fmac_f32_e32 v116, v4, v168
	v_mul_f32_e32 v170, v81, v117
	s_or_b32 s10, s2, 0xa80
	s_mov_b32 s11, s3
	v_lshl_add_u64 v[92:93], s[10:11], 2, v[16:17]
	v_mul_f32_e32 v171, v3, v170
	v_mul_f32_e32 v170, v2, v170
	s_nop 0
	v_fma_f32 v170, v12, v38, v170
	v_fma_f32 v171, v13, v39, v171
	global_store_dwordx2 v[92:93], v[170:171], off
	v_mul_f32_e32 v117, v5, v171
	v_fmac_f32_e32 v117, v4, v170
	v_mul_f32_e32 v172, v81, v118
	s_or_b32 s10, s2, 0xb00
	s_mov_b32 s11, s3
	v_lshl_add_u64 v[92:93], s[10:11], 2, v[16:17]
	v_mul_f32_e32 v173, v3, v172
	v_mul_f32_e32 v172, v2, v172
	s_nop 0
	v_fma_f32 v172, v12, v36, v172
	v_fma_f32 v173, v13, v37, v173
	global_store_dwordx2 v[92:93], v[172:173], off
	v_mul_f32_e32 v118, v5, v173
	v_fmac_f32_e32 v118, v4, v172
	v_mul_f32_e32 v174, v81, v119
	s_or_b32 s10, s2, 0xb80
	s_mov_b32 s11, s3
	v_lshl_add_u64 v[92:93], s[10:11], 2, v[16:17]
	v_mul_f32_e32 v175, v3, v174
	v_mul_f32_e32 v174, v2, v174
	s_nop 0
	v_fma_f32 v174, v12, v34, v174
	v_fma_f32 v175, v13, v35, v175
	global_store_dwordx2 v[92:93], v[174:175], off
	v_mul_f32_e32 v119, v5, v175
	v_fmac_f32_e32 v119, v4, v174
	v_mul_f32_e32 v176, v81, v120
	s_or_b32 s10, s2, 0xc00
	s_mov_b32 s11, s3
	v_lshl_add_u64 v[92:93], s[10:11], 2, v[16:17]
	v_mul_f32_e32 v177, v3, v176
	v_mul_f32_e32 v176, v2, v176
	s_nop 0
	v_fma_f32 v176, v12, v32, v176
	v_fma_f32 v177, v13, v33, v177
	global_store_dwordx2 v[92:93], v[176:177], off
	v_mul_f32_e32 v120, v5, v177
	v_fmac_f32_e32 v120, v4, v176
	v_mul_f32_e32 v178, v81, v121
	s_or_b32 s10, s2, 0xc80
	s_mov_b32 s11, s3
	v_lshl_add_u64 v[92:93], s[10:11], 2, v[16:17]
	v_mul_f32_e32 v179, v3, v178
	v_mul_f32_e32 v178, v2, v178
	s_nop 0
	v_fma_f32 v178, v12, v30, v178
	v_fma_f32 v179, v13, v31, v179
	global_store_dwordx2 v[92:93], v[178:179], off
	v_mul_f32_e32 v121, v5, v179
	v_fmac_f32_e32 v121, v4, v178
	v_mul_f32_e32 v180, v81, v122
	s_or_b32 s10, s2, 0xd00
	s_mov_b32 s11, s3
	v_lshl_add_u64 v[92:93], s[10:11], 2, v[16:17]
	v_mul_f32_e32 v181, v3, v180
	v_mul_f32_e32 v180, v2, v180
	s_nop 0
	v_fma_f32 v180, v12, v28, v180
	v_fma_f32 v181, v13, v29, v181
	global_store_dwordx2 v[92:93], v[180:181], off
	v_mul_f32_e32 v122, v5, v181
	v_fmac_f32_e32 v122, v4, v180
	v_mul_f32_e32 v182, v81, v123
	s_or_b32 s10, s2, 0xd80
	s_mov_b32 s11, s3
	v_lshl_add_u64 v[92:93], s[10:11], 2, v[16:17]
	v_mul_f32_e32 v183, v3, v182
	v_mul_f32_e32 v182, v2, v182
	s_nop 0
	v_fma_f32 v182, v12, v26, v182
	v_fma_f32 v183, v13, v27, v183
	global_store_dwordx2 v[92:93], v[182:183], off
	v_mul_f32_e32 v123, v5, v183
	v_fmac_f32_e32 v123, v4, v182
	v_mul_f32_e32 v184, v81, v124
	s_or_b32 s10, s2, 0xe00
	s_mov_b32 s11, s3
	v_lshl_add_u64 v[92:93], s[10:11], 2, v[16:17]
	v_mul_f32_e32 v185, v3, v184
	v_mul_f32_e32 v184, v2, v184
	s_nop 0
	v_fma_f32 v184, v12, v24, v184
	v_fma_f32 v185, v13, v25, v185
	global_store_dwordx2 v[92:93], v[184:185], off
	v_mul_f32_e32 v124, v5, v185
	v_fmac_f32_e32 v124, v4, v184
	v_mul_f32_e32 v186, v81, v125
	s_or_b32 s10, s2, 0xe80
	s_mov_b32 s11, s3
	v_lshl_add_u64 v[92:93], s[10:11], 2, v[16:17]
	v_mul_f32_e32 v187, v3, v186
	v_mul_f32_e32 v186, v2, v186
	s_nop 0
	v_fma_f32 v186, v12, v22, v186
	v_fma_f32 v187, v13, v23, v187
	global_store_dwordx2 v[92:93], v[186:187], off
	v_mul_f32_e32 v125, v5, v187
	v_fmac_f32_e32 v125, v4, v186
	v_mul_f32_e32 v188, v81, v126
	s_or_b32 s10, s2, 0xf00
	s_mov_b32 s11, s3
	v_lshl_add_u64 v[92:93], s[10:11], 2, v[16:17]
	v_mul_f32_e32 v189, v3, v188
	v_mul_f32_e32 v188, v2, v188
	s_nop 0
	v_fma_f32 v188, v12, v20, v188
	v_fma_f32 v189, v13, v21, v189
	global_store_dwordx2 v[92:93], v[188:189], off
	v_mul_f32_e32 v126, v5, v189
	v_fmac_f32_e32 v126, v4, v188
	v_mul_f32_e32 v190, v81, v127
	s_or_b32 s10, s2, 0xf80
	s_mov_b32 s11, s3
	v_lshl_add_u64 v[92:93], s[10:11], 2, v[16:17]
	v_mul_f32_e32 v191, v3, v190
	v_mul_f32_e32 v190, v2, v190
	s_nop 0
	v_fma_f32 v190, v12, v18, v190
	v_fma_f32 v191, v13, v19, v191
	global_store_dwordx2 v[92:93], v[190:191], off
	v_mul_f32_e32 v127, v5, v191
	v_fmac_f32_e32 v127, v4, v190
	ds_bpermute_b32 v128, v0, v96
	ds_bpermute_b32 v129, v0, v97
	ds_bpermute_b32 v130, v0, v98
	ds_bpermute_b32 v131, v0, v99
	ds_bpermute_b32 v132, v0, v100
	ds_bpermute_b32 v133, v0, v101
	ds_bpermute_b32 v134, v0, v102
	ds_bpermute_b32 v135, v0, v103
	ds_bpermute_b32 v136, v0, v104
	ds_bpermute_b32 v137, v0, v105
	ds_bpermute_b32 v138, v0, v106
	ds_bpermute_b32 v139, v0, v107
	ds_bpermute_b32 v140, v0, v108
	ds_bpermute_b32 v141, v0, v109
	ds_bpermute_b32 v142, v0, v110
	ds_bpermute_b32 v143, v0, v111
	s_waitcnt lgkmcnt(0)
	v_add_f32_e32 v96, v96, v128
	v_add_f32_e32 v97, v97, v129
	v_add_f32_e32 v98, v98, v130
	v_add_f32_e32 v99, v99, v131
	v_add_f32_e32 v100, v100, v132
	v_add_f32_e32 v101, v101, v133
	v_add_f32_e32 v102, v102, v134
	v_add_f32_e32 v103, v103, v135
	v_add_f32_e32 v104, v104, v136
	v_add_f32_e32 v105, v105, v137
	v_add_f32_e32 v106, v106, v138
	v_add_f32_e32 v107, v107, v139
	v_add_f32_e32 v108, v108, v140
	v_add_f32_e32 v109, v109, v141
	v_add_f32_e32 v110, v110, v142
	v_add_f32_e32 v111, v111, v143
	ds_bpermute_b32 v128, v0, v112
	ds_bpermute_b32 v129, v0, v113
	ds_bpermute_b32 v130, v0, v114
	ds_bpermute_b32 v131, v0, v115
	ds_bpermute_b32 v132, v0, v116
	ds_bpermute_b32 v133, v0, v117
	ds_bpermute_b32 v134, v0, v118
	ds_bpermute_b32 v135, v0, v119
	ds_bpermute_b32 v136, v0, v120
	ds_bpermute_b32 v137, v0, v121
	ds_bpermute_b32 v138, v0, v122
	ds_bpermute_b32 v139, v0, v123
	ds_bpermute_b32 v140, v0, v124
	ds_bpermute_b32 v141, v0, v125
	ds_bpermute_b32 v142, v0, v126
	ds_bpermute_b32 v143, v0, v127
	s_waitcnt lgkmcnt(0)
	v_add_f32_e32 v112, v112, v128
	v_add_f32_e32 v113, v113, v129
	v_add_f32_e32 v114, v114, v130
	v_add_f32_e32 v115, v115, v131
	v_add_f32_e32 v116, v116, v132
	v_add_f32_e32 v117, v117, v133
	v_add_f32_e32 v118, v118, v134
	v_add_f32_e32 v119, v119, v135
	v_add_f32_e32 v120, v120, v136
	v_add_f32_e32 v121, v121, v137
	v_add_f32_e32 v122, v122, v138
	v_add_f32_e32 v123, v123, v139
	v_add_f32_e32 v124, v124, v140
	v_add_f32_e32 v125, v125, v141
	v_add_f32_e32 v126, v126, v142
	v_add_f32_e32 v127, v127, v143
	ds_bpermute_b32 v128, v82, v96
	ds_bpermute_b32 v129, v82, v97
	ds_bpermute_b32 v130, v82, v98
	ds_bpermute_b32 v131, v82, v99
	ds_bpermute_b32 v132, v82, v100
	ds_bpermute_b32 v133, v82, v101
	ds_bpermute_b32 v134, v82, v102
	ds_bpermute_b32 v135, v82, v103
	ds_bpermute_b32 v136, v82, v104
	ds_bpermute_b32 v137, v82, v105
	ds_bpermute_b32 v138, v82, v106
	ds_bpermute_b32 v139, v82, v107
	ds_bpermute_b32 v140, v82, v108
	ds_bpermute_b32 v141, v82, v109
	ds_bpermute_b32 v142, v82, v110
	ds_bpermute_b32 v143, v82, v111
	s_waitcnt lgkmcnt(0)
	v_add_f32_e32 v96, v96, v128
	v_add_f32_e32 v97, v97, v129
	v_add_f32_e32 v98, v98, v130
	v_add_f32_e32 v99, v99, v131
	v_add_f32_e32 v100, v100, v132
	v_add_f32_e32 v101, v101, v133
	v_add_f32_e32 v102, v102, v134
	v_add_f32_e32 v103, v103, v135
	v_add_f32_e32 v104, v104, v136
	v_add_f32_e32 v105, v105, v137
	v_add_f32_e32 v106, v106, v138
	v_add_f32_e32 v107, v107, v139
	v_add_f32_e32 v108, v108, v140
	v_add_f32_e32 v109, v109, v141
	v_add_f32_e32 v110, v110, v142
	v_add_f32_e32 v111, v111, v143
	ds_bpermute_b32 v128, v82, v112
	ds_bpermute_b32 v129, v82, v113
	ds_bpermute_b32 v130, v82, v114
	ds_bpermute_b32 v131, v82, v115
	ds_bpermute_b32 v132, v82, v116
	ds_bpermute_b32 v133, v82, v117
	ds_bpermute_b32 v134, v82, v118
	ds_bpermute_b32 v135, v82, v119
	ds_bpermute_b32 v136, v82, v120
	ds_bpermute_b32 v137, v82, v121
	ds_bpermute_b32 v138, v82, v122
	ds_bpermute_b32 v139, v82, v123
	ds_bpermute_b32 v140, v82, v124
	ds_bpermute_b32 v141, v82, v125
	ds_bpermute_b32 v142, v82, v126
	ds_bpermute_b32 v143, v82, v127
	s_waitcnt lgkmcnt(0)
	v_add_f32_e32 v112, v112, v128
	v_add_f32_e32 v113, v113, v129
	v_add_f32_e32 v114, v114, v130
	v_add_f32_e32 v115, v115, v131
	v_add_f32_e32 v116, v116, v132
	v_add_f32_e32 v117, v117, v133
	v_add_f32_e32 v118, v118, v134
	v_add_f32_e32 v119, v119, v135
	v_add_f32_e32 v120, v120, v136
	v_add_f32_e32 v121, v121, v137
	v_add_f32_e32 v122, v122, v138
	v_add_f32_e32 v123, v123, v139
	v_add_f32_e32 v124, v124, v140
	v_add_f32_e32 v125, v125, v141
	v_add_f32_e32 v126, v126, v142
	v_add_f32_e32 v127, v127, v143
	ds_bpermute_b32 v128, v83, v96
	ds_bpermute_b32 v129, v83, v97
	ds_bpermute_b32 v130, v83, v98
	ds_bpermute_b32 v131, v83, v99
	ds_bpermute_b32 v132, v83, v100
	ds_bpermute_b32 v133, v83, v101
	ds_bpermute_b32 v134, v83, v102
	ds_bpermute_b32 v135, v83, v103
	ds_bpermute_b32 v136, v83, v104
	ds_bpermute_b32 v137, v83, v105
	ds_bpermute_b32 v138, v83, v106
	ds_bpermute_b32 v139, v83, v107
	ds_bpermute_b32 v140, v83, v108
	ds_bpermute_b32 v141, v83, v109
	ds_bpermute_b32 v142, v83, v110
	ds_bpermute_b32 v143, v83, v111
	s_waitcnt lgkmcnt(0)
	v_add_f32_e32 v96, v96, v128
	v_add_f32_e32 v97, v97, v129
	v_add_f32_e32 v98, v98, v130
	v_add_f32_e32 v99, v99, v131
	v_add_f32_e32 v100, v100, v132
	v_add_f32_e32 v101, v101, v133
	v_add_f32_e32 v102, v102, v134
	v_add_f32_e32 v103, v103, v135
	v_add_f32_e32 v104, v104, v136
	v_add_f32_e32 v105, v105, v137
	v_add_f32_e32 v106, v106, v138
	v_add_f32_e32 v107, v107, v139
	v_add_f32_e32 v108, v108, v140
	v_add_f32_e32 v109, v109, v141
	v_add_f32_e32 v110, v110, v142
	v_add_f32_e32 v111, v111, v143
	ds_bpermute_b32 v128, v83, v112
	ds_bpermute_b32 v129, v83, v113
	ds_bpermute_b32 v130, v83, v114
	ds_bpermute_b32 v131, v83, v115
	ds_bpermute_b32 v132, v83, v116
	ds_bpermute_b32 v133, v83, v117
	ds_bpermute_b32 v134, v83, v118
	ds_bpermute_b32 v135, v83, v119
	ds_bpermute_b32 v136, v83, v120
	ds_bpermute_b32 v137, v83, v121
	ds_bpermute_b32 v138, v83, v122
	ds_bpermute_b32 v139, v83, v123
	ds_bpermute_b32 v140, v83, v124
	ds_bpermute_b32 v141, v83, v125
	ds_bpermute_b32 v142, v83, v126
	ds_bpermute_b32 v143, v83, v127
	s_waitcnt lgkmcnt(0)
	v_add_f32_e32 v112, v112, v128
	v_add_f32_e32 v113, v113, v129
	v_add_f32_e32 v114, v114, v130
	v_add_f32_e32 v115, v115, v131
	v_add_f32_e32 v116, v116, v132
	v_add_f32_e32 v117, v117, v133
	v_add_f32_e32 v118, v118, v134
	v_add_f32_e32 v119, v119, v135
	v_add_f32_e32 v120, v120, v136
	v_add_f32_e32 v121, v121, v137
	v_add_f32_e32 v122, v122, v138
	v_add_f32_e32 v123, v123, v139
	v_add_f32_e32 v124, v124, v140
	v_add_f32_e32 v125, v125, v141
	v_add_f32_e32 v126, v126, v142
	v_add_f32_e32 v127, v127, v143
	ds_bpermute_b32 v128, v84, v96
	ds_bpermute_b32 v129, v84, v97
	ds_bpermute_b32 v130, v84, v98
	ds_bpermute_b32 v131, v84, v99
	ds_bpermute_b32 v132, v84, v100
	ds_bpermute_b32 v133, v84, v101
	ds_bpermute_b32 v134, v84, v102
	ds_bpermute_b32 v135, v84, v103
	ds_bpermute_b32 v136, v84, v104
	ds_bpermute_b32 v137, v84, v105
	ds_bpermute_b32 v138, v84, v106
	ds_bpermute_b32 v139, v84, v107
	ds_bpermute_b32 v140, v84, v108
	ds_bpermute_b32 v141, v84, v109
	ds_bpermute_b32 v142, v84, v110
	ds_bpermute_b32 v143, v84, v111
	s_waitcnt lgkmcnt(0)
	v_add_f32_e32 v96, v96, v128
	v_add_f32_e32 v97, v97, v129
	v_add_f32_e32 v98, v98, v130
	v_add_f32_e32 v99, v99, v131
	v_add_f32_e32 v100, v100, v132
	v_add_f32_e32 v101, v101, v133
	v_add_f32_e32 v102, v102, v134
	v_add_f32_e32 v103, v103, v135
	v_add_f32_e32 v104, v104, v136
	v_add_f32_e32 v105, v105, v137
	v_add_f32_e32 v106, v106, v138
	v_add_f32_e32 v107, v107, v139
	v_add_f32_e32 v108, v108, v140
	v_add_f32_e32 v109, v109, v141
	v_add_f32_e32 v110, v110, v142
	v_add_f32_e32 v111, v111, v143
	ds_bpermute_b32 v128, v84, v112
	ds_bpermute_b32 v129, v84, v113
	ds_bpermute_b32 v130, v84, v114
	ds_bpermute_b32 v131, v84, v115
	ds_bpermute_b32 v132, v84, v116
	ds_bpermute_b32 v133, v84, v117
	ds_bpermute_b32 v134, v84, v118
	ds_bpermute_b32 v135, v84, v119
	ds_bpermute_b32 v136, v84, v120
	ds_bpermute_b32 v137, v84, v121
	ds_bpermute_b32 v138, v84, v122
	ds_bpermute_b32 v139, v84, v123
	ds_bpermute_b32 v140, v84, v124
	ds_bpermute_b32 v141, v84, v125
	ds_bpermute_b32 v142, v84, v126
	ds_bpermute_b32 v143, v84, v127
	s_waitcnt lgkmcnt(0)
	v_add_f32_e32 v112, v112, v128
	v_add_f32_e32 v113, v113, v129
	v_add_f32_e32 v114, v114, v130
	v_add_f32_e32 v115, v115, v131
	v_add_f32_e32 v116, v116, v132
	v_add_f32_e32 v117, v117, v133
	v_add_f32_e32 v118, v118, v134
	v_add_f32_e32 v119, v119, v135
	v_add_f32_e32 v120, v120, v136
	v_add_f32_e32 v121, v121, v137
	v_add_f32_e32 v122, v122, v138
	v_add_f32_e32 v123, v123, v139
	v_add_f32_e32 v124, v124, v140
	v_add_f32_e32 v125, v125, v141
	v_add_f32_e32 v126, v126, v142
	v_add_f32_e32 v127, v127, v143
	ds_bpermute_b32 v128, v85, v96
	ds_bpermute_b32 v129, v85, v97
	ds_bpermute_b32 v130, v85, v98
	ds_bpermute_b32 v131, v85, v99
	ds_bpermute_b32 v132, v85, v100
	ds_bpermute_b32 v133, v85, v101
	ds_bpermute_b32 v134, v85, v102
	ds_bpermute_b32 v135, v85, v103
	ds_bpermute_b32 v136, v85, v104
	ds_bpermute_b32 v137, v85, v105
	ds_bpermute_b32 v138, v85, v106
	ds_bpermute_b32 v139, v85, v107
	ds_bpermute_b32 v140, v85, v108
	ds_bpermute_b32 v141, v85, v109
	ds_bpermute_b32 v142, v85, v110
	ds_bpermute_b32 v143, v85, v111
	s_waitcnt lgkmcnt(0)
	v_add_f32_e32 v96, v96, v128
	v_add_f32_e32 v97, v97, v129
	v_add_f32_e32 v98, v98, v130
	v_add_f32_e32 v99, v99, v131
	v_add_f32_e32 v100, v100, v132
	v_add_f32_e32 v101, v101, v133
	v_add_f32_e32 v102, v102, v134
	v_add_f32_e32 v103, v103, v135
	v_add_f32_e32 v104, v104, v136
	v_add_f32_e32 v105, v105, v137
	v_add_f32_e32 v106, v106, v138
	v_add_f32_e32 v107, v107, v139
	v_add_f32_e32 v108, v108, v140
	v_add_f32_e32 v109, v109, v141
	v_add_f32_e32 v110, v110, v142
	v_add_f32_e32 v111, v111, v143
	ds_bpermute_b32 v128, v85, v112
	ds_bpermute_b32 v129, v85, v113
	ds_bpermute_b32 v130, v85, v114
	ds_bpermute_b32 v131, v85, v115
	ds_bpermute_b32 v132, v85, v116
	ds_bpermute_b32 v133, v85, v117
	ds_bpermute_b32 v134, v85, v118
	ds_bpermute_b32 v135, v85, v119
	ds_bpermute_b32 v136, v85, v120
	ds_bpermute_b32 v137, v85, v121
	ds_bpermute_b32 v138, v85, v122
	ds_bpermute_b32 v139, v85, v123
	ds_bpermute_b32 v140, v85, v124
	ds_bpermute_b32 v141, v85, v125
	ds_bpermute_b32 v142, v85, v126
	ds_bpermute_b32 v143, v85, v127
	s_waitcnt lgkmcnt(0)
	v_add_f32_e32 v112, v112, v128
	v_add_f32_e32 v113, v113, v129
	v_add_f32_e32 v114, v114, v130
	v_add_f32_e32 v115, v115, v131
	v_add_f32_e32 v116, v116, v132
	v_add_f32_e32 v117, v117, v133
	v_add_f32_e32 v118, v118, v134
	v_add_f32_e32 v119, v119, v135
	v_add_f32_e32 v120, v120, v136
	v_add_f32_e32 v121, v121, v137
	v_add_f32_e32 v122, v122, v138
	v_add_f32_e32 v123, v123, v139
	v_add_f32_e32 v124, v124, v140
	v_add_f32_e32 v125, v125, v141
	v_add_f32_e32 v126, v126, v142
	v_add_f32_e32 v127, v127, v143
	ds_bpermute_b32 v128, v86, v96
	ds_bpermute_b32 v129, v86, v97
	ds_bpermute_b32 v130, v86, v98
	ds_bpermute_b32 v131, v86, v99
	ds_bpermute_b32 v132, v86, v100
	ds_bpermute_b32 v133, v86, v101
	ds_bpermute_b32 v134, v86, v102
	ds_bpermute_b32 v135, v86, v103
	ds_bpermute_b32 v136, v86, v104
	ds_bpermute_b32 v137, v86, v105
	ds_bpermute_b32 v138, v86, v106
	ds_bpermute_b32 v139, v86, v107
	ds_bpermute_b32 v140, v86, v108
	ds_bpermute_b32 v141, v86, v109
	ds_bpermute_b32 v142, v86, v110
	ds_bpermute_b32 v143, v86, v111
	s_waitcnt lgkmcnt(0)
	v_add_f32_e32 v96, v96, v128
	v_add_f32_e32 v97, v97, v129
	v_add_f32_e32 v98, v98, v130
	v_add_f32_e32 v99, v99, v131
	v_add_f32_e32 v100, v100, v132
	v_add_f32_e32 v101, v101, v133
	v_add_f32_e32 v102, v102, v134
	v_add_f32_e32 v103, v103, v135
	v_add_f32_e32 v104, v104, v136
	v_add_f32_e32 v105, v105, v137
	v_add_f32_e32 v106, v106, v138
	v_add_f32_e32 v107, v107, v139
	v_add_f32_e32 v108, v108, v140
	v_add_f32_e32 v109, v109, v141
	v_add_f32_e32 v110, v110, v142
	v_add_f32_e32 v111, v111, v143
	ds_bpermute_b32 v128, v86, v112
	ds_bpermute_b32 v129, v86, v113
	ds_bpermute_b32 v130, v86, v114
	ds_bpermute_b32 v131, v86, v115
	ds_bpermute_b32 v132, v86, v116
	ds_bpermute_b32 v133, v86, v117
	ds_bpermute_b32 v134, v86, v118
	ds_bpermute_b32 v135, v86, v119
	ds_bpermute_b32 v136, v86, v120
	ds_bpermute_b32 v137, v86, v121
	ds_bpermute_b32 v138, v86, v122
	ds_bpermute_b32 v139, v86, v123
	ds_bpermute_b32 v140, v86, v124
	ds_bpermute_b32 v141, v86, v125
	ds_bpermute_b32 v142, v86, v126
	ds_bpermute_b32 v143, v86, v127
	s_waitcnt lgkmcnt(0)
	v_add_f32_e32 v112, v112, v128
	v_add_f32_e32 v113, v113, v129
	v_add_f32_e32 v114, v114, v130
	v_add_f32_e32 v115, v115, v131
	v_add_f32_e32 v116, v116, v132
	v_add_f32_e32 v117, v117, v133
	v_add_f32_e32 v118, v118, v134
	v_add_f32_e32 v119, v119, v135
	v_add_f32_e32 v120, v120, v136
	v_add_f32_e32 v121, v121, v137
	v_add_f32_e32 v122, v122, v138
	v_add_f32_e32 v123, v123, v139
	v_add_f32_e32 v124, v124, v140
	v_add_f32_e32 v125, v125, v141
	v_add_f32_e32 v126, v126, v142
	v_add_f32_e32 v127, v127, v143
	s_and_saveexec_b64 s[10:11], s[4:5]
	ds_write_b32 v87, v96 offset:6144
	ds_write_b32 v87, v97 offset:6148
	ds_write_b32 v87, v98 offset:6152
	ds_write_b32 v87, v99 offset:6156
	ds_write_b32 v87, v100 offset:6160
	ds_write_b32 v87, v101 offset:6164
	ds_write_b32 v87, v102 offset:6168
	ds_write_b32 v87, v103 offset:6172
	ds_write_b32 v87, v104 offset:6176
	ds_write_b32 v87, v105 offset:6180
	ds_write_b32 v87, v106 offset:6184
	ds_write_b32 v87, v107 offset:6188
	ds_write_b32 v87, v108 offset:6192
	ds_write_b32 v87, v109 offset:6196
	ds_write_b32 v87, v110 offset:6200
	ds_write_b32 v87, v111 offset:6204
	ds_write_b32 v87, v112 offset:6208
	ds_write_b32 v87, v113 offset:6212
	ds_write_b32 v87, v114 offset:6216
	ds_write_b32 v87, v115 offset:6220
	ds_write_b32 v87, v116 offset:6224
	ds_write_b32 v87, v117 offset:6228
	ds_write_b32 v87, v118 offset:6232
	ds_write_b32 v87, v119 offset:6236
	ds_write_b32 v87, v120 offset:6240
	ds_write_b32 v87, v121 offset:6244
	ds_write_b32 v87, v122 offset:6248
	ds_write_b32 v87, v123 offset:6252
	ds_write_b32 v87, v124 offset:6256
	ds_write_b32 v87, v125 offset:6260
	ds_write_b32 v87, v126 offset:6264
	ds_write_b32 v87, v127 offset:6268
	s_branch .LBB0_333
	s_nop 0

.LBB0_402:
	s_or_b64 exec, exec, s[4:5]
	v_readlane_b32 s4, v254, 18
	s_add_i32 s4, s6, s4
	v_readlane_b32 s6, v253, 42
	v_readlane_b32 s7, v253, 43
	s_waitcnt lgkmcnt(0)
	s_barrier
	s_load_dwordx4 s[8:11], s[6:7], 0x18
	s_ashr_i32 s5, s4, 31
	s_lshl_b64 s[20:21], s[4:5], 19
	s_movk_i32 s4, 0x183
	v_cmp_gt_i32_e64 s[4:5], s4, v62
	v_mov_b32_e32 v0, 0xff800000
	s_and_saveexec_b64 s[22:23], s[4:5]
	s_cbranch_execz .LBB0_408
	s_mov_b32 s6, 0xfe03f81
	v_mul_hi_i32 v0, v62, s6
	v_lshrrev_b32_e32 v2, 31, v0
	v_ashrrev_i32_e32 v0, 3, v0
	v_add_u32_e32 v2, v0, v2
	v_lshl_add_u32 v0, v2, 7, v2
	v_sub_u32_e32 v3, v62, v0
	v_cmp_ne_u32_e64 s[6:7], 0, v3
	s_and_saveexec_b64 s[26:27], s[6:7]
	s_xor_b64 s[6:7], exec, s[26:27]
	s_cbranch_execz .LBB0_405
	s_lshl_b64 s[26:27], s[20:21], 2
	v_lshlrev_b32_e32 v0, 1, v2
	s_waitcnt lgkmcnt(0)
	s_add_u32 s8, s8, s26
	v_lshlrev_b32_e32 v0, v0, v3
	s_addc_u32 s9, s9, s27
	s_lshl_b32 s17, s2, 2
	v_sub_u32_e32 v2, 0x800, v0
	s_add_u32 s8, s8, s17
	v_ashrrev_i32_e32 v3, 31, v2
	s_addc_u32 s9, s9, 0
	v_lshlrev_b64 v[2:3], 10, v[2:3]
	v_lshl_add_u64 v[14:15], s[8:9], 0, v[2:3]
	global_load_dwordx4 v[2:5], v[14:15], off offset:48
	global_load_dwordx4 v[6:9], v[14:15], off offset:32
	global_load_dwordx4 v[10:13], v[14:15], off offset:16
	global_load_dwordx4 v[16:19], v[14:15], off
	ds_read_b128 v[20:23], v1
	ds_read_b128 v[24:27], v1 offset:16
	ds_read_b128 v[28:31], v1 offset:32
	ds_read_b128 v[32:35], v1 offset:48
	s_waitcnt vmcnt(3) lgkmcnt(0)
	v_mul_f32_e32 v3, v3, v33
	s_waitcnt vmcnt(2)
	v_mul_f32_e32 v7, v7, v29
	s_waitcnt vmcnt(1)
	v_mul_f32_e32 v11, v11, v25
	s_waitcnt vmcnt(0)
	v_mul_f32_e32 v0, v17, v21
	v_fmac_f32_e32 v0, v16, v20
	v_fmac_f32_e32 v0, v18, v22
	v_fmac_f32_e32 v11, v10, v24
	v_fmac_f32_e32 v0, v19, v23
	v_fmac_f32_e32 v11, v12, v26
	v_fmac_f32_e32 v7, v6, v28
	v_add_f32_e32 v0, 0, v0
	v_fmac_f32_e32 v11, v13, v27
	v_fmac_f32_e32 v7, v8, v30
	v_fmac_f32_e32 v3, v2, v32
	v_add_f32_e32 v0, v0, v11
	v_fmac_f32_e32 v7, v9, v31
	v_fmac_f32_e32 v3, v4, v34
	v_add_f32_e32 v0, v0, v7
	v_fmac_f32_e32 v3, v5, v35
	v_add_f32_e32 v0, v0, v3
	global_load_dwordx4 v[2:5], v[14:15], off offset:112
	global_load_dwordx4 v[6:9], v[14:15], off offset:96
	global_load_dwordx4 v[10:13], v[14:15], off offset:80
	global_load_dwordx4 v[16:19], v[14:15], off offset:64
	ds_read_b128 v[20:23], v1 offset:80
	ds_read_b128 v[24:27], v1 offset:64
	s_waitcnt vmcnt(1) lgkmcnt(1)
	v_mul_f32_e32 v10, v10, v20
	v_mul_f32_e32 v11, v11, v21
	s_waitcnt vmcnt(0) lgkmcnt(0)
	v_mul_f32_e32 v16, v16, v24
	v_mul_f32_e32 v17, v17, v25
	v_mul_f32_e32 v18, v18, v26
	v_mul_f32_e32 v19, v19, v27
	v_mul_f32_e32 v12, v12, v22
	v_mul_f32_e32 v13, v13, v23
	v_mov_b32_e32 v20, v16
	v_mov_b32_e32 v21, v10
	v_mov_b32_e32 v10, v17
	v_add_f32_e32 v10, v20, v10
	v_add_f32_e32 v11, v21, v11
	v_mov_b32_e32 v16, v18
	v_mov_b32_e32 v17, v12
	v_add_f32_e32 v10, v10, v16
	v_add_f32_e32 v11, v11, v17
	v_mov_b32_e32 v12, v19
	v_add_f32_e32 v10, v10, v12
	v_add_f32_e32 v11, v11, v13
	s_nop 0
	v_add_f32_e32 v0, v0, v10
	v_add_f32_e32 v0, v0, v11
	ds_read_b128 v[10:13], v1 offset:112
	ds_read_b128 v[16:19], v1 offset:96
	s_waitcnt lgkmcnt(1)
	v_mul_f32_e32 v2, v2, v10
	v_mul_f32_e32 v3, v3, v11
	s_waitcnt lgkmcnt(0)
	v_mul_f32_e32 v6, v6, v16
	v_mul_f32_e32 v7, v7, v17
	v_mul_f32_e32 v8, v8, v18
	v_mul_f32_e32 v9, v9, v19
	v_mul_f32_e32 v4, v4, v12
	v_mul_f32_e32 v5, v5, v13
	v_mov_b32_e32 v10, v6
	v_mov_b32_e32 v11, v2
	v_mov_b32_e32 v2, v7
	v_add_f32_e32 v2, v10, v2
	v_add_f32_e32 v3, v11, v3
	v_mov_b32_e32 v6, v8
	v_mov_b32_e32 v7, v4
	v_add_f32_e32 v2, v2, v6
	v_add_f32_e32 v3, v3, v7
	v_mov_b32_e32 v4, v9
	v_add_f32_e32 v2, v2, v4
	v_add_f32_e32 v3, v3, v5
	s_nop 0
	v_add_f32_e32 v0, v0, v2
	v_add_f32_e32 v0, v0, v3
	global_load_dwordx4 v[2:5], v[14:15], off offset:176
	global_load_dwordx4 v[6:9], v[14:15], off offset:160
	global_load_dwordx4 v[10:13], v[14:15], off offset:144
	global_load_dwordx4 v[16:19], v[14:15], off offset:128
	ds_read_b128 v[20:23], v1 offset:144
	ds_read_b128 v[24:27], v1 offset:128
	s_waitcnt vmcnt(1) lgkmcnt(1)
	v_mul_f32_e32 v10, v10, v20
	v_mul_f32_e32 v11, v11, v21
	s_waitcnt vmcnt(0) lgkmcnt(0)
	v_mul_f32_e32 v16, v16, v24
	v_mul_f32_e32 v17, v17, v25
	v_mul_f32_e32 v18, v18, v26
	v_mul_f32_e32 v19, v19, v27
	v_mul_f32_e32 v12, v12, v22
	v_mul_f32_e32 v13, v13, v23
	v_mov_b32_e32 v20, v16
	v_mov_b32_e32 v21, v10
	v_mov_b32_e32 v10, v17
	v_add_f32_e32 v10, v20, v10
	v_add_f32_e32 v11, v21, v11
	v_mov_b32_e32 v16, v18
	v_mov_b32_e32 v17, v12
	v_add_f32_e32 v10, v10, v16
	v_add_f32_e32 v11, v11, v17
	v_mov_b32_e32 v12, v19
	v_add_f32_e32 v10, v10, v12
	v_add_f32_e32 v11, v11, v13
	s_nop 0
	v_add_f32_e32 v0, v0, v10
	v_add_f32_e32 v0, v0, v11
	ds_read_b128 v[10:13], v1 offset:176
	ds_read_b128 v[16:19], v1 offset:160
	s_waitcnt lgkmcnt(1)
	v_mul_f32_e32 v2, v2, v10
	v_mul_f32_e32 v3, v3, v11
	s_waitcnt lgkmcnt(0)
	v_mul_f32_e32 v6, v6, v16
	v_mul_f32_e32 v7, v7, v17
	v_mul_f32_e32 v8, v8, v18
	v_mul_f32_e32 v9, v9, v19
	v_mul_f32_e32 v4, v4, v12
	v_mul_f32_e32 v5, v5, v13
	v_mov_b32_e32 v10, v6
	v_mov_b32_e32 v11, v2
	v_mov_b32_e32 v2, v7
	v_add_f32_e32 v2, v10, v2
	v_add_f32_e32 v3, v11, v3
	v_mov_b32_e32 v6, v8
	v_mov_b32_e32 v7, v4
	v_add_f32_e32 v2, v2, v6
	v_add_f32_e32 v3, v3, v7
	v_mov_b32_e32 v4, v9
	v_add_f32_e32 v2, v2, v4
	v_add_f32_e32 v3, v3, v5
	s_nop 0
	v_add_f32_e32 v0, v0, v2
	v_add_f32_e32 v0, v0, v3
	global_load_dwordx4 v[2:5], v[14:15], off offset:240
	global_load_dwordx4 v[6:9], v[14:15], off offset:224
	global_load_dwordx4 v[10:13], v[14:15], off offset:208
	s_nop 0
	global_load_dwordx4 v[14:17], v[14:15], off offset:192
	ds_read_b128 v[18:21], v1 offset:208
	ds_read_b128 v[22:25], v1 offset:192
	s_waitcnt vmcnt(1) lgkmcnt(1)
	v_mul_f32_e32 v10, v10, v18
	v_mul_f32_e32 v11, v11, v19
	s_waitcnt vmcnt(0) lgkmcnt(0)
	v_mul_f32_e32 v14, v14, v22
	v_mul_f32_e32 v15, v15, v23
	v_mul_f32_e32 v16, v16, v24
	v_mul_f32_e32 v17, v17, v25
	v_mul_f32_e32 v12, v12, v20
	v_mul_f32_e32 v13, v13, v21
	v_mov_b32_e32 v18, v14
	v_mov_b32_e32 v19, v10
	v_mov_b32_e32 v10, v15
	v_add_f32_e32 v10, v18, v10
	v_add_f32_e32 v11, v19, v11
	v_mov_b32_e32 v14, v16
	v_mov_b32_e32 v15, v12
	v_add_f32_e32 v10, v10, v14
	v_add_f32_e32 v11, v11, v15
	v_mov_b32_e32 v12, v17
	v_add_f32_e32 v10, v10, v12
	v_add_f32_e32 v11, v11, v13
	s_nop 0
	v_add_f32_e32 v0, v0, v10
	v_add_f32_e32 v0, v0, v11
	ds_read_b128 v[10:13], v1 offset:240
	ds_read_b128 v[14:17], v1 offset:224
	s_waitcnt lgkmcnt(1)
	v_mul_f32_e32 v2, v2, v10
	v_mul_f32_e32 v3, v3, v11
	s_waitcnt lgkmcnt(0)
	v_mul_f32_e32 v6, v6, v14
	v_mul_f32_e32 v7, v7, v15
	v_mul_f32_e32 v8, v8, v16
	v_mul_f32_e32 v9, v9, v17
	v_mul_f32_e32 v4, v4, v12
	v_mul_f32_e32 v5, v5, v13
	v_mov_b32_e32 v10, v6
	v_mov_b32_e32 v11, v2
	v_mov_b32_e32 v2, v7
	v_add_f32_e32 v2, v10, v2
	v_add_f32_e32 v3, v11, v3
	v_mov_b32_e32 v6, v8
	v_mov_b32_e32 v7, v4
	v_add_f32_e32 v2, v2, v6
	v_add_f32_e32 v3, v3, v7
	v_mov_b32_e32 v4, v9
	v_add_f32_e32 v2, v2, v4
	v_add_f32_e32 v3, v3, v5
	s_nop 0
	v_add_f32_e32 v0, v0, v2
	v_add_f32_e32 v0, v0, v3
.LBB0_405:
	s_andn2_saveexec_b64 s[6:7], s[6:7]
	s_cbranch_execz .LBB0_407
	ds_read_b128 v[2:5], v1
	ds_read_b128 v[6:9], v1 offset:16
	ds_read_b128 v[10:13], v1 offset:32
	ds_read_b128 v[14:17], v1 offset:48
	ds_read_b128 v[18:21], v1 offset:256
	s_waitcnt lgkmcnt(0)
	v_fma_f32 v0, v2, v18, 0
	v_fmac_f32_e32 v0, v3, v19
	v_fmac_f32_e32 v0, v4, v20
	v_fmac_f32_e32 v0, v5, v21
	ds_read_b128 v[2:5], v1 offset:272
	s_waitcnt lgkmcnt(0)
	v_fmac_f32_e32 v0, v6, v2
	v_fmac_f32_e32 v0, v7, v3
	v_fmac_f32_e32 v0, v8, v4
	v_fmac_f32_e32 v0, v9, v5
	ds_read_b128 v[2:5], v1 offset:288
	s_waitcnt lgkmcnt(0)
	v_fmac_f32_e32 v0, v10, v2
	v_fmac_f32_e32 v0, v11, v3
	v_fmac_f32_e32 v0, v12, v4
	v_fmac_f32_e32 v0, v13, v5
	ds_read_b128 v[2:5], v1 offset:304
	s_waitcnt lgkmcnt(0)
	v_fmac_f32_e32 v0, v14, v2
	v_fmac_f32_e32 v0, v15, v3
	v_fmac_f32_e32 v0, v16, v4
	v_fmac_f32_e32 v0, v17, v5
	ds_read_b128 v[2:5], v1 offset:64
	ds_read_b128 v[6:9], v1 offset:320
	s_waitcnt lgkmcnt(0)
	v_fmac_f32_e32 v0, v2, v6
	v_fmac_f32_e32 v0, v3, v7
	v_fmac_f32_e32 v0, v4, v8
	v_fmac_f32_e32 v0, v5, v9
	ds_read_b128 v[2:5], v1 offset:80
	ds_read_b128 v[6:9], v1 offset:336
	s_waitcnt lgkmcnt(0)
	v_fmac_f32_e32 v0, v2, v6
	v_fmac_f32_e32 v0, v3, v7
	v_fmac_f32_e32 v0, v4, v8
	v_fmac_f32_e32 v0, v5, v9
	ds_read_b128 v[2:5], v1 offset:96
	ds_read_b128 v[6:9], v1 offset:352
	s_waitcnt lgkmcnt(0)
	v_fmac_f32_e32 v0, v2, v6
	v_fmac_f32_e32 v0, v3, v7
	v_fmac_f32_e32 v0, v4, v8
	v_fmac_f32_e32 v0, v5, v9
	ds_read_b128 v[2:5], v1 offset:112
	ds_read_b128 v[6:9], v1 offset:368
	s_waitcnt lgkmcnt(0)
	v_fmac_f32_e32 v0, v2, v6
	v_fmac_f32_e32 v0, v3, v7
	v_fmac_f32_e32 v0, v4, v8
	v_fmac_f32_e32 v0, v5, v9
	ds_read_b128 v[2:5], v1 offset:128
	ds_read_b128 v[6:9], v1 offset:384
	s_waitcnt lgkmcnt(0)
	v_fmac_f32_e32 v0, v2, v6
	v_fmac_f32_e32 v0, v3, v7
	v_fmac_f32_e32 v0, v4, v8
	v_fmac_f32_e32 v0, v5, v9
	ds_read_b128 v[2:5], v1 offset:144
	ds_read_b128 v[6:9], v1 offset:400
	s_waitcnt lgkmcnt(0)
	v_fmac_f32_e32 v0, v2, v6
	v_fmac_f32_e32 v0, v3, v7
	v_fmac_f32_e32 v0, v4, v8
	v_fmac_f32_e32 v0, v5, v9
	ds_read_b128 v[2:5], v1 offset:160
	ds_read_b128 v[6:9], v1 offset:416
	s_waitcnt lgkmcnt(0)
	v_fmac_f32_e32 v0, v2, v6
	v_fmac_f32_e32 v0, v3, v7
	v_fmac_f32_e32 v0, v4, v8
	v_fmac_f32_e32 v0, v5, v9
	ds_read_b128 v[2:5], v1 offset:176
	ds_read_b128 v[6:9], v1 offset:432
	s_waitcnt lgkmcnt(0)
	v_fmac_f32_e32 v0, v2, v6
	v_fmac_f32_e32 v0, v3, v7
	v_fmac_f32_e32 v0, v4, v8
	v_fmac_f32_e32 v0, v5, v9
	ds_read_b128 v[2:5], v1 offset:192
	ds_read_b128 v[6:9], v1 offset:448
	s_waitcnt lgkmcnt(0)
	v_fmac_f32_e32 v0, v2, v6
	v_fmac_f32_e32 v0, v3, v7
	v_fmac_f32_e32 v0, v4, v8
	v_fmac_f32_e32 v0, v5, v9
	ds_read_b128 v[2:5], v1 offset:208
	ds_read_b128 v[6:9], v1 offset:464
	s_waitcnt lgkmcnt(0)
	v_mul_f32_e32 v2, v2, v6
	v_mul_f32_e32 v3, v3, v7
	s_nop 0
	v_add_f32_e32 v0, v0, v2
	v_add_f32_e32 v0, v0, v3
	v_mul_f32_e32 v2, v4, v8
	v_mul_f32_e32 v3, v5, v9
	s_nop 0
	v_add_f32_e32 v0, v0, v2
	v_add_f32_e32 v0, v0, v3
	ds_read_b128 v[2:5], v1 offset:224
	ds_read_b128 v[6:9], v1 offset:480
	s_waitcnt lgkmcnt(0)
	v_mul_f32_e32 v2, v2, v6
	v_mul_f32_e32 v3, v3, v7
	s_nop 0
	v_add_f32_e32 v0, v0, v2
	v_add_f32_e32 v0, v0, v3
	v_mul_f32_e32 v2, v4, v8
	v_mul_f32_e32 v3, v5, v9
	s_nop 0
	v_add_f32_e32 v0, v0, v2
	v_add_f32_e32 v0, v0, v3
	ds_read_b128 v[2:5], v1 offset:240
	ds_read_b128 v[6:9], v1 offset:496
	s_waitcnt lgkmcnt(0)
	v_mul_f32_e32 v2, v2, v6
	v_mul_f32_e32 v3, v3, v7
	s_nop 0
	v_add_f32_e32 v0, v0, v2
	v_add_f32_e32 v0, v0, v3
	v_mul_f32_e32 v2, v4, v8
	v_mul_f32_e32 v3, v5, v9
	s_nop 0
	v_add_f32_e32 v0, v0, v2
	v_add_f32_e32 v0, v0, v3

.LBB0_464:
	s_or_b64 exec, exec, s[6:7]
	s_waitcnt vmcnt(0) lgkmcnt(0)
	v_fma_f32 v10, v10, v68, 0
	v_fma_f32 v11, v11, v68, 0
	v_fma_f32 v12, v12, v68, 0
	v_fma_f32 v13, v13, v68, 0
	v_fma_f32 v10, v14, v70, v10
	v_fma_f32 v11, v15, v70, v11
	v_fma_f32 v12, v16, v70, v12
	v_fma_f32 v13, v17, v70, v13
	v_fma_f32 v10, v18, v72, v10
	v_fma_f32 v11, v19, v72, v11
	v_fma_f32 v12, v20, v72, v12
	v_fma_f32 v13, v21, v72, v13
	v_fma_f32 v10, v22, v74, v10
	v_fma_f32 v11, v23, v74, v11
	v_fma_f32 v12, v24, v74, v12
	v_fma_f32 v13, v25, v74, v13
	v_fma_f32 v10, v26, v76, v10
	v_fma_f32 v11, v27, v76, v11
	v_fma_f32 v12, v28, v76, v12
	v_fma_f32 v13, v29, v76, v13
	v_fma_f32 v10, v30, v78, v10
	v_fma_f32 v11, v31, v78, v11
	v_fma_f32 v12, v32, v78, v12
	v_fma_f32 v13, v33, v78, v13
	v_fma_f32 v10, v34, v80, v10
	v_fma_f32 v11, v35, v80, v11
	v_fma_f32 v12, v36, v80, v12
	v_fma_f32 v13, v37, v80, v13
	v_fma_f32 v10, v38, v82, v10
	v_fma_f32 v11, v39, v82, v11
	v_fma_f32 v12, v40, v82, v12
	v_fma_f32 v13, v41, v82, v13
	v_fma_f32 v10, v42, v84, v10
	v_fma_f32 v11, v43, v84, v11
	v_fma_f32 v12, v44, v84, v12
	v_fma_f32 v13, v45, v84, v13
	v_fma_f32 v10, v46, v86, v10
	v_fma_f32 v11, v47, v86, v11
	v_fma_f32 v12, v48, v86, v12
	v_fma_f32 v13, v49, v86, v13
	v_fma_f32 v10, v50, v88, v10
	v_fma_f32 v11, v51, v88, v11
	v_fma_f32 v12, v52, v88, v12
	v_fma_f32 v13, v53, v88, v13
	v_lshlrev_b32_e32 v14, 8, v71
	v_fma_f32 v10, v54, v90, v10
	v_fma_f32 v11, v55, v90, v11
	v_fma_f32 v12, v56, v90, v12
	v_fma_f32 v13, v57, v90, v13
	v_add3_u32 v0, 0, v14, v0
	v_fma_f32 v10, v58, v92, v10
	v_fma_f32 v11, v59, v92, v11
	v_fma_f32 v12, v60, v92, v12
	v_fma_f32 v13, v61, v92, v13
	ds_write_b128 v0, v[10:13] offset:2944
	s_waitcnt lgkmcnt(0)
	s_barrier
	s_and_saveexec_b64 s[4:5], vcc
	s_cbranch_execz .LBB0_314
	v_add_u32_e32 v16, 0x80, v69
	ds_read2st64_b32 v[10:11], v16 offset0:11 offset1:12
	v_mov_b32_e32 v19, v6
	v_readlane_b32 s8, v254, 3
	v_readlane_b32 s9, v254, 4
	s_waitcnt lgkmcnt(0)
	v_add_f32_e32 v0, 0, v10
	v_add_f32_e32 v0, v0, v11
	ds_read2st64_b32 v[10:11], v16 offset0:13 offset1:14
	s_waitcnt lgkmcnt(0)
	v_add_f32_e32 v0, v0, v10
	v_add_f32_e32 v0, v0, v11
	ds_read2st64_b32 v[10:11], v16 offset0:15 offset1:16
	s_waitcnt lgkmcnt(0)
	v_add_f32_e32 v0, v0, v10
	v_add_f32_e32 v0, v0, v11
	ds_read2st64_b32 v[10:11], v16 offset0:17 offset1:18
	s_waitcnt lgkmcnt(0)
	v_add_f32_e32 v0, v0, v10
	v_add_f32_e32 v0, v0, v11
	ds_read2st64_b32 v[10:11], v16 offset0:19 offset1:20
	s_waitcnt lgkmcnt(0)
	v_add_f32_e32 v0, v0, v10
	v_add_f32_e32 v0, v0, v11
	ds_read2st64_b32 v[10:11], v16 offset0:21 offset1:22
	s_waitcnt lgkmcnt(0)
	v_add_f32_e32 v0, v0, v10
	v_add_f32_e32 v0, v0, v11
	ds_read2st64_b32 v[10:11], v16 offset0:23 offset1:24
	s_waitcnt lgkmcnt(0)
	v_add_f32_e32 v0, v0, v10
	v_add_f32_e32 v0, v0, v11
	ds_read2st64_b32 v[10:11], v16 offset0:25 offset1:26
	s_waitcnt lgkmcnt(0)
	v_add_f32_e32 v0, v0, v10
	v_add_f32_e32 v0, v0, v11
	ds_read2st64_b32 v[10:11], v16 offset0:27 offset1:28
	s_waitcnt lgkmcnt(0)
	v_add_f32_e32 v0, v0, v10
	v_add_f32_e32 v0, v0, v11
	ds_read2st64_b32 v[10:11], v16 offset0:29 offset1:30
	s_waitcnt lgkmcnt(0)
	v_add_f32_e32 v0, v0, v10
	v_add_f32_e32 v0, v0, v11
	ds_read2st64_b32 v[10:11], v16 offset0:31 offset1:32
	s_waitcnt lgkmcnt(0)
	v_add_f32_e32 v0, v0, v10
	v_add_f32_e32 v0, v0, v11
	ds_read2st64_b32 v[10:11], v16 offset0:33 offset1:34
	s_waitcnt lgkmcnt(0)
	v_add_f32_e32 v0, v0, v10
	v_add_f32_e32 v0, v0, v11
	ds_read2st64_b32 v[10:11], v16 offset0:35 offset1:36
	ds_read2st64_b32 v[12:13], v16 offset0:37 offset1:38
	ds_read2st64_b32 v[14:15], v16 offset0:39 offset1:40
	ds_read2st64_b32 v[16:17], v16 offset0:41 offset1:42
	s_waitcnt lgkmcnt(3)
	v_mov_b32_e32 v18, v10
	v_add_f32_e32 v18, v0, v18
	v_add_f32_e32 v19, v1, v19
	v_mov_b32_e32 v6, v11
	v_add_f32_e32 v6, v18, v6
	v_add_f32_e32 v7, v19, v7
	s_waitcnt lgkmcnt(2)
	v_mov_b32_e32 v10, v12
	v_mov_b32_e32 v11, v8
	v_add_f32_e32 v6, v6, v10
	v_add_f32_e32 v7, v7, v11
	v_mov_b32_e32 v8, v13
	v_add_f32_e32 v6, v6, v8
	v_add_f32_e32 v7, v7, v9
	s_waitcnt lgkmcnt(1)
	v_mov_b32_e32 v8, v14
	v_mov_b32_e32 v9, v2
	v_add_f32_e32 v6, v6, v8
	v_add_f32_e32 v7, v7, v9
	v_mov_b32_e32 v2, v15
	v_add_f32_e32 v2, v6, v2
	v_add_f32_e32 v3, v7, v3
	s_waitcnt lgkmcnt(0)
	v_mov_b32_e32 v6, v16
	v_mov_b32_e32 v7, v4
	v_add_f32_e32 v2, v2, v6
	v_add_f32_e32 v3, v3, v7
	v_mov_b32_e32 v4, v17
	v_add_f32_e32 v2, v2, v4
	v_add_f32_e32 v3, v3, v5
	s_nop 0
	v_div_scale_f32 v0, s[6:7], v3, v3, v2
	v_rcp_f32_e32 v4, v0
	s_lshl_b64 s[6:7], s[18:19], 11
	s_add_u32 s6, s8, s6
	s_addc_u32 s7, s9, s7
	v_fma_f32 v5, -v0, v4, 1.0
	v_fmac_f32_e32 v4, v5, v4
	v_div_scale_f32 v5, vcc, v2, v3, v2
	v_mul_f32_e32 v6, v5, v4
	v_fma_f32 v7, -v0, v6, v5
	v_fmac_f32_e32 v6, v7, v4
	s_lshl_b32 s2, s2, 1
	v_fma_f32 v0, -v0, v6, v5
	s_add_u32 s6, s6, s2
	v_div_fmas_f32 v0, v0, v4, v6
	s_addc_u32 s7, s7, 0
	v_div_fixup_f32 v0, v0, v3, v2
	v_lshl_add_u64 v[2:3], v[62:63], 1, s[6:7]
	v_cvt_pk_bf16_f32 v0, v0, v1
	global_store_short v[2:3], v0, off offset:512
	s_branch .LBB0_314

.LBB0_543:
	s_or_b64 exec, exec, s[14:15]
	v_add_u32_e32 v50, s44, v89
	ds_read_b32 v0, v128
	v_cvt_f32_i32_e32 v42, v50
	s_waitcnt lgkmcnt(0)
	v_mul_f32_e32 v0, v0, v42
	v_mul_f32_e32 v42, 0.15915494, v0
	v_rndne_f32_e32 v42, v42
	v_fmac_f32_e32 v0, 0xc0c90fdb, v42
	v_fmac_f32_e32 v0, 0x343bbd2e, v42
	v_mul_f32_e32 v0, 0.15915494, v0
	v_sin_f32_e32 v43, v0
	v_cos_f32_e32 v42, v0
	v_add_u32_e32 v0, 0, v87
	v_add_u32_e32 v0, 0x1bc00, v0
	ds_write_b64 v0, v[42:43]
	s_waitcnt lgkmcnt(0)
	s_barrier
	s_and_saveexec_b64 s[14:15], s[6:7]
	s_cbranch_execz .LBB0_547
	ds_read2st64_b32 v[42:43], v130 offset1:2
	v_readlane_b32 s28, v253, 50
	v_readlane_b32 s29, v253, 51
	s_waitcnt lgkmcnt(0)
	v_add_f32_e32 v0, 0, v42
	v_add_f32_e32 v0, v0, v43
	ds_read2st64_b32 v[42:43], v130 offset0:4 offset1:6
	s_waitcnt lgkmcnt(0)
	v_add_f32_e32 v0, v0, v42
	v_add_f32_e32 v0, v0, v43
	ds_read2st64_b32 v[42:43], v130 offset0:8 offset1:10
	s_waitcnt lgkmcnt(0)
	v_add_f32_e32 v0, v0, v42
	v_add_f32_e32 v0, v0, v43
	ds_read2st64_b32 v[42:43], v130 offset0:12 offset1:14
	s_waitcnt lgkmcnt(0)
	v_add_f32_e32 v0, v0, v42
	v_add_u32_e32 v42, s33, v129
	v_add_f32_e32 v51, v0, v43
	v_ashrrev_i32_e32 v43, 31, v42
	v_lshlrev_b64 v[44:45], 6, v[42:43]
	s_waitcnt vmcnt(0)
	v_mov_b64_e32 v[44:45], v[222:223]
	v_mov_b64_e32 v[46:47], v[224:225]
	v_mov_b64_e32 v[52:53], v[226:227]
	v_mov_b64_e32 v[54:55], v[228:229]
	v_mov_b64_e32 v[56:57], v[230:231]
	v_mov_b64_e32 v[58:59], v[232:233]
	v_mov_b64_e32 v[60:61], v[234:235]
	v_mov_b64_e32 v[62:63], v[236:237]
	s_mov_b32 s28, 0x800000
	v_mov_b32_e32 v0, v45
	v_mov_b32_e32 v64, v53
	v_mov_b32_e32 v48, v57
	v_mov_b32_e32 v49, v58
	v_mov_b32_e32 v65, v54
	v_mov_b32_e32 v57, v59
	v_mov_b32_e32 v53, v55
	v_add_f32_e32 v48, v48, v56
	v_add_f32_e32 v49, v49, v57
	v_add_f32_e32 v52, v64, v52
	v_add_f32_e32 v53, v65, v53
	v_add_f32_e32 v44, v44, v0
	v_add_f32_e32 v45, v45, v1
	v_mov_b32_e32 v0, v47
	v_pk_add_f32 v[48:49], v[48:49], v[48:49] op_sel:[0,1] op_sel_hi:[1,0]
	v_pk_add_f32 v[52:53], v[52:53], v[52:53] op_sel:[0,1] op_sel_hi:[1,0]
	v_add_f32_e32 v46, v46, v0
	v_add_f32_e32 v47, v47, v1
	v_mov_b32_e32 v49, v60
	v_mov_b32_e32 v53, v61
	v_mov_b32_e32 v45, v62
	v_mov_b32_e32 v47, v63
	v_add_f32_e32 v48, v48, v52
	v_add_f32_e32 v49, v49, v53
	v_add_f32_e32 v44, v44, v46
	v_add_f32_e32 v45, v45, v47
	s_nop 0
	v_add_f32_e32 v44, v48, v44
	v_add_f32_e32 v45, v49, v45
	s_nop 0
	v_add_f32_e32 v0, v44, v45
	v_fmamk_f32 v0, v0, 0x3a800000, v241
	v_cmp_gt_f32_e32 vcc, s28, v0
	v_mul_f32_e32 v44, 0x4b800000, v0
	v_readlane_b32 s28, v253, 42
	v_cndmask_b32_e32 v0, v0, v44, vcc
	v_readlane_b32 s29, v253, 43
	v_rsq_f32_e32 v0, v0
	s_nop 0
	v_mul_f32_e32 v44, 0x45800000, v0
	v_cndmask_b32_e32 v46, v0, v44, vcc
	v_mov_b32_e32 v0, v192
	s_mov_b32 s28, 0x41a00000
	v_fmac_f32_e32 v0, v51, v46
	v_cmp_nlt_f32_e32 vcc, s28, v0
	s_and_saveexec_b64 s[28:29], vcc
	s_cbranch_execz .LBB0_546
	v_mul_f32_e32 v0, 0x3fb8aa3b, v0
	v_exp_f32_e32 v0, v0
	s_mov_b32 s30, 0x3f2aaaab
	v_add_f32_e32 v46, 1.0, v0
	v_frexp_mant_f32_e32 v48, v46
	v_cvt_f64_f32_e32 v[44:45], v46
	v_frexp_exp_i32_f64_e32 v44, v[44:45]
	v_cmp_gt_f32_e32 vcc, s30, v48
	v_add_f32_e32 v47, -1.0, v46
	v_sub_f32_e32 v49, v47, v46
	v_subbrev_co_u32_e32 v51, vcc, 0, v44, vcc
	v_sub_u32_e32 v44, 0, v51
	v_sub_f32_e32 v47, v0, v47
	v_add_f32_e32 v49, 1.0, v49
	v_ldexp_f32 v45, v46, v44
	v_add_f32_e32 v47, v47, v49
	v_add_f32_e32 v46, -1.0, v45
	v_add_f32_e32 v48, 1.0, v45
	v_ldexp_f32 v44, v47, v44
	v_add_f32_e32 v47, 1.0, v46
	v_add_f32_e32 v49, -1.0, v48
	v_sub_f32_e32 v47, v45, v47
	v_sub_f32_e32 v45, v45, v49
	v_add_f32_e32 v47, v44, v47
	v_add_f32_e32 v44, v44, v45
	v_add_f32_e32 v54, v48, v44
	v_rcp_f32_e32 v56, v54
	v_sub_f32_e32 v45, v54, v48
	v_sub_f32_e32 v55, v44, v45
	v_add_f32_e32 v45, v46, v47
	v_mul_f32_e32 v58, v45, v56
	v_sub_f32_e32 v44, v45, v46
	v_mul_f32_e32 v46, v54, v58
	v_fma_f32 v48, v58, v54, -v46
	v_fmac_f32_e32 v48, v58, v55
	v_sub_f32_e32 v57, v47, v44
	v_add_f32_e32 v44, v46, v48
	v_sub_f32_e32 v47, v45, v44
	v_sub_f32_e32 v52, v44, v46
	v_sub_f32_e32 v53, v45, v47
	v_mov_b32_e32 v49, v44
	v_sub_f32_e32 v44, v52, v48
	v_sub_f32_e32 v45, v53, v49
	s_mov_b32 s30, 0x3f317218
	v_add_f32_e32 v45, v57, v45
	v_add_f32_e32 v44, v44, v45
	v_add_f32_e32 v45, v47, v44
	v_mul_f32_e32 v57, v56, v45
	v_mul_f32_e32 v46, v54, v57
	v_fma_f32 v48, v57, v54, -v46
	v_fmac_f32_e32 v48, v57, v55
	v_sub_f32_e32 v47, v47, v45
	v_add_f32_e32 v54, v44, v47
	v_add_f32_e32 v44, v46, v48
	v_sub_f32_e32 v47, v45, v44
	v_sub_f32_e32 v52, v44, v46
	v_sub_f32_e32 v53, v45, v47
	v_mov_b32_e32 v49, v44
	v_sub_f32_e32 v44, v52, v48
	v_sub_f32_e32 v45, v53, v49
	s_nop 0
	v_add_f32_e32 v45, v54, v45
	v_add_f32_e32 v44, v44, v45
	v_add_f32_e32 v45, v58, v57
	v_add_f32_e32 v44, v47, v44
	v_sub_f32_e32 v46, v45, v58
	v_mul_f32_e32 v44, v56, v44
	v_sub_f32_e32 v46, v57, v46
	v_add_f32_e32 v46, v46, v44
	v_add_f32_e32 v48, v45, v46
	v_mul_f32_e32 v49, v48, v48
	v_mov_b32_e32 v44, 0x3ecc95a3
	v_fmamk_f32 v44, v49, 0x3e9b6dac, v44
	v_fmaak_f32 v195, v49, v44, 0x3f2aaada
	v_cvt_f32_i32_e32 v44, v51
	v_sub_f32_e32 v45, v48, v45
	v_sub_f32_e32 v45, v46, v45
	v_ldexp_f32 v51, v45, 1
	v_mul_f32_e32 v45, v48, v49
	v_ldexp_f32 v47, v48, 1
	v_mul_f32_e32 v48, v44, v194
	v_mul_f32_e32 v49, v45, v195
	s_nop 0
	v_fma_f32 v46, v44, s30, -v48
	v_fmac_f32_e32 v46, 0xb102e308, v44
	v_add_f32_e32 v44, v48, v46
	v_add_f32_e32 v45, v49, v47
	v_mov_b32_e32 v52, v48
	v_sub_f32_e32 v47, v45, v47
	v_sub_f32_e32 v47, v49, v47
	v_add_f32_e32 v53, v51, v47
	v_sub_f32_e32 v48, v44, v48
	v_sub_f32_e32 v49, v45, v49
	v_add_f32_e32 v54, v44, v52
	v_add_f32_e32 v55, v45, v53
	v_mov_b32_e32 v47, v44
	v_mov_b32_e32 v49, v55
	v_sub_f32_e32 v56, v46, v48
	v_sub_f32_e32 v57, v47, v49
	v_add_f32_e32 v46, v46, v48
	v_add_f32_e32 v47, v47, v49
	v_mov_b32_e32 v52, v53
	v_sub_f32_e32 v48, v47, v44
	v_sub_f32_e32 v49, v46, v45
	v_sub_f32_e32 v58, v54, v48
	v_sub_f32_e32 v59, v55, v48
	v_mov_b32_e32 v54, v55
	v_mov_b32_e32 v55, v47
	v_pk_mov_b32 v[48:49], v[44:45], v[48:49] op_sel:[1,0]
	v_mov_b32_e32 v53, v44
	v_sub_f32_e32 v48, v54, v48
	v_sub_f32_e32 v49, v55, v49
	v_mov_b32_e32 v58, v56
	v_sub_f32_e32 v44, v52, v48
	v_sub_f32_e32 v45, v53, v49
	v_mov_b32_e32 v57, v47
	v_add_f32_e32 v48, v58, v44
	v_add_f32_e32 v49, v59, v45
	s_mov_b32 s30, 0x7f800000
	v_add_f32_e32 v52, v48, v49
	v_add_f32_e32 v53, v49, v48
	v_cmp_neq_f32_e32 vcc, s30, v0
	v_pk_add_f32 v[46:47], v[46:47], v[52:53] op_sel:[1,0] op_sel_hi:[0,1]
	v_mov_b32_e32 v49, v46
	v_sub_f32_e32 v54, v48, v56
	v_sub_f32_e32 v55, v49, v57
	v_mov_b32_e32 v45, v52
	v_sub_f32_e32 v47, v48, v54
	v_sub_f32_e32 v44, v44, v54
	v_sub_f32_e32 v45, v45, v55
	v_sub_f32_e32 v47, v56, v47
	v_add_f32_e32 v44, v44, v47
	v_add_f32_e32 v44, v44, v45
	v_add_f32_e32 v44, v46, v44
	v_mov_b32_e32 v45, 0x7f800000
	v_cndmask_b32_e32 v44, v45, v44, vcc
	v_cmp_ngt_f32_e32 vcc, -1.0, v0
	s_mov_b32 s30, 0x33800000
	s_nop 0
	v_cndmask_b32_e32 v44, v248, v44, vcc
	v_cmp_neq_f32_e32 vcc, -1.0, v0
	s_nop 1
	v_cndmask_b32_e32 v44, v244, v44, vcc
	v_cmp_lt_f32_e64 vcc, |v0|, s30
	s_nop 1
	v_cndmask_b32_e32 v0, v44, v0, vcc

.LBB0_554:
	s_or_b64 exec, exec, s[14:15]
	s_waitcnt lgkmcnt(0)
	s_barrier
	ds_read_b128 v[42:45], v143
	ds_read_b128 v[46:49], v131
	ds_read_b128 v[52:55], v143 offset:64
	ds_read_b128 v[56:59], v131 offset:64
	s_waitcnt lgkmcnt(2)
	v_mfma_f32_16x16x32_bf16 v[42:45], v[42:45], v[46:49], 0
	s_waitcnt lgkmcnt(0)
	v_mfma_f32_16x16x32_bf16 v[42:45], v[52:55], v[56:59], v[42:45]
	ds_read_b128 v[52:55], v143 offset:2304
	s_waitcnt vmcnt(1)
	v_lshlrev_b32_e32 v60, 16, v41
	s_waitcnt lgkmcnt(0)
	v_mfma_f32_16x16x32_bf16 v[46:49], v[52:55], v[46:49], 0
	ds_read_b128 v[52:55], v143 offset:2368
	v_and_b32_e32 v61, 0xffff0000, v41
	s_waitcnt vmcnt(0)
	v_lshlrev_b32_e32 v62, 16, v34
	v_and_b32_e32 v63, 0xffff0000, v34
	s_waitcnt lgkmcnt(0)
	v_mfma_f32_16x16x32_bf16 v[46:49], v[52:55], v[56:59], v[46:49]
	v_mov_b64_e32 v[52:53], v[188:189]
	v_mov_b64_e32 v[54:55], v[190:191]
	v_mov_b64_e32 v[56:57], v[196:197]
	v_mov_b64_e32 v[58:59], v[198:199]
	v_lshlrev_b32_e32 v64, 16, v35
	v_and_b32_e32 v65, 0xffff0000, v35
	v_lshlrev_b32_e32 v66, 16, v36
	v_and_b32_e32 v67, 0xffff0000, v36
	v_lshlrev_b32_e32 v68, 16, v37
	v_and_b32_e32 v69, 0xffff0000, v37
	s_movk_i32 s14, 0x1800
	v_cmp_gt_i32_e32 vcc, s14, v50
	s_or_b64 s[14:15], s[42:43], vcc
	v_mul_f32_e32 v0, v42, v56
	v_mul_f32_e32 v42, v43, v57
	v_cvt_pk_bf16_f32 v42, v0, v42
	v_mul_f32_e32 v0, v44, v58
	v_mul_f32_e32 v43, v45, v59
	v_cvt_pk_bf16_f32 v43, v0, v43
	v_mul_f32_e32 v0, v46, v52
	v_mul_f32_e32 v44, v47, v53
	v_mul_f32_e32 v45, v49, v55
	v_lshl_add_u64 v[46:47], v[96:97], 0, v[124:125]
	v_cvt_pk_bf16_f32 v44, v0, v44
	v_mul_f32_e32 v0, v48, v54
	v_cvt_pk_bf16_f32 v45, v0, v45
	global_store_dwordx4 v[46:47], v[42:45], off
	v_lshlrev_b32_e32 v58, 16, v40
	v_and_b32_e32 v59, 0xffff0000, v40
	ds_read_b128 v[34:37], v144
	ds_read_b128 v[40:43], v144 offset:16
	ds_read_b128 v[46:49], v144 offset:32
	ds_read_b128 v[52:55], v144 offset:48
	v_lshlrev_b32_e32 v44, 16, v38
	s_waitcnt lgkmcnt(3)
	v_mov_b32_e32 v71, v36
	v_mov_b32_e32 v36, v35
	v_and_b32_e32 v45, 0xffff0000, v38
	v_mov_b32_e32 v70, v34
	v_mul_f32_e32 v34, v36, v62
	v_mul_f32_e32 v35, v37, v63
	v_lshlrev_b32_e32 v56, 16, v39
	v_fma_f32 v34, v70, v44, -v34
	v_fma_f32 v35, v71, v45, -v35
	v_and_b32_e32 v57, 0xffff0000, v39
	v_mul_f32_e32 v38, v98, v34
	v_mul_f32_e32 v39, v99, v35
	v_mul_f32_e32 v34, v36, v44
	v_mul_f32_e32 v35, v37, v45
	s_waitcnt lgkmcnt(2)
	v_mov_b32_e32 v37, v42
	v_mov_b32_e32 v42, v41
	v_mov_b32_e32 v36, v40
	v_mul_f32_e32 v40, v42, v64
	v_mul_f32_e32 v41, v43, v65
	v_mul_f32_e32 v42, v42, v56
	v_mul_f32_e32 v43, v43, v57
	v_fma_f32 v40, v36, v56, -v40
	v_fma_f32 v41, v37, v57, -v41
	v_fma_f32 v36, v36, v64, v42
	v_fma_f32 v37, v37, v65, v43
	s_waitcnt lgkmcnt(1)
	v_mov_b32_e32 v43, v48
	v_mov_b32_e32 v48, v47
	v_mov_b32_e32 v42, v46
	v_mul_f32_e32 v44, v48, v66
	v_mul_f32_e32 v45, v49, v67
	v_fma_f32 v34, v70, v62, v34
	v_fma_f32 v35, v71, v63, v35
	v_fma_f32 v44, v42, v58, -v44
	v_fma_f32 v45, v43, v59, -v45
	v_mul_f32_e32 v34, v98, v34
	v_mul_f32_e32 v35, v99, v35
	v_mul_f32_e32 v46, v98, v44
	v_mul_f32_e32 v47, v99, v45
	v_mul_f32_e32 v44, v48, v58
	v_mul_f32_e32 v45, v49, v59
	v_mul_f32_e32 v40, v98, v40
	v_mul_f32_e32 v41, v99, v41
	v_fma_f32 v42, v42, v66, v44
	v_fma_f32 v43, v43, v67, v45
	s_waitcnt lgkmcnt(0)
	v_mov_b32_e32 v45, v54
	v_mov_b32_e32 v54, v53
	v_mov_b32_e32 v44, v52
	v_mul_f32_e32 v48, v54, v68
	v_mul_f32_e32 v49, v55, v69
	v_mul_f32_e32 v52, v54, v60
	v_mul_f32_e32 v53, v55, v61
	v_fma_f32 v48, v44, v60, -v48
	v_fma_f32 v49, v45, v61, -v49
	v_fma_f32 v44, v44, v68, v52
	v_fma_f32 v45, v45, v69, v53
	v_mul_f32_e32 v36, v98, v36
	v_mul_f32_e32 v37, v99, v37
	v_mul_f32_e32 v42, v98, v42
	v_mul_f32_e32 v43, v99, v43
	v_mul_f32_e32 v48, v98, v48
	v_mul_f32_e32 v49, v99, v49
	v_mul_f32_e32 v44, v98, v44
	v_mul_f32_e32 v45, v99, v45
	v_cvt_pk_bf16_f32 v52, v38, v39
	v_cvt_pk_bf16_f32 v53, v40, v41
	v_cvt_pk_bf16_f32 v54, v46, v47
	v_cvt_pk_bf16_f32 v55, v48, v49
	v_cvt_pk_bf16_f32 v56, v34, v35
	v_cvt_pk_bf16_f32 v57, v36, v37
	v_cvt_pk_bf16_f32 v58, v42, v43
	s_nop 0
	v_cvt_pk_bf16_f32 v59, v44, v45
	global_store_dwordx4 v[122:123], v[52:55], off offset:512
	global_store_dwordx4 v[122:123], v[56:59], off offset:576
	s_and_saveexec_b64 s[30:31], s[14:15]
	s_xor_b64 s[14:15], exec, s[30:31]
	s_cbranch_execnz .LBB0_568
	s_or_saveexec_b64 s[14:15], s[14:15]
	v_mov_b64_e32 v[70:71], s[28:29]
	s_xor_b64 exec, exec, s[14:15]
	s_cbranch_execnz .LBB0_569

.LBB0_583:
	s_andn2_b64 vcc, exec, s[4:5]
	s_cbranch_vccnz .LBB0_589
	s_lshl_b64 s[4:5], s[12:13], 11
	v_readlane_b32 s14, v253, 44
	v_and_b32_e32 v3, 63, v2
	v_readlane_b32 s15, v253, 45
	s_add_u32 s4, s14, s4
	s_addc_u32 s5, s15, s5
	v_lshlrev_b32_e32 v0, 1, v3
	v_ashrrev_i32_e32 v4, 6, v2
	v_lshlrev_b32_e32 v6, 10, v4
	v_ashrrev_i32_e32 v7, 31, v6
	v_lshl_add_u64 v[6:7], v[6:7], 1, s[16:17]
	v_lshl_add_u64 v[6:7], v[6:7], 0, v[0:1]
	global_load_ushort v36, v0, s[4:5]
	global_load_ushort v37, v0, s[4:5] offset:128
	global_load_ushort v38, v0, s[4:5] offset:256
	global_load_ushort v39, v0, s[4:5] offset:384
	global_load_ushort v40, v0, s[4:5] offset:512
	global_load_ushort v41, v0, s[4:5] offset:640
	global_load_ushort v42, v0, s[4:5] offset:768
	global_load_ushort v43, v0, s[4:5] offset:896
	global_load_ushort v44, v0, s[4:5] offset:1024
	global_load_ushort v45, v0, s[4:5] offset:1152
	global_load_ushort v46, v0, s[4:5] offset:1280
	global_load_ushort v47, v0, s[4:5] offset:1408
	global_load_ushort v48, v0, s[4:5] offset:1536
	global_load_ushort v49, v0, s[4:5] offset:1664
	global_load_ushort v50, v0, s[4:5] offset:1792
	global_load_ushort v51, v0, s[4:5] offset:1920
	global_load_ushort v52, v[6:7], off
	global_load_ushort v53, v[6:7], off offset:128
	global_load_ushort v54, v[6:7], off offset:256
	global_load_ushort v55, v[6:7], off offset:384
	global_load_ushort v56, v[6:7], off offset:512
	global_load_ushort v57, v[6:7], off offset:640
	global_load_ushort v58, v[6:7], off offset:768
	global_load_ushort v59, v[6:7], off offset:896
	global_load_ushort v60, v[6:7], off offset:1024
	global_load_ushort v61, v[6:7], off offset:1152
	global_load_ushort v62, v[6:7], off offset:1280
	global_load_ushort v63, v[6:7], off offset:1408
	global_load_ushort v64, v[6:7], off offset:1536
	global_load_ushort v65, v[6:7], off offset:1664
	global_load_ushort v66, v[6:7], off offset:1792
	global_load_ushort v67, v[6:7], off offset:1920
	s_waitcnt vmcnt(0)
	v_lshlrev_b32_e32 v36, 16, v36
	v_lshlrev_b32_e32 v37, 16, v37
	v_lshlrev_b32_e32 v38, 16, v38
	v_lshlrev_b32_e32 v39, 16, v39
	v_lshlrev_b32_e32 v40, 16, v40
	v_lshlrev_b32_e32 v41, 16, v41
	v_lshlrev_b32_e32 v42, 16, v42
	v_lshlrev_b32_e32 v43, 16, v43
	v_lshlrev_b32_e32 v44, 16, v44
	v_lshlrev_b32_e32 v45, 16, v45
	v_lshlrev_b32_e32 v46, 16, v46
	v_lshlrev_b32_e32 v47, 16, v47
	v_lshlrev_b32_e32 v48, 16, v48
	v_lshlrev_b32_e32 v49, 16, v49
	v_lshlrev_b32_e32 v50, 16, v50
	v_lshlrev_b32_e32 v51, 16, v51
	v_lshlrev_b32_e32 v52, 16, v52
	v_lshlrev_b32_e32 v53, 16, v53
	v_lshlrev_b32_e32 v54, 16, v54
	v_lshlrev_b32_e32 v55, 16, v55
	v_lshlrev_b32_e32 v56, 16, v56
	v_lshlrev_b32_e32 v57, 16, v57
	v_lshlrev_b32_e32 v58, 16, v58
	v_lshlrev_b32_e32 v59, 16, v59
	v_lshlrev_b32_e32 v60, 16, v60
	v_lshlrev_b32_e32 v61, 16, v61
	v_lshlrev_b32_e32 v62, 16, v62
	v_lshlrev_b32_e32 v63, 16, v63
	v_lshlrev_b32_e32 v64, 16, v64
	v_lshlrev_b32_e32 v65, 16, v65
	v_lshlrev_b32_e32 v66, 16, v66
	v_lshlrev_b32_e32 v67, 16, v67
	v_fma_f32 v8, v36, v52, 0
	v_mul_f32_e32 v5, v37, v37
	v_fmac_f32_e32 v5, v36, v36
	v_fmac_f32_e32 v8, v37, v53
	v_fmac_f32_e32 v5, v38, v38
	v_fmac_f32_e32 v8, v38, v54
	v_fmac_f32_e32 v5, v39, v39
	v_fmac_f32_e32 v8, v39, v55
	v_fmac_f32_e32 v5, v40, v40
	v_fmac_f32_e32 v8, v40, v56
	v_fmac_f32_e32 v5, v41, v41
	v_fmac_f32_e32 v8, v41, v57
	v_fmac_f32_e32 v5, v42, v42
	v_fmac_f32_e32 v8, v42, v58
	v_fmac_f32_e32 v5, v43, v43
	v_fmac_f32_e32 v8, v43, v59
	v_fmac_f32_e32 v5, v44, v44
	v_fmac_f32_e32 v8, v44, v60
	v_fmac_f32_e32 v5, v45, v45
	v_fmac_f32_e32 v8, v45, v61
	v_fmac_f32_e32 v5, v46, v46
	v_fmac_f32_e32 v8, v46, v62
	v_fmac_f32_e32 v5, v47, v47
	v_fmac_f32_e32 v8, v47, v63
	v_fmac_f32_e32 v5, v48, v48
	v_fmac_f32_e32 v8, v48, v64
	v_fmac_f32_e32 v5, v49, v49
	v_fmac_f32_e32 v8, v49, v65
	v_fmac_f32_e32 v5, v50, v50
	v_fmac_f32_e32 v8, v50, v66
	v_fmac_f32_e32 v5, v51, v51
	v_fmac_f32_e32 v8, v51, v67
	v_and_b32_e32 v0, 64, v243
	v_add_u32_e32 v6, 64, v0
	v_xor_b32_e32 v0, 32, v243
	v_cmp_lt_i32_e32 vcc, v0, v6
	s_nop 1
	v_cndmask_b32_e32 v0, v243, v0, vcc
	v_lshlrev_b32_e32 v7, 2, v0
	ds_bpermute_b32 v0, v7, v8
	ds_bpermute_b32 v7, v7, v5
	s_waitcnt lgkmcnt(1)
	v_add_f32_e32 v0, v8, v0
	v_xor_b32_e32 v8, 16, v243
	v_cmp_lt_i32_e32 vcc, v8, v6
	s_waitcnt lgkmcnt(0)
	v_add_f32_e32 v5, v5, v7
	v_cndmask_b32_e32 v8, v243, v8, vcc
	v_lshlrev_b32_e32 v8, 2, v8
	ds_bpermute_b32 v9, v8, v0
	ds_bpermute_b32 v7, v8, v5
	s_waitcnt lgkmcnt(1)
	v_add_f32_e32 v0, v0, v9
	v_xor_b32_e32 v9, 8, v243
	v_cmp_lt_i32_e32 vcc, v9, v6
	s_waitcnt lgkmcnt(0)
	v_add_f32_e32 v5, v5, v7
	v_cndmask_b32_e32 v9, v243, v9, vcc
	v_lshlrev_b32_e32 v9, 2, v9
	ds_bpermute_b32 v10, v9, v0
	ds_bpermute_b32 v7, v9, v5
	s_waitcnt lgkmcnt(1)
	v_add_f32_e32 v0, v0, v10
	v_xor_b32_e32 v10, 4, v243
	v_cmp_lt_i32_e32 vcc, v10, v6
	s_waitcnt lgkmcnt(0)
	v_add_f32_e32 v5, v5, v7
	v_cndmask_b32_e32 v10, v243, v10, vcc
	v_lshlrev_b32_e32 v10, 2, v10
	ds_bpermute_b32 v11, v10, v0
	ds_bpermute_b32 v7, v10, v5
	s_waitcnt lgkmcnt(1)
	v_add_f32_e32 v0, v0, v11
	v_xor_b32_e32 v11, 2, v243
	v_cmp_lt_i32_e32 vcc, v11, v6
	s_waitcnt lgkmcnt(0)
	v_add_f32_e32 v5, v5, v7
	v_cndmask_b32_e32 v11, v243, v11, vcc
	v_lshlrev_b32_e32 v11, 2, v11
	ds_bpermute_b32 v12, v11, v0
	ds_bpermute_b32 v7, v11, v5
	s_waitcnt lgkmcnt(1)
	v_add_f32_e32 v0, v0, v12
	v_xor_b32_e32 v12, 1, v243
	v_cmp_lt_i32_e32 vcc, v12, v6
	s_waitcnt lgkmcnt(0)
	v_add_f32_e32 v5, v5, v7
	v_cndmask_b32_e32 v6, v243, v12, vcc
	v_lshlrev_b32_e32 v12, 2, v6
	ds_bpermute_b32 v6, v12, v0
	ds_bpermute_b32 v7, v12, v5
	v_cmp_eq_u32_e32 vcc, 0, v3
	s_and_saveexec_b64 s[4:5], vcc
	s_cbranch_execz .LBB0_588
	s_waitcnt lgkmcnt(0)
	v_add_f32_e32 v3, v5, v7
	v_add_f32_e32 v5, v0, v6
	v_fmamk_f32 v0, v3, 0x3a800000, v241
	s_mov_b32 s9, 0x800000
	v_readlane_b32 s14, v253, 42
	v_cmp_gt_f32_e32 vcc, s9, v0
	v_mul_f32_e32 v3, 0x4b800000, v0
	v_readlane_b32 s15, v253, 43
	v_cndmask_b32_e32 v0, v0, v3, vcc
	s_load_dwordx2 s[14:15], s[14:15], 0x88
	v_rsq_f32_e32 v0, v0
	v_readlane_b32 s9, v253, 58
	v_mul_f32_e32 v3, 0x45800000, v0
	s_nop 0
	v_add_u32_e32 v6, s9, v4
	v_ashrrev_i32_e32 v7, 31, v6
	s_waitcnt lgkmcnt(0)
	v_lshl_add_u64 v[6:7], v[6:7], 2, s[14:15]
	v_cndmask_b32_e32 v3, v0, v3, vcc
	global_load_dword v0, v[6:7], off
	s_mov_b32 s9, 0x41a00000
	s_waitcnt vmcnt(0)
	v_fmac_f32_e32 v0, v5, v3
	v_cmp_nlt_f32_e32 vcc, s9, v0
	s_and_saveexec_b64 s[14:15], vcc
	s_cbranch_execz .LBB0_587
	v_mul_f32_e32 v0, 0x3fb8aa3b, v0
	v_exp_f32_e32 v0, v0
	s_mov_b32 s9, 0x3f2aaaab
	v_add_f32_e32 v3, 1.0, v0
	v_frexp_mant_f32_e32 v8, v3
	v_cvt_f64_f32_e32 v[6:7], v3
	v_add_f32_e32 v5, -1.0, v3
	v_frexp_exp_i32_f64_e32 v6, v[6:7]
	v_cmp_gt_f32_e32 vcc, s9, v8
	v_sub_f32_e32 v9, v5, v3
	v_sub_f32_e32 v5, v0, v5
	v_subbrev_co_u32_e32 v14, vcc, 0, v6, vcc
	v_add_f32_e32 v9, 1.0, v9
	v_sub_u32_e32 v6, 0, v14
	v_add_f32_e32 v5, v5, v9
	v_ldexp_f32 v3, v3, v6
	v_ldexp_f32 v5, v5, v6
	v_add_f32_e32 v6, -1.0, v3
	v_add_f32_e32 v7, 1.0, v6
	v_sub_f32_e32 v7, v3, v7
	v_add_f32_e32 v8, v5, v7
	v_add_f32_e32 v7, 1.0, v3
	v_add_f32_e32 v9, -1.0, v7
	v_sub_f32_e32 v3, v3, v9
	v_add_f32_e32 v3, v5, v3
	v_add_f32_e32 v5, v7, v3
	v_rcp_f32_e32 v15, v5
	v_sub_f32_e32 v7, v5, v7
	v_sub_f32_e32 v3, v3, v7
	v_add_f32_e32 v7, v6, v8
	v_sub_f32_e32 v6, v7, v6
	v_mul_f32_e32 v17, v7, v15
	v_sub_f32_e32 v16, v8, v6
	v_mul_f32_e32 v8, v5, v17
	v_fma_f32 v10, v17, v5, -v8
	v_fmac_f32_e32 v10, v17, v3
	v_add_f32_e32 v6, v8, v10
	v_sub_f32_e32 v9, v7, v6
	v_sub_f32_e32 v12, v6, v8
	v_sub_f32_e32 v13, v7, v9
	v_mov_b32_e32 v11, v6
	v_sub_f32_e32 v6, v12, v10
	v_sub_f32_e32 v7, v13, v11
	s_mov_b32 s9, 0x3f317218
	v_add_f32_e32 v7, v16, v7
	v_add_f32_e32 v6, v6, v7
	v_add_f32_e32 v7, v9, v6
	v_mul_f32_e32 v16, v15, v7
	v_mul_f32_e32 v8, v5, v16
	v_fma_f32 v10, v16, v5, -v8
	v_fmac_f32_e32 v10, v16, v3
	v_sub_f32_e32 v3, v9, v7
	v_add_f32_e32 v3, v6, v3
	v_add_f32_e32 v6, v8, v10
	v_sub_f32_e32 v9, v7, v6
	v_sub_f32_e32 v12, v6, v8
	v_sub_f32_e32 v13, v7, v9
	v_mov_b32_e32 v11, v6
	v_sub_f32_e32 v6, v12, v10
	v_sub_f32_e32 v7, v13, v11
	v_add_f32_e32 v5, v17, v16
	v_add_f32_e32 v3, v3, v7
	v_add_f32_e32 v3, v6, v3
	v_add_f32_e32 v3, v9, v3
	v_sub_f32_e32 v6, v5, v17
	v_mul_f32_e32 v3, v15, v3
	v_sub_f32_e32 v6, v16, v6
	v_add_f32_e32 v3, v6, v3
	v_add_f32_e32 v7, v5, v3
	v_mul_f32_e32 v8, v7, v7
	v_mov_b32_e32 v6, 0x3ecc95a3
	v_fmamk_f32 v6, v8, 0x3e9b6dac, v6
	v_fmaak_f32 v195, v8, v6, 0x3f2aaada
	v_cvt_f32_i32_e32 v6, v14
	v_sub_f32_e32 v5, v7, v5
	v_ldexp_f32 v9, v7, 1
	v_mul_f32_e32 v7, v7, v8
	v_mul_f32_e32 v10, v6, v194
	v_mul_f32_e32 v11, v7, v195
	v_sub_f32_e32 v3, v3, v5
	v_fma_f32 v8, v6, s9, -v10
	v_fmac_f32_e32 v8, 0xb102e308, v6
	v_add_f32_e32 v6, v10, v8
	v_add_f32_e32 v7, v11, v9
	v_ldexp_f32 v3, v3, 1
	v_sub_f32_e32 v5, v7, v9
	v_sub_f32_e32 v5, v11, v5
	v_add_f32_e32 v13, v3, v5
	v_mov_b32_e32 v12, v10
	v_sub_f32_e32 v10, v6, v10
	v_sub_f32_e32 v11, v7, v11
	v_add_f32_e32 v14, v6, v12
	v_add_f32_e32 v15, v7, v13
	v_mov_b32_e32 v9, v6
	v_mov_b32_e32 v11, v15
	v_sub_f32_e32 v16, v8, v10
	v_sub_f32_e32 v17, v9, v11
	v_add_f32_e32 v8, v8, v10
	v_add_f32_e32 v9, v9, v11
	v_mov_b32_e32 v12, v13
	v_sub_f32_e32 v10, v9, v6
	v_sub_f32_e32 v11, v8, v7
	v_sub_f32_e32 v18, v14, v10
	v_sub_f32_e32 v19, v15, v10
	v_mov_b32_e32 v14, v15
	v_mov_b32_e32 v15, v9
	v_pk_mov_b32 v[10:11], v[6:7], v[10:11] op_sel:[1,0]
	v_mov_b32_e32 v13, v6
	v_sub_f32_e32 v10, v14, v10
	v_sub_f32_e32 v11, v15, v11
	v_mov_b32_e32 v18, v16
	v_sub_f32_e32 v6, v12, v10
	v_sub_f32_e32 v7, v13, v11
	v_mov_b32_e32 v17, v9
	v_add_f32_e32 v10, v18, v6
	v_add_f32_e32 v11, v19, v7
	s_mov_b32 s9, 0x7f800000
	v_add_f32_e32 v12, v10, v11
	v_add_f32_e32 v13, v11, v10
	v_cmp_neq_f32_e32 vcc, s9, v0
	v_pk_add_f32 v[8:9], v[8:9], v[12:13] op_sel:[1,0] op_sel_hi:[0,1]
	v_mov_b32_e32 v11, v8
	v_sub_f32_e32 v14, v10, v16
	v_sub_f32_e32 v15, v11, v17
	v_mov_b32_e32 v7, v12
	v_sub_f32_e32 v3, v10, v14
	v_sub_f32_e32 v6, v6, v14
	v_sub_f32_e32 v7, v7, v15
	v_sub_f32_e32 v3, v16, v3
	v_add_f32_e32 v3, v6, v3
	v_add_f32_e32 v3, v3, v7
	v_add_f32_e32 v3, v8, v3
	v_mov_b32_e32 v5, 0x7f800000
	v_cndmask_b32_e32 v3, v5, v3, vcc
	v_cmp_ngt_f32_e32 vcc, -1.0, v0
	s_mov_b32 s9, 0x33800000
	s_nop 0
	v_cndmask_b32_e32 v3, v248, v3, vcc
	v_cmp_neq_f32_e32 vcc, -1.0, v0
	s_nop 1
	v_cndmask_b32_e32 v3, v244, v3, vcc
	v_cmp_lt_f32_e64 vcc, |v0|, s9
	s_nop 1
	v_cndmask_b32_e32 v0, v3, v0, vcc

.LBB0_614:
	s_and_b64 s[22:23], s[4:5], s[12:13]
	v_mov_b32_e32 v148, 0
	s_and_saveexec_b64 s[20:21], s[22:23]
	s_cbranch_execz .LBB0_616
	v_add_u32_e32 v138, s18, v142
	v_ashrrev_i32_e32 v139, 31, v138
	v_readlane_b32 s18, v253, 50
	v_lshlrev_b64 v[138:139], 6, v[138:139]
	v_readlane_b32 s19, v253, 51
	s_nop 1
	v_lshl_add_u64 v[156:157], s[18:19], 0, v[138:139]
	global_load_dwordx4 v[138:141], v[156:157], off offset:32
	global_load_dwordx4 v[148:151], v[156:157], off offset:16
	global_load_dwordx4 v[152:155], v[156:157], off
	s_nop 0
	global_load_dwordx4 v[156:159], v[156:157], off offset:48
	s_mov_b32 s18, 0x800000
	s_waitcnt vmcnt(0)
	v_mov_b32_e32 v162, v149
	v_mov_b32_e32 v160, v153
	v_mov_b32_e32 v161, v154
	v_mov_b32_e32 v163, v150
	v_mov_b32_e32 v153, v155
	v_mov_b32_e32 v149, v151
	v_mov_b32_e32 v150, v139
	v_add_f32_e32 v152, v160, v152
	v_add_f32_e32 v153, v161, v153
	v_add_f32_e32 v148, v162, v148
	v_add_f32_e32 v149, v163, v149
	v_add_f32_e32 v138, v138, v150
	v_add_f32_e32 v139, v139, v151
	v_mov_b32_e32 v150, v141
	v_pk_add_f32 v[152:153], v[152:153], v[152:153] op_sel:[0,1] op_sel_hi:[1,0]
	v_pk_add_f32 v[148:149], v[148:149], v[148:149] op_sel:[0,1] op_sel_hi:[1,0]
	v_add_f32_e32 v140, v140, v150
	v_add_f32_e32 v141, v141, v151
	v_mov_b32_e32 v153, v156
	v_mov_b32_e32 v149, v157
	v_mov_b32_e32 v139, v158
	v_mov_b32_e32 v141, v159
	v_add_f32_e32 v148, v152, v148
	v_add_f32_e32 v149, v153, v149
	v_add_f32_e32 v138, v138, v140
	v_add_f32_e32 v139, v139, v141
	s_nop 0
	v_add_f32_e32 v138, v148, v138
	v_add_f32_e32 v139, v149, v139
	s_nop 0
	v_add_f32_e32 v138, v138, v139
	v_fmamk_f32 v138, v138, 0x3a800000, v241
	v_cmp_gt_f32_e32 vcc, s18, v138
	v_mul_f32_e32 v139, 0x4b800000, v138
	s_nop 0
	v_cndmask_b32_e32 v138, v138, v139, vcc
	v_rsq_f32_e32 v138, v138
	s_nop 0
	v_mul_f32_e32 v139, 0x45800000, v138
	v_cndmask_b32_e32 v148, v138, v139, vcc
.LBB0_616:
	s_or_b64 exec, exec, s[20:21]
	v_lshl_add_u32 v138, s36, 10, v146
	ds_read2_b32 v[150:151], v138 offset1:16
	ds_read2_b32 v[152:153], v138 offset0:32 offset1:48
	ds_read2_b32 v[140:141], v138 offset0:128 offset1:144
	ds_read2_b32 v[138:139], v138 offset0:160 offset1:176
	v_readlane_b32 s20, v254, 1
	s_lshl_b32 s18, s41, 8
	s_waitcnt lgkmcnt(0)
	v_mul_f32_e32 v126, v126, v150
	v_mul_f32_e32 v127, v127, v150
	v_mul_f32_e32 v122, v122, v150
	v_mul_f32_e32 v123, v123, v150
	v_readlane_b32 s21, v254, 2
	v_lshl_add_u32 v149, s40, 8, v143
	s_ashr_i32 s19, s18, 31
	v_mul_f32_e32 v128, v128, v150
	v_mul_f32_e32 v129, v129, v150
	v_mul_f32_e32 v154, v124, v150
	v_mul_f32_e32 v155, v125, v150
	v_cvt_pk_bf16_f32 v124, v126, v127
	v_cvt_pk_bf16_f32 v126, v122, v123
	v_mov_b64_e32 v[122:123], s[20:21]
	s_movk_i32 s22, 0x1400
	v_cvt_pk_bf16_f32 v125, v128, v129
	v_mad_i64_i32 v[128:129], s[20:21], v149, s22, v[122:123]
	s_lshl_b64 s[18:19], s[18:19], 1
	v_lshl_add_u64 v[128:129], v[128:129], 0, s[18:19]
	v_lshl_add_u64 v[128:129], v[128:129], 0, s[2:3]
	v_lshl_add_u64 v[128:129], v[128:129], 0, v[0:1]
	v_cvt_pk_bf16_f32 v127, v154, v155
	global_store_dwordx4 v[128:129], v[124:127], off
	v_mul_f32_e32 v120, v120, v150
	v_mul_f32_e32 v121, v121, v150
	v_mul_f32_e32 v118, v118, v150
	v_mul_f32_e32 v119, v119, v150
	v_mul_f32_e32 v124, v112, v150
	v_mul_f32_e32 v125, v113, v150
	v_mul_f32_e32 v112, v110, v150
	v_mul_f32_e32 v113, v111, v150
	v_cvt_pk_bf16_f32 v110, v118, v119
	v_cvt_pk_bf16_f32 v111, v120, v121
	v_mul_f32_e32 v88, v88, v152
	v_mul_f32_e32 v89, v89, v152
	v_cvt_pk_bf16_f32 v112, v112, v113
	v_cvt_pk_bf16_f32 v113, v124, v125
	global_store_dwordx4 v[128:129], v[110:113], off offset:256
	v_mul_f32_e32 v86, v86, v152
	v_mul_f32_e32 v87, v87, v152
	v_mul_f32_e32 v62, v62, v140
	v_mul_f32_e32 v63, v63, v140
	v_or_b32_e32 v111, 16, v149
	v_mov_b32_e32 v110, v151
	v_mul_f32_e32 v112, v116, v110
	v_mul_f32_e32 v113, v117, v110
	v_mul_f32_e32 v116, v108, v110
	v_mul_f32_e32 v117, v109, v110
	v_mul_f32_e32 v108, v106, v110
	v_mul_f32_e32 v109, v107, v110
	v_cvt_pk_bf16_f32 v107, v112, v113
	v_mad_i64_i32 v[112:113], s[20:21], v111, s22, v[122:123]
	v_lshl_add_u64 v[112:113], v[112:113], 0, s[18:19]
	v_lshl_add_u64 v[112:113], v[112:113], 0, s[2:3]
	v_mul_f32_e32 v114, v114, v110
	v_mul_f32_e32 v115, v115, v110
	v_lshl_add_u64 v[112:113], v[112:113], 0, v[0:1]
	v_cvt_pk_bf16_f32 v106, v114, v115
	v_cvt_pk_bf16_f32 v108, v108, v109
	v_cvt_pk_bf16_f32 v109, v116, v117
	global_store_dwordx4 v[112:113], v[106:109], off
	v_mul_f32_e32 v104, v104, v110
	v_mul_f32_e32 v105, v105, v110
	v_mul_f32_e32 v102, v102, v110
	v_mul_f32_e32 v103, v103, v110
	v_mul_f32_e32 v106, v96, v110
	v_mul_f32_e32 v107, v97, v110
	v_mul_f32_e32 v96, v94, v110
	v_mul_f32_e32 v97, v95, v110
	v_cvt_pk_bf16_f32 v94, v102, v103
	v_cvt_pk_bf16_f32 v95, v104, v105
	v_or_b32_e32 v102, 32, v149
	v_cvt_pk_bf16_f32 v96, v96, v97
	v_cvt_pk_bf16_f32 v97, v106, v107
	global_store_dwordx4 v[112:113], v[94:97], off offset:256
	v_mul_f32_e32 v64, v64, v140
	v_mul_f32_e32 v65, v65, v140
	v_mul_f32_e32 v56, v56, v140
	v_mul_f32_e32 v57, v57, v140
	v_mul_f32_e32 v94, v100, v152
	v_mul_f32_e32 v95, v101, v152
	v_mul_f32_e32 v96, v98, v152
	v_mul_f32_e32 v97, v99, v152
	v_mul_f32_e32 v98, v92, v152
	v_mul_f32_e32 v99, v93, v152
	v_mul_f32_e32 v92, v90, v152
	v_mul_f32_e32 v93, v91, v152
	v_cvt_pk_bf16_f32 v91, v94, v95
	v_mad_i64_i32 v[94:95], s[20:21], v102, s22, v[122:123]
	v_lshl_add_u64 v[94:95], v[94:95], 0, s[18:19]
	v_lshl_add_u64 v[94:95], v[94:95], 0, s[2:3]
	v_cvt_pk_bf16_f32 v90, v96, v97
	v_lshl_add_u64 v[94:95], v[94:95], 0, v[0:1]
	v_cvt_pk_bf16_f32 v92, v92, v93
	v_cvt_pk_bf16_f32 v93, v98, v99
	global_store_dwordx4 v[94:95], v[90:93], off
	v_mul_f32_e32 v54, v54, v140
	v_mul_f32_e32 v55, v55, v140
	v_mul_f32_e32 v24, v24, v138
	v_mul_f32_e32 v25, v25, v138
	v_mul_f32_e32 v90, v80, v152
	v_mul_f32_e32 v91, v81, v152
	v_mul_f32_e32 v80, v78, v152
	v_mul_f32_e32 v81, v79, v152
	v_cvt_pk_bf16_f32 v78, v86, v87
	v_cvt_pk_bf16_f32 v79, v88, v89
	v_mul_f32_e32 v22, v22, v138
	v_mul_f32_e32 v23, v23, v138
	v_cvt_pk_bf16_f32 v80, v80, v81
	v_cvt_pk_bf16_f32 v81, v90, v91
	global_store_dwordx4 v[94:95], v[78:81], off offset:256
	s_nop 1
	v_or_b32_e32 v79, 48, v149
	v_mov_b32_e32 v78, v153
	v_mul_f32_e32 v80, v84, v78
	v_mul_f32_e32 v81, v85, v78
	v_mul_f32_e32 v84, v76, v78
	v_mul_f32_e32 v85, v77, v78
	v_mul_f32_e32 v76, v74, v78
	v_mul_f32_e32 v77, v75, v78
	v_cvt_pk_bf16_f32 v75, v80, v81
	v_mad_i64_i32 v[80:81], s[20:21], v79, s22, v[122:123]
	v_lshl_add_u64 v[80:81], v[80:81], 0, s[18:19]
	v_lshl_add_u64 v[80:81], v[80:81], 0, s[2:3]
	v_mul_f32_e32 v82, v82, v78
	v_mul_f32_e32 v83, v83, v78
	v_lshl_add_u64 v[80:81], v[80:81], 0, v[0:1]
	v_cvt_pk_bf16_f32 v74, v82, v83
	v_cvt_pk_bf16_f32 v76, v76, v77
	v_cvt_pk_bf16_f32 v77, v84, v85
	global_store_dwordx4 v[80:81], v[74:77], off
	v_mul_f32_e32 v72, v72, v78
	v_mul_f32_e32 v73, v73, v78
	v_mul_f32_e32 v70, v70, v78
	v_mul_f32_e32 v71, v71, v78
	v_mul_f32_e32 v74, v68, v78
	v_mul_f32_e32 v75, v69, v78
	v_mul_f32_e32 v68, v66, v78
	v_mul_f32_e32 v69, v67, v78
	v_cvt_pk_bf16_f32 v66, v70, v71
	v_cvt_pk_bf16_f32 v67, v72, v73
	s_nop 0
	v_cvt_pk_bf16_f32 v68, v68, v69
	v_cvt_pk_bf16_f32 v69, v74, v75
	global_store_dwordx4 v[80:81], v[66:69], off offset:256
	s_nop 1
	v_add_u32_e32 v68, 0x80, v149
	v_mul_f32_e32 v66, v60, v140
	v_mul_f32_e32 v67, v61, v140
	v_mul_f32_e32 v60, v58, v140
	v_mul_f32_e32 v61, v59, v140
	v_cvt_pk_bf16_f32 v58, v62, v63
	v_mad_i64_i32 v[62:63], s[20:21], v68, s22, v[122:123]
	v_lshl_add_u64 v[62:63], v[62:63], 0, s[18:19]
	v_lshl_add_u64 v[62:63], v[62:63], 0, s[2:3]
	v_cvt_pk_bf16_f32 v59, v64, v65
	v_lshl_add_u64 v[62:63], v[62:63], 0, v[0:1]
	v_cvt_pk_bf16_f32 v60, v60, v61
	v_cvt_pk_bf16_f32 v61, v66, v67
	global_store_dwordx4 v[62:63], v[58:61], off
	s_nop 1
	v_mul_f32_e32 v58, v48, v140
	v_mul_f32_e32 v59, v49, v140
	v_mul_f32_e32 v48, v46, v140
	v_mul_f32_e32 v49, v47, v140
	v_cvt_pk_bf16_f32 v46, v54, v55
	v_cvt_pk_bf16_f32 v47, v56, v57
	s_nop 0
	v_cvt_pk_bf16_f32 v48, v48, v49
	v_cvt_pk_bf16_f32 v49, v58, v59
	global_store_dwordx4 v[62:63], v[46:49], off offset:256
	s_nop 1
	v_add_u32_e32 v47, 0x90, v149
	v_mov_b32_e32 v46, v141
	v_mul_f32_e32 v48, v52, v46
	v_mul_f32_e32 v49, v53, v46
	v_mul_f32_e32 v52, v44, v46
	v_mul_f32_e32 v53, v45, v46
	v_mul_f32_e32 v44, v42, v46
	v_mul_f32_e32 v45, v43, v46
	v_cvt_pk_bf16_f32 v43, v48, v49
	v_mad_i64_i32 v[48:49], s[20:21], v47, s22, v[122:123]
	v_lshl_add_u64 v[48:49], v[48:49], 0, s[18:19]
	v_lshl_add_u64 v[48:49], v[48:49], 0, s[2:3]
	v_mul_f32_e32 v50, v50, v46
	v_mul_f32_e32 v51, v51, v46
	v_lshl_add_u64 v[48:49], v[48:49], 0, v[0:1]
	v_cvt_pk_bf16_f32 v42, v50, v51
	v_cvt_pk_bf16_f32 v44, v44, v45
	v_cvt_pk_bf16_f32 v45, v52, v53
	global_store_dwordx4 v[48:49], v[42:45], off
	v_mul_f32_e32 v40, v40, v46
	v_mul_f32_e32 v41, v41, v46
	v_mul_f32_e32 v38, v38, v46
	v_mul_f32_e32 v39, v39, v46
	v_mul_f32_e32 v42, v32, v46
	v_mul_f32_e32 v43, v33, v46
	v_mul_f32_e32 v32, v30, v46
	v_mul_f32_e32 v33, v31, v46
	v_cvt_pk_bf16_f32 v30, v38, v39
	v_cvt_pk_bf16_f32 v31, v40, v41
	v_add_u32_e32 v38, 0xa0, v149
	v_cvt_pk_bf16_f32 v32, v32, v33
	v_cvt_pk_bf16_f32 v33, v42, v43
	global_store_dwordx4 v[48:49], v[30:33], off offset:256
	s_nop 1
	v_mul_f32_e32 v30, v36, v138
	v_mul_f32_e32 v31, v37, v138
	v_mul_f32_e32 v32, v34, v138
	v_mul_f32_e32 v33, v35, v138
	v_mul_f32_e32 v34, v28, v138
	v_mul_f32_e32 v35, v29, v138
	v_mul_f32_e32 v28, v26, v138
	v_mul_f32_e32 v29, v27, v138
	v_cvt_pk_bf16_f32 v27, v30, v31
	v_mad_i64_i32 v[30:31], s[20:21], v38, s22, v[122:123]
	v_lshl_add_u64 v[30:31], v[30:31], 0, s[18:19]
	v_lshl_add_u64 v[30:31], v[30:31], 0, s[2:3]
	v_cvt_pk_bf16_f32 v26, v32, v33
	v_lshl_add_u64 v[30:31], v[30:31], 0, v[0:1]
	v_cvt_pk_bf16_f32 v28, v28, v29
	v_cvt_pk_bf16_f32 v29, v34, v35
	global_store_dwordx4 v[30:31], v[26:29], off
	s_nop 1
	v_mul_f32_e32 v26, v16, v138
	v_mul_f32_e32 v27, v17, v138
	v_mul_f32_e32 v16, v14, v138
	v_mul_f32_e32 v17, v15, v138
	v_cvt_pk_bf16_f32 v14, v22, v23
	v_cvt_pk_bf16_f32 v15, v24, v25
	s_nop 0
	v_cvt_pk_bf16_f32 v16, v16, v17
	v_cvt_pk_bf16_f32 v17, v26, v27
	global_store_dwordx4 v[30:31], v[14:17], off offset:256
	s_nop 1
	v_add_u32_e32 v15, 0xb0, v149
	v_mov_b32_e32 v14, v139
	v_mul_f32_e32 v16, v20, v14
	v_mul_f32_e32 v17, v21, v14
	v_mul_f32_e32 v20, v12, v14
	v_mul_f32_e32 v21, v13, v14
	v_mul_f32_e32 v12, v10, v14
	v_mul_f32_e32 v13, v11, v14
	v_cvt_pk_bf16_f32 v11, v16, v17
	v_mad_i64_i32 v[16:17], s[20:21], v15, s22, v[122:123]
	v_lshl_add_u64 v[16:17], v[16:17], 0, s[18:19]
	v_lshl_add_u64 v[16:17], v[16:17], 0, s[2:3]
	v_mul_f32_e32 v18, v18, v14
	v_mul_f32_e32 v19, v19, v14
	v_lshl_add_u64 v[16:17], v[16:17], 0, v[0:1]
	v_cvt_pk_bf16_f32 v10, v18, v19
	v_cvt_pk_bf16_f32 v12, v12, v13
	v_cvt_pk_bf16_f32 v13, v20, v21
	global_store_dwordx4 v[16:17], v[10:13], off
	v_mul_f32_e32 v8, v8, v14
	v_mul_f32_e32 v9, v9, v14
	v_mul_f32_e32 v6, v6, v14
	v_mul_f32_e32 v7, v7, v14
	v_mul_f32_e32 v10, v4, v14
	v_mul_f32_e32 v11, v5, v14
	v_mul_f32_e32 v4, v2, v14
	v_mul_f32_e32 v5, v3, v14
	v_cvt_pk_bf16_f32 v2, v6, v7
	v_cvt_pk_bf16_f32 v3, v8, v9
	s_nop 0
	v_cvt_pk_bf16_f32 v4, v4, v5
	v_cvt_pk_bf16_f32 v5, v10, v11
	global_store_dwordx4 v[16:17], v[2:5], off offset:256
	s_andn2_b64 vcc, exec, s[12:13]
	s_mov_b64 s[12:13], -1
	s_cbranch_vccnz .LBB0_607
	s_and_saveexec_b64 s[12:13], s[4:5]
	s_lshl_b32 s18, s36, 8
	s_xor_b32 s18, s18, 0x100
	v_lshl_add_u32 v2, s18, 2, v145
	ds_write_b32 v2, v148
	s_or_b64 exec, exec, s[12:13]
	s_andn2_b64 vcc, exec, s[8:9]
	s_cbranch_vccnz .LBB0_606
	s_barrier
	s_branch .LBB0_606

.LBB0_691:
	s_and_b64 s[20:21], s[40:41], s[10:11]
	v_mov_b32_e32 v153, 0
	s_and_saveexec_b64 s[18:19], s[20:21]
	s_cbranch_execz .LBB0_693
	v_add_u32_e32 v136, s16, v146
	v_ashrrev_i32_e32 v137, 31, v136
	v_readlane_b32 s16, v253, 50
	v_lshlrev_b64 v[136:137], 6, v[136:137]
	v_readlane_b32 s17, v253, 51
	s_nop 1
	v_lshl_add_u64 v[144:145], s[16:17], 0, v[136:137]
	global_load_dwordx4 v[136:139], v[144:145], off offset:32
	global_load_dwordx4 v[140:143], v[144:145], off offset:16
	global_load_dwordx4 v[154:157], v[144:145], off
	global_load_dwordx4 v[158:161], v[144:145], off offset:48
	s_mov_b32 s16, 0x800000
	s_waitcnt vmcnt(0)
	v_mov_b32_e32 v162, v141
	v_mov_b32_e32 v144, v155
	v_mov_b32_e32 v145, v156
	v_mov_b32_e32 v163, v142
	v_mov_b32_e32 v155, v157
	v_mov_b32_e32 v141, v143
	v_mov_b32_e32 v142, v137
	v_add_f32_e32 v144, v144, v154
	v_add_f32_e32 v145, v145, v155
	v_add_f32_e32 v140, v162, v140
	v_add_f32_e32 v141, v163, v141
	v_add_f32_e32 v136, v136, v142
	v_add_f32_e32 v137, v137, v143
	v_mov_b32_e32 v142, v139
	v_pk_add_f32 v[144:145], v[144:145], v[144:145] op_sel:[0,1] op_sel_hi:[1,0]
	v_pk_add_f32 v[140:141], v[140:141], v[140:141] op_sel:[0,1] op_sel_hi:[1,0]
	v_add_f32_e32 v138, v138, v142
	v_add_f32_e32 v139, v139, v143
	v_mov_b32_e32 v145, v158
	v_mov_b32_e32 v141, v159
	v_mov_b32_e32 v137, v160
	v_mov_b32_e32 v139, v161
	v_add_f32_e32 v140, v144, v140
	v_add_f32_e32 v141, v145, v141
	v_add_f32_e32 v136, v136, v138
	v_add_f32_e32 v137, v137, v139
	s_nop 0
	v_add_f32_e32 v136, v140, v136
	v_add_f32_e32 v137, v141, v137
	s_nop 0
	v_add_f32_e32 v136, v136, v137
	v_fmamk_f32 v136, v136, 0x3a800000, v241
	v_cmp_gt_f32_e32 vcc, s16, v136
	v_mul_f32_e32 v137, 0x4b800000, v136
	s_nop 0
	v_cndmask_b32_e32 v136, v136, v137, vcc
	v_rsq_f32_e32 v136, v136
	s_nop 0
	v_mul_f32_e32 v137, 0x45800000, v136
	v_cndmask_b32_e32 v153, v136, v137, vcc
.LBB0_693:
	s_or_b64 exec, exec, s[18:19]
	v_lshl_add_u32 v136, s33, 10, v150
	ds_read2_b32 v[142:143], v136 offset1:16
	ds_read2_b32 v[140:141], v136 offset0:32 offset1:48
	ds_read2_b32 v[138:139], v136 offset0:128 offset1:144
	ds_read2_b32 v[136:137], v136 offset0:160 offset1:176
	v_readlane_b32 s16, v254, 1
	s_waitcnt lgkmcnt(0)
	v_mul_f32_e32 v126, v126, v142
	v_mul_f32_e32 v127, v127, v142
	v_mul_f32_e32 v128, v128, v142
	v_mul_f32_e32 v129, v129, v142
	v_mul_f32_e32 v120, v120, v142
	v_mul_f32_e32 v121, v121, v142
	v_mul_f32_e32 v118, v118, v142
	v_mul_f32_e32 v119, v119, v142
	v_mul_f32_e32 v124, v124, v142
	v_mul_f32_e32 v125, v125, v142
	v_mul_f32_e32 v122, v122, v142
	v_mul_f32_e32 v123, v123, v142
	v_mul_f32_e32 v116, v116, v142
	v_mul_f32_e32 v117, v117, v142
	v_mul_f32_e32 v114, v114, v142
	v_mul_f32_e32 v115, v115, v142
	v_mul_f32_e32 v142, 0xbfb8aa3b, v126
	v_exp_f32_e32 v142, v142
	v_lshl_or_b32 v144, s38, 7, v151
	v_readlane_b32 s17, v254, 2
	v_lshl_add_u32 v154, s37, 8, v147
	v_add_f32_e32 v142, 1.0, v142
	v_rcp_f32_e32 v142, v142
	v_ashrrev_i32_e32 v145, 31, v144
	s_movk_i32 s18, 0x1600
	v_mul_f32_e32 v94, v94, v140
	v_mul_f32_e32 v95, v95, v140
	v_mul_f32_e32 v126, v126, v142
	v_mul_f32_e32 v118, v118, v126
	v_mul_f32_e32 v126, 0xbfb8aa3b, v127
	v_exp_f32_e32 v126, v126
	v_mul_f32_e32 v86, v86, v140
	v_mul_f32_e32 v87, v87, v140
	v_mul_f32_e32 v96, v96, v140
	v_mul_f32_e32 v97, v97, v140
	v_mul_f32_e32 v88, v88, v140
	v_mul_f32_e32 v89, v89, v140
	v_add_f32_e32 v126, 1.0, v126
	v_rcp_f32_e32 v126, v126
	v_mul_f32_e32 v90, v90, v140
	v_mul_f32_e32 v91, v91, v140
	v_mul_f32_e32 v92, v92, v140
	v_mul_f32_e32 v93, v93, v140
	v_mul_f32_e32 v62, v62, v138
	v_mul_f32_e32 v63, v63, v138
	v_mul_f32_e32 v126, v127, v126
	v_mul_f32_e32 v119, v119, v126
	v_cvt_pk_bf16_f32 v118, v118, v119
	v_mul_f32_e32 v119, 0xbfb8aa3b, v128
	v_exp_f32_e32 v119, v119
	v_mul_f32_e32 v54, v54, v138
	v_mul_f32_e32 v55, v55, v138
	v_mul_f32_e32 v64, v64, v138
	v_mul_f32_e32 v65, v65, v138
	v_mul_f32_e32 v56, v56, v138
	v_mul_f32_e32 v57, v57, v138
	v_add_f32_e32 v119, 1.0, v119
	v_rcp_f32_e32 v119, v119
	v_mul_f32_e32 v58, v58, v138
	v_mul_f32_e32 v59, v59, v138
	v_mul_f32_e32 v60, v60, v138
	v_mul_f32_e32 v61, v61, v138
	v_mul_f32_e32 v30, v30, v136
	v_mul_f32_e32 v31, v31, v136
	v_mul_f32_e32 v119, v128, v119
	v_mul_f32_e32 v119, v120, v119
	v_mul_f32_e32 v120, 0xbfb8aa3b, v129
	v_exp_f32_e32 v120, v120
	v_mul_f32_e32 v22, v22, v136
	v_mul_f32_e32 v23, v23, v136
	v_mul_f32_e32 v32, v32, v136
	v_mul_f32_e32 v33, v33, v136
	v_mul_f32_e32 v24, v24, v136
	v_mul_f32_e32 v25, v25, v136
	v_add_f32_e32 v120, 1.0, v120
	v_rcp_f32_e32 v120, v120
	v_mul_f32_e32 v26, v26, v136
	v_mul_f32_e32 v27, v27, v136
	v_mul_f32_e32 v28, v28, v136
	v_mul_f32_e32 v29, v29, v136
	v_mul_f32_e32 v120, v129, v120
	v_mul_f32_e32 v120, v121, v120
	v_cvt_pk_bf16_f32 v119, v119, v120
	v_mul_f32_e32 v120, 0xbfb8aa3b, v122
	v_exp_f32_e32 v120, v120
	s_nop 0
	v_add_f32_e32 v120, 1.0, v120
	v_rcp_f32_e32 v120, v120
	s_nop 0
	v_mul_f32_e32 v120, v122, v120
	v_mul_f32_e32 v114, v114, v120
	v_mul_f32_e32 v120, 0xbfb8aa3b, v123
	v_exp_f32_e32 v120, v120
	s_nop 0
	v_add_f32_e32 v120, 1.0, v120
	v_rcp_f32_e32 v120, v120
	s_nop 0
	v_mul_f32_e32 v120, v123, v120
	v_mul_f32_e32 v115, v115, v120
	v_cvt_pk_bf16_f32 v120, v114, v115
	v_mul_f32_e32 v114, 0xbfb8aa3b, v124
	v_mul_f32_e32 v115, 0xbfb8aa3b, v125
	v_exp_f32_e32 v114, v114
	v_exp_f32_e32 v115, v115
	v_add_f32_e32 v114, 1.0, v114
	v_add_f32_e32 v115, 1.0, v115
	v_rcp_f32_e32 v114, v114
	v_rcp_f32_e32 v115, v115
	v_mul_f32_e32 v114, v124, v114
	v_mul_f32_e32 v115, v125, v115
	v_mul_f32_e32 v114, v116, v114
	v_mul_f32_e32 v115, v117, v115
	v_cvt_pk_bf16_f32 v121, v114, v115
	v_mov_b64_e32 v[114:115], s[16:17]
	v_mad_i64_i32 v[122:123], s[16:17], v154, s18, v[114:115]
	v_lshlrev_b64 v[116:117], 1, v[144:145]
	v_lshl_add_u64 v[122:123], v[122:123], 0, v[116:117]
	global_store_dwordx4 v[122:123], v[118:121], off
	s_nop 1
	v_or_b32_e32 v119, 16, v154
	v_mov_b32_e32 v118, v143
	v_mul_f32_e32 v110, v110, v118
	v_mul_f32_e32 v111, v111, v118
	v_mul_f32_e32 v120, v100, v118
	v_mul_f32_e32 v121, v101, v118
	v_mul_f32_e32 v100, v98, v118
	v_mul_f32_e32 v101, v99, v118
	v_mul_f32_e32 v98, 0xbfb8aa3b, v110
	v_mul_f32_e32 v99, 0xbfb8aa3b, v111
	v_exp_f32_e32 v98, v98
	v_exp_f32_e32 v99, v99
	v_mul_f32_e32 v102, v102, v118
	v_mul_f32_e32 v103, v103, v118
	v_mul_f32_e32 v112, v112, v118
	v_mul_f32_e32 v113, v113, v118
	v_add_f32_e32 v98, 1.0, v98
	v_add_f32_e32 v99, 1.0, v99
	v_rcp_f32_e32 v98, v98
	v_rcp_f32_e32 v99, v99
	v_mul_f32_e32 v104, v104, v118
	v_mul_f32_e32 v105, v105, v118
	v_mul_f32_e32 v106, v106, v118
	v_mul_f32_e32 v107, v107, v118
	v_mul_f32_e32 v98, v110, v98
	v_mul_f32_e32 v99, v111, v99
	v_mul_f32_e32 v98, v102, v98
	v_mul_f32_e32 v99, v103, v99
	v_cvt_pk_bf16_f32 v98, v98, v99
	v_mul_f32_e32 v99, 0xbfb8aa3b, v112
	v_mul_f32_e32 v102, 0xbfb8aa3b, v113
	v_exp_f32_e32 v99, v99
	v_exp_f32_e32 v102, v102
	v_mul_f32_e32 v108, v108, v118
	v_mul_f32_e32 v109, v109, v118
	v_add_f32_e32 v99, 1.0, v99
	v_add_f32_e32 v102, 1.0, v102
	v_rcp_f32_e32 v99, v99
	v_rcp_f32_e32 v102, v102
	v_mul_f32_e32 v99, v112, v99
	v_mul_f32_e32 v102, v113, v102
	v_mul_f32_e32 v99, v104, v99
	v_mul_f32_e32 v102, v105, v102
	v_cvt_pk_bf16_f32 v99, v99, v102
	v_mul_f32_e32 v102, 0xbfb8aa3b, v106
	v_exp_f32_e32 v102, v102
	s_nop 0
	v_add_f32_e32 v102, 1.0, v102
	v_rcp_f32_e32 v102, v102
	s_nop 0
	v_mul_f32_e32 v102, v106, v102
	v_mul_f32_e32 v100, v100, v102
	v_mul_f32_e32 v102, 0xbfb8aa3b, v107
	v_exp_f32_e32 v102, v102
	s_nop 0
	v_add_f32_e32 v102, 1.0, v102
	v_rcp_f32_e32 v102, v102
	s_nop 0
	v_mul_f32_e32 v102, v107, v102
	v_mul_f32_e32 v101, v101, v102
	v_cvt_pk_bf16_f32 v100, v100, v101
	v_mul_f32_e32 v101, 0xbfb8aa3b, v108
	v_mul_f32_e32 v102, 0xbfb8aa3b, v109
	v_exp_f32_e32 v101, v101
	v_exp_f32_e32 v102, v102
	v_add_f32_e32 v101, 1.0, v101
	v_add_f32_e32 v102, 1.0, v102
	v_rcp_f32_e32 v101, v101
	v_rcp_f32_e32 v102, v102
	v_mul_f32_e32 v101, v108, v101
	v_mul_f32_e32 v102, v109, v102
	v_mul_f32_e32 v101, v120, v101
	v_mul_f32_e32 v102, v121, v102
	v_cvt_pk_bf16_f32 v101, v101, v102
	v_mad_i64_i32 v[102:103], s[16:17], v119, s18, v[114:115]
	v_lshl_add_u64 v[102:103], v[102:103], 0, v[116:117]
	global_store_dwordx4 v[102:103], v[98:101], off
	s_nop 1
	v_mul_f32_e32 v98, v84, v140
	v_mul_f32_e32 v99, v85, v140
	v_mul_f32_e32 v84, v82, v140
	v_mul_f32_e32 v85, v83, v140
	v_mul_f32_e32 v82, 0xbfb8aa3b, v94
	v_mul_f32_e32 v83, 0xbfb8aa3b, v95
	v_exp_f32_e32 v82, v82
	v_exp_f32_e32 v83, v83
	v_or_b32_e32 v100, 32, v154
	v_add_f32_e32 v82, 1.0, v82
	v_add_f32_e32 v83, 1.0, v83
	v_rcp_f32_e32 v82, v82
	v_rcp_f32_e32 v83, v83
	v_mul_f32_e32 v82, v94, v82
	v_mul_f32_e32 v83, v95, v83
	v_mul_f32_e32 v82, v86, v82
	v_mul_f32_e32 v83, v87, v83
	v_cvt_pk_bf16_f32 v82, v82, v83
	v_mul_f32_e32 v83, 0xbfb8aa3b, v96
	v_mul_f32_e32 v86, 0xbfb8aa3b, v97
	v_exp_f32_e32 v83, v83
	v_exp_f32_e32 v86, v86
	v_add_f32_e32 v83, 1.0, v83
	v_add_f32_e32 v86, 1.0, v86
	v_rcp_f32_e32 v83, v83
	v_rcp_f32_e32 v86, v86
	v_mul_f32_e32 v83, v96, v83
	v_mul_f32_e32 v86, v97, v86
	v_mul_f32_e32 v83, v88, v83
	v_mul_f32_e32 v86, v89, v86
	v_cvt_pk_bf16_f32 v83, v83, v86
	v_mul_f32_e32 v86, 0xbfb8aa3b, v90
	v_exp_f32_e32 v86, v86
	s_nop 0
	v_add_f32_e32 v86, 1.0, v86
	v_rcp_f32_e32 v86, v86
	s_nop 0
	v_mul_f32_e32 v86, v90, v86
	v_mul_f32_e32 v84, v84, v86
	v_mul_f32_e32 v86, 0xbfb8aa3b, v91
	v_exp_f32_e32 v86, v86
	s_nop 0
	v_add_f32_e32 v86, 1.0, v86
	v_rcp_f32_e32 v86, v86
	s_nop 0
	v_mul_f32_e32 v86, v91, v86
	v_mul_f32_e32 v85, v85, v86
	v_cvt_pk_bf16_f32 v84, v84, v85
	v_mul_f32_e32 v85, 0xbfb8aa3b, v92
	v_mul_f32_e32 v86, 0xbfb8aa3b, v93
	v_exp_f32_e32 v85, v85
	v_exp_f32_e32 v86, v86
	v_add_f32_e32 v85, 1.0, v85
	v_add_f32_e32 v86, 1.0, v86
	v_rcp_f32_e32 v85, v85
	v_rcp_f32_e32 v86, v86
	v_mul_f32_e32 v85, v92, v85
	v_mul_f32_e32 v86, v93, v86
	v_mul_f32_e32 v85, v98, v85
	v_mul_f32_e32 v86, v99, v86
	v_cvt_pk_bf16_f32 v85, v85, v86
	v_mad_i64_i32 v[86:87], s[16:17], v100, s18, v[114:115]
	v_lshl_add_u64 v[86:87], v[86:87], 0, v[116:117]
	global_store_dwordx4 v[86:87], v[82:85], off
	s_nop 1
	v_or_b32_e32 v83, 48, v154
	v_mov_b32_e32 v82, v141
	v_mul_f32_e32 v78, v78, v82
	v_mul_f32_e32 v79, v79, v82
	v_mul_f32_e32 v84, v68, v82
	v_mul_f32_e32 v85, v69, v82
	v_mul_f32_e32 v68, v66, v82
	v_mul_f32_e32 v69, v67, v82
	v_mul_f32_e32 v66, 0xbfb8aa3b, v78
	v_mul_f32_e32 v67, 0xbfb8aa3b, v79
	v_exp_f32_e32 v66, v66
	v_exp_f32_e32 v67, v67
	v_mul_f32_e32 v70, v70, v82
	v_mul_f32_e32 v71, v71, v82
	v_mul_f32_e32 v80, v80, v82
	v_mul_f32_e32 v81, v81, v82
	v_add_f32_e32 v66, 1.0, v66
	v_add_f32_e32 v67, 1.0, v67
	v_rcp_f32_e32 v66, v66
	v_rcp_f32_e32 v67, v67
	v_mul_f32_e32 v72, v72, v82
	v_mul_f32_e32 v73, v73, v82
	v_mul_f32_e32 v74, v74, v82
	v_mul_f32_e32 v75, v75, v82
	v_mul_f32_e32 v66, v78, v66
	v_mul_f32_e32 v67, v79, v67
	v_mul_f32_e32 v66, v70, v66
	v_mul_f32_e32 v67, v71, v67
	v_cvt_pk_bf16_f32 v66, v66, v67
	v_mul_f32_e32 v67, 0xbfb8aa3b, v80
	v_mul_f32_e32 v70, 0xbfb8aa3b, v81
	v_exp_f32_e32 v67, v67
	v_exp_f32_e32 v70, v70
	v_mul_f32_e32 v76, v76, v82
	v_mul_f32_e32 v77, v77, v82
	v_add_f32_e32 v67, 1.0, v67
	v_add_f32_e32 v70, 1.0, v70
	v_rcp_f32_e32 v67, v67
	v_rcp_f32_e32 v70, v70
	v_mul_f32_e32 v67, v80, v67
	v_mul_f32_e32 v70, v81, v70
	v_mul_f32_e32 v67, v72, v67
	v_mul_f32_e32 v70, v73, v70
	v_cvt_pk_bf16_f32 v67, v67, v70
	v_mul_f32_e32 v70, 0xbfb8aa3b, v74
	v_exp_f32_e32 v70, v70
	s_nop 0
	v_add_f32_e32 v70, 1.0, v70
	v_rcp_f32_e32 v70, v70
	s_nop 0
	v_mul_f32_e32 v70, v74, v70
	v_mul_f32_e32 v68, v68, v70
	v_mul_f32_e32 v70, 0xbfb8aa3b, v75
	v_exp_f32_e32 v70, v70
	s_nop 0
	v_add_f32_e32 v70, 1.0, v70
	v_rcp_f32_e32 v70, v70
	s_nop 0
	v_mul_f32_e32 v70, v75, v70
	v_mul_f32_e32 v69, v69, v70
	v_cvt_pk_bf16_f32 v68, v68, v69
	v_mul_f32_e32 v69, 0xbfb8aa3b, v76
	v_mul_f32_e32 v70, 0xbfb8aa3b, v77
	v_exp_f32_e32 v69, v69
	v_exp_f32_e32 v70, v70
	v_add_f32_e32 v69, 1.0, v69
	v_add_f32_e32 v70, 1.0, v70
	v_rcp_f32_e32 v69, v69
	v_rcp_f32_e32 v70, v70
	v_mul_f32_e32 v69, v76, v69
	v_mul_f32_e32 v70, v77, v70
	v_mul_f32_e32 v69, v84, v69
	v_mul_f32_e32 v70, v85, v70
	v_cvt_pk_bf16_f32 v69, v69, v70
	v_mad_i64_i32 v[70:71], s[16:17], v83, s18, v[114:115]
	v_lshl_add_u64 v[70:71], v[70:71], 0, v[116:117]
	global_store_dwordx4 v[70:71], v[66:69], off
	s_nop 1
	v_mul_f32_e32 v66, v52, v138
	v_mul_f32_e32 v67, v53, v138
	v_mul_f32_e32 v52, v50, v138
	v_mul_f32_e32 v53, v51, v138
	v_mul_f32_e32 v50, 0xbfb8aa3b, v62
	v_mul_f32_e32 v51, 0xbfb8aa3b, v63
	v_exp_f32_e32 v50, v50
	v_exp_f32_e32 v51, v51
	v_add_u32_e32 v68, 0x80, v154
	v_add_f32_e32 v50, 1.0, v50
	v_add_f32_e32 v51, 1.0, v51
	v_rcp_f32_e32 v50, v50
	v_rcp_f32_e32 v51, v51
	v_mul_f32_e32 v50, v62, v50
	v_mul_f32_e32 v51, v63, v51
	v_mul_f32_e32 v50, v54, v50
	v_mul_f32_e32 v51, v55, v51
	v_cvt_pk_bf16_f32 v50, v50, v51
	v_mul_f32_e32 v51, 0xbfb8aa3b, v64
	v_mul_f32_e32 v54, 0xbfb8aa3b, v65
	v_exp_f32_e32 v51, v51
	v_exp_f32_e32 v54, v54
	v_add_f32_e32 v51, 1.0, v51
	v_add_f32_e32 v54, 1.0, v54
	v_rcp_f32_e32 v51, v51
	v_rcp_f32_e32 v54, v54
	v_mul_f32_e32 v51, v64, v51
	v_mul_f32_e32 v54, v65, v54
	v_mul_f32_e32 v51, v56, v51
	v_mul_f32_e32 v54, v57, v54
	v_cvt_pk_bf16_f32 v51, v51, v54
	v_mul_f32_e32 v54, 0xbfb8aa3b, v58
	v_exp_f32_e32 v54, v54
	s_nop 0
	v_add_f32_e32 v54, 1.0, v54
	v_rcp_f32_e32 v54, v54
	s_nop 0
	v_mul_f32_e32 v54, v58, v54
	v_mul_f32_e32 v52, v52, v54
	v_mul_f32_e32 v54, 0xbfb8aa3b, v59
	v_exp_f32_e32 v54, v54
	s_nop 0
	v_add_f32_e32 v54, 1.0, v54
	v_rcp_f32_e32 v54, v54
	s_nop 0
	v_mul_f32_e32 v54, v59, v54
	v_mul_f32_e32 v53, v53, v54
	v_cvt_pk_bf16_f32 v52, v52, v53
	v_mul_f32_e32 v53, 0xbfb8aa3b, v60
	v_mul_f32_e32 v54, 0xbfb8aa3b, v61
	v_exp_f32_e32 v53, v53
	v_exp_f32_e32 v54, v54
	v_add_f32_e32 v53, 1.0, v53
	v_add_f32_e32 v54, 1.0, v54
	v_rcp_f32_e32 v53, v53
	v_rcp_f32_e32 v54, v54
	v_mul_f32_e32 v53, v60, v53
	v_mul_f32_e32 v54, v61, v54
	v_mul_f32_e32 v53, v66, v53
	v_mul_f32_e32 v54, v67, v54
	v_cvt_pk_bf16_f32 v53, v53, v54
	v_mad_i64_i32 v[54:55], s[16:17], v68, s18, v[114:115]
	v_lshl_add_u64 v[54:55], v[54:55], 0, v[116:117]
	global_store_dwordx4 v[54:55], v[50:53], off
	s_nop 1
	v_add_u32_e32 v51, 0x90, v154
	v_mov_b32_e32 v50, v139
	v_mul_f32_e32 v46, v46, v50
	v_mul_f32_e32 v47, v47, v50
	v_mul_f32_e32 v52, v36, v50
	v_mul_f32_e32 v53, v37, v50
	v_mul_f32_e32 v36, v34, v50
	v_mul_f32_e32 v37, v35, v50
	v_mul_f32_e32 v34, 0xbfb8aa3b, v46
	v_mul_f32_e32 v35, 0xbfb8aa3b, v47
	v_exp_f32_e32 v34, v34
	v_exp_f32_e32 v35, v35
	v_mul_f32_e32 v38, v38, v50
	v_mul_f32_e32 v39, v39, v50
	v_mul_f32_e32 v48, v48, v50
	v_mul_f32_e32 v49, v49, v50
	v_add_f32_e32 v34, 1.0, v34
	v_add_f32_e32 v35, 1.0, v35
	v_rcp_f32_e32 v34, v34
	v_rcp_f32_e32 v35, v35
	v_mul_f32_e32 v40, v40, v50
	v_mul_f32_e32 v41, v41, v50
	v_mul_f32_e32 v42, v42, v50
	v_mul_f32_e32 v43, v43, v50
	v_mul_f32_e32 v34, v46, v34
	v_mul_f32_e32 v35, v47, v35
	v_mul_f32_e32 v34, v38, v34
	v_mul_f32_e32 v35, v39, v35
	v_cvt_pk_bf16_f32 v34, v34, v35
	v_mul_f32_e32 v35, 0xbfb8aa3b, v48
	v_mul_f32_e32 v38, 0xbfb8aa3b, v49
	v_exp_f32_e32 v35, v35
	v_exp_f32_e32 v38, v38
	v_mul_f32_e32 v44, v44, v50
	v_mul_f32_e32 v45, v45, v50
	v_add_f32_e32 v35, 1.0, v35
	v_add_f32_e32 v38, 1.0, v38
	v_rcp_f32_e32 v35, v35
	v_rcp_f32_e32 v38, v38
	v_mul_f32_e32 v35, v48, v35
	v_mul_f32_e32 v38, v49, v38
	v_mul_f32_e32 v35, v40, v35
	v_mul_f32_e32 v38, v41, v38
	v_cvt_pk_bf16_f32 v35, v35, v38
	v_mul_f32_e32 v38, 0xbfb8aa3b, v42
	v_exp_f32_e32 v38, v38
	s_nop 0
	v_add_f32_e32 v38, 1.0, v38
	v_rcp_f32_e32 v38, v38
	s_nop 0
	v_mul_f32_e32 v38, v42, v38
	v_mul_f32_e32 v36, v36, v38
	v_mul_f32_e32 v38, 0xbfb8aa3b, v43
	v_exp_f32_e32 v38, v38
	s_nop 0
	v_add_f32_e32 v38, 1.0, v38
	v_rcp_f32_e32 v38, v38
	s_nop 0
	v_mul_f32_e32 v38, v43, v38
	v_mul_f32_e32 v37, v37, v38
	v_cvt_pk_bf16_f32 v36, v36, v37
	v_mul_f32_e32 v37, 0xbfb8aa3b, v44
	v_mul_f32_e32 v38, 0xbfb8aa3b, v45
	v_exp_f32_e32 v37, v37
	v_exp_f32_e32 v38, v38
	v_add_f32_e32 v37, 1.0, v37
	v_add_f32_e32 v38, 1.0, v38
	v_rcp_f32_e32 v37, v37
	v_rcp_f32_e32 v38, v38
	v_mul_f32_e32 v37, v44, v37
	v_mul_f32_e32 v38, v45, v38
	v_mul_f32_e32 v37, v52, v37
	v_mul_f32_e32 v38, v53, v38
	v_cvt_pk_bf16_f32 v37, v37, v38
	v_mad_i64_i32 v[38:39], s[16:17], v51, s18, v[114:115]
	v_lshl_add_u64 v[38:39], v[38:39], 0, v[116:117]
	global_store_dwordx4 v[38:39], v[34:37], off
	s_nop 1
	v_mul_f32_e32 v34, v20, v136
	v_mul_f32_e32 v35, v21, v136
	v_mul_f32_e32 v20, v18, v136
	v_mul_f32_e32 v21, v19, v136
	v_mul_f32_e32 v18, 0xbfb8aa3b, v30
	v_mul_f32_e32 v19, 0xbfb8aa3b, v31
	v_exp_f32_e32 v18, v18
	v_exp_f32_e32 v19, v19
	v_add_u32_e32 v36, 0xa0, v154
	v_add_f32_e32 v18, 1.0, v18
	v_add_f32_e32 v19, 1.0, v19
	v_rcp_f32_e32 v18, v18
	v_rcp_f32_e32 v19, v19
	v_mul_f32_e32 v18, v30, v18
	v_mul_f32_e32 v19, v31, v19
	v_mul_f32_e32 v18, v22, v18
	v_mul_f32_e32 v19, v23, v19
	v_cvt_pk_bf16_f32 v18, v18, v19
	v_mul_f32_e32 v19, 0xbfb8aa3b, v32
	v_mul_f32_e32 v22, 0xbfb8aa3b, v33
	v_exp_f32_e32 v19, v19
	v_exp_f32_e32 v22, v22
	v_add_f32_e32 v19, 1.0, v19
	v_add_f32_e32 v22, 1.0, v22
	v_rcp_f32_e32 v19, v19
	v_rcp_f32_e32 v22, v22
	v_mul_f32_e32 v19, v32, v19
	v_mul_f32_e32 v22, v33, v22
	v_mul_f32_e32 v19, v24, v19
	v_mul_f32_e32 v22, v25, v22
	v_cvt_pk_bf16_f32 v19, v19, v22
	v_mul_f32_e32 v22, 0xbfb8aa3b, v26
	v_exp_f32_e32 v22, v22
	s_nop 0
	v_add_f32_e32 v22, 1.0, v22
	v_rcp_f32_e32 v22, v22
	s_nop 0
	v_mul_f32_e32 v22, v26, v22
	v_mul_f32_e32 v20, v20, v22
	v_mul_f32_e32 v22, 0xbfb8aa3b, v27
	v_exp_f32_e32 v22, v22
	s_nop 0
	v_add_f32_e32 v22, 1.0, v22
	v_rcp_f32_e32 v22, v22
	s_nop 0
	v_mul_f32_e32 v22, v27, v22
	v_mul_f32_e32 v21, v21, v22
	v_cvt_pk_bf16_f32 v20, v20, v21
	v_mul_f32_e32 v21, 0xbfb8aa3b, v28
	v_mul_f32_e32 v22, 0xbfb8aa3b, v29
	v_exp_f32_e32 v21, v21
	v_exp_f32_e32 v22, v22
	v_add_f32_e32 v21, 1.0, v21
	v_add_f32_e32 v22, 1.0, v22
	v_rcp_f32_e32 v21, v21
	v_rcp_f32_e32 v22, v22
	v_mul_f32_e32 v21, v28, v21
	v_mul_f32_e32 v22, v29, v22
	v_mul_f32_e32 v21, v34, v21
	v_mul_f32_e32 v22, v35, v22
	v_cvt_pk_bf16_f32 v21, v21, v22
	v_mad_i64_i32 v[22:23], s[16:17], v36, s18, v[114:115]
	v_lshl_add_u64 v[22:23], v[22:23], 0, v[116:117]
	global_store_dwordx4 v[22:23], v[18:21], off
	s_nop 1
	v_add_u32_e32 v19, 0xb0, v154
	v_mov_b32_e32 v18, v137
	v_mul_f32_e32 v14, v14, v18
	v_mul_f32_e32 v15, v15, v18
	v_mul_f32_e32 v20, v4, v18
	v_mul_f32_e32 v21, v5, v18
	v_mul_f32_e32 v4, v2, v18
	v_mul_f32_e32 v5, v3, v18
	v_mul_f32_e32 v2, 0xbfb8aa3b, v14
	v_mul_f32_e32 v3, 0xbfb8aa3b, v15
	v_exp_f32_e32 v2, v2
	v_exp_f32_e32 v3, v3
	v_mul_f32_e32 v6, v6, v18
	v_mul_f32_e32 v7, v7, v18
	v_mul_f32_e32 v16, v16, v18
	v_mul_f32_e32 v17, v17, v18
	v_add_f32_e32 v2, 1.0, v2
	v_add_f32_e32 v3, 1.0, v3
	v_rcp_f32_e32 v2, v2
	v_rcp_f32_e32 v3, v3
	v_mul_f32_e32 v8, v8, v18
	v_mul_f32_e32 v9, v9, v18
	v_mul_f32_e32 v10, v10, v18
	v_mul_f32_e32 v11, v11, v18
	v_mul_f32_e32 v2, v14, v2
	v_mul_f32_e32 v3, v15, v3
	v_mul_f32_e32 v2, v6, v2
	v_mul_f32_e32 v3, v7, v3
	v_cvt_pk_bf16_f32 v2, v2, v3
	v_mul_f32_e32 v3, 0xbfb8aa3b, v16
	v_mul_f32_e32 v6, 0xbfb8aa3b, v17
	v_exp_f32_e32 v3, v3
	v_exp_f32_e32 v6, v6
	v_mul_f32_e32 v12, v12, v18
	v_mul_f32_e32 v13, v13, v18
	v_add_f32_e32 v3, 1.0, v3
	v_add_f32_e32 v6, 1.0, v6
	v_rcp_f32_e32 v3, v3
	v_rcp_f32_e32 v6, v6
	v_mul_f32_e32 v3, v16, v3
	v_mul_f32_e32 v6, v17, v6
	v_mul_f32_e32 v3, v8, v3
	v_mul_f32_e32 v6, v9, v6
	v_cvt_pk_bf16_f32 v3, v3, v6
	v_mul_f32_e32 v6, 0xbfb8aa3b, v10
	v_exp_f32_e32 v6, v6
	s_nop 0
	v_add_f32_e32 v6, 1.0, v6
	v_rcp_f32_e32 v6, v6
	s_nop 0
	v_mul_f32_e32 v6, v10, v6
	v_mul_f32_e32 v4, v4, v6
	v_mul_f32_e32 v6, 0xbfb8aa3b, v11
	v_exp_f32_e32 v6, v6
	s_nop 0
	v_add_f32_e32 v6, 1.0, v6
	v_rcp_f32_e32 v6, v6
	s_nop 0
	v_mul_f32_e32 v6, v11, v6
	v_mul_f32_e32 v5, v5, v6
	v_cvt_pk_bf16_f32 v4, v4, v5
	v_mul_f32_e32 v5, 0xbfb8aa3b, v12
	v_mul_f32_e32 v6, 0xbfb8aa3b, v13
	v_exp_f32_e32 v5, v5
	v_exp_f32_e32 v6, v6
	v_add_f32_e32 v5, 1.0, v5
	v_add_f32_e32 v6, 1.0, v6
	v_rcp_f32_e32 v5, v5
	v_rcp_f32_e32 v6, v6
	v_mul_f32_e32 v5, v12, v5
	v_mul_f32_e32 v6, v13, v6
	v_mul_f32_e32 v5, v20, v5
	v_mul_f32_e32 v6, v21, v6
	v_cvt_pk_bf16_f32 v5, v5, v6
	v_mad_i64_i32 v[6:7], s[16:17], v19, s18, v[114:115]
	v_lshl_add_u64 v[6:7], v[6:7], 0, v[116:117]
	global_store_dwordx4 v[6:7], v[2:5], off
	s_andn2_b64 vcc, exec, s[10:11]
	s_mov_b64 s[10:11], -1
	s_cbranch_vccnz .LBB0_684
	s_and_saveexec_b64 s[10:11], s[40:41]
	s_lshl_b32 s16, s33, 8
	s_xor_b32 s16, s16, 0x100
	v_lshl_add_u32 v2, s16, 2, v149
	ds_write_b32 v2, v153
	s_or_b64 exec, exec, s[10:11]
	s_andn2_b64 vcc, exec, s[4:5]
	s_cbranch_vccnz .LBB0_683
	s_barrier
	s_branch .LBB0_683

.LBB0_703:
	s_or_b64 exec, exec, s[4:5]
	v_lshl_add_u32 v0, v64, 4, 0
	s_waitcnt lgkmcnt(0)
	v_lshl_add_u32 v2, v63, 12, v0
	v_lshl_add_u32 v3, v58, 10, v0
	v_lshl_add_u32 v0, v60, 10, v0
	ds_write_b128 v2, v[26:29]
	ds_write_b128 v3, v[30:33]
	ds_write_b128 v0, v[34:37]
	ds_write_b128 v2, v[38:41] offset:3072
	v_ashrrev_i32_e32 v0, 8, v62
	v_and_b32_e32 v20, 3, v62
	v_lshlrev_b32_e32 v2, 2, v62
	v_lshl_add_u32 v4, v20, 2, 0
	v_and_b32_e32 v5, 0x3f0, v2
	v_lshlrev_b32_e32 v6, 10, v0
	v_add3_u32 v14, v4, v6, v5
	s_waitcnt lgkmcnt(0)
	s_barrier
	ds_read2st64_b32 v[2:3], v14 offset1:16
	v_add3_u32 v16, v4, v5, v6
	v_bfe_u32 v18, v62, 2, 4
	ds_read2st64_b32 v[4:5], v16 offset0:8 offset1:24
	ds_read2st64_b32 v[6:7], v14 offset0:32 offset1:48
	ds_read2st64_b32 v[8:9], v16 offset0:40 offset1:56
	ds_read2st64_b32 v[10:11], v14 offset0:64 offset1:80
	ds_read2st64_b32 v[12:13], v16 offset0:72 offset1:88
	ds_read2st64_b32 v[14:15], v14 offset0:96 offset1:112
	ds_read2st64_b32 v[16:17], v16 offset0:104 offset1:120
	v_lshl_or_b32 v21, v0, 4, v18
	s_waitcnt lgkmcnt(6)
	v_mov_b32_e32 v18, v4
	v_mov_b32_e32 v19, v2
	v_add_f32_e32 v18, 0, v18
	v_add_f32_e32 v19, 0, v19
	v_mov_b32_e32 v2, v5
	v_add_f32_e32 v2, v18, v2
	v_add_f32_e32 v3, v19, v3
	s_waitcnt lgkmcnt(4)
	v_mov_b32_e32 v4, v8
	v_mov_b32_e32 v5, v6
	v_lshl_add_u32 v0, v21, 2, 0
	v_add_f32_e32 v2, v2, v4
	v_add_f32_e32 v3, v3, v5
	v_mov_b32_e32 v6, v9
	ds_read_b32 v0, v0 offset:32768
	v_add_f32_e32 v2, v2, v6
	v_add_f32_e32 v3, v3, v7
	s_waitcnt lgkmcnt(3)
	v_mov_b32_e32 v4, v12
	v_mov_b32_e32 v5, v10
	v_add_f32_e32 v2, v2, v4
	v_add_f32_e32 v3, v3, v5
	v_mov_b32_e32 v10, v13
	v_add_f32_e32 v2, v2, v10
	v_add_f32_e32 v3, v3, v11
	s_waitcnt lgkmcnt(1)
	v_mov_b32_e32 v4, v16
	v_mov_b32_e32 v5, v14
	v_add_f32_e32 v2, v2, v4
	v_add_f32_e32 v3, v3, v5
	v_mov_b32_e32 v14, v17
	v_add_f32_e32 v2, v2, v14
	v_add_f32_e32 v3, v3, v15
	s_lshr_b32 s5, s10, 2
	s_waitcnt lgkmcnt(0)
	v_mul_f32_e32 v2, v2, v0
	v_mul_f32_e32 v3, v3, v0
	s_and_b32 s4, s10, 0xffffffe0
	v_mul_f32_e32 v0, 0xbfb8aa3b, v3
	v_exp_f32_e32 v0, v0
	v_lshrrev_b32_e32 v4, 3, v62
	s_and_b32 s5, s5, 4
	v_and_b32_e32 v4, 24, v4
	v_add_f32_e32 v0, 1.0, v0
	v_rcp_f32_e32 v0, v0
	s_or_b32 s4, s5, s4
	v_or3_b32 v4, s4, v4, v20
	v_readlane_b32 s4, v254, 1
	v_mul_f32_e32 v0, v3, v0
	v_readlane_b32 s5, v254, 2
	v_mul_f32_e32 v0, v2, v0
	v_add_u32_e32 v6, 0x8000, v21
	v_mov_b64_e32 v[2:3], s[4:5]
	s_movk_i32 s4, 0x1600
	v_mad_i64_i32 v[2:3], s[4:5], v6, s4, v[2:3]
	v_readlane_b32 s4, v251, 1
	v_readlane_b32 s5, v251, 2
	s_add_i32 s11, s11, s4
	v_readlane_b32 s4, v253, 9
	s_add_i32 s10, s10, s4
	v_readlane_b32 s4, v253, 20
	v_ashrrev_i32_e32 v5, 31, v4
	s_add_i32 s2, s2, s4
	v_lshl_add_u64 v[2:3], v[4:5], 1, v[2:3]
	s_cmpk_gt_i32 s11, 0xaf
	v_cvt_pk_bf16_f32 v0, v0, v1
	v_readlane_b32 s5, v253, 21
	global_store_short v[2:3], v0, off
	s_cbranch_scc1 .LBB0_700

.LBB0_712:
	s_and_b64 s[4:5], s[14:15], exec
	s_cselect_b32 s10, 0x80, 0
	s_lshl_b32 s2, s2, 7
	s_and_b32 s2, s2, 0xffffff00
	s_and_b32 s11, s16, 64
	s_and_b64 s[4:5], s[6:7], exec
	s_cselect_b32 s4, 0x1780000, 0
	s_movk_i32 s6, 0x104
	s_add_u32 s4, s8, s4
	v_mad_u64_u32 v[6:7], s[6:7], v54, s6, v[0:1]
	s_waitcnt vmcnt(0)
	v_mul_f32_e32 v2, v2, v10
	v_mul_f32_e32 v3, v3, v10
	s_addc_u32 s5, s9, 0
	ds_write2_b32 v6, v2, v3 offset1:1
	v_mul_f32_e32 v2, v4, v10
	v_mul_f32_e32 v3, v5, v10
	s_or_b32 s6, s11, s10
	ds_write2_b32 v6, v2, v3 offset0:2 offset1:3
	v_lshrrev_b32_e32 v0, 2, v50
	v_lshrrev_b32_e32 v2, 3, v50
	v_and_b32_e32 v3, 0xfc, v50
	s_or_b32 s2, s6, s2
	v_and_b32_e32 v2, 12, v2
	v_add_u32_e32 v8, 0, v3
	v_and_b32_e32 v0, 35, v0
	v_and_or_b32 v3, v50, 16, s2
	v_or3_b32 v2, v3, v2, v0
	v_ashrrev_i32_e32 v3, 31, v2
	v_lshlrev_b64 v[2:3], 11, v[2:3]
	v_ashrrev_i32_e32 v0, 6, v50
	v_lshl_add_u64 v[2:3], s[4:5], 0, v[2:3]
	s_ashr_i32 s13, s12, 31
	v_bfi_b32 v0, -4, v0, v50
	s_movk_i32 s2, 0x820
	v_lshl_add_u64 v[6:7], s[12:13], 1, v[2:3]
	v_mad_u64_u32 v[2:3], s[4:5], v0, s2, v[8:9]
	s_waitcnt lgkmcnt(0)
	s_barrier
	ds_read2_b32 v[4:5], v2 offset1:65
	ds_read2_b32 v[10:11], v2 offset0:130 offset1:195
	v_add_u32_e32 v2, 0x400, v2
	ds_read2_b32 v[12:13], v2 offset0:4 offset1:69
	ds_read2_b32 v[14:15], v2 offset0:134 offset1:199
	v_lshlrev_b32_e32 v16, 3, v0
	v_ashrrev_i32_e32 v17, 31, v16
	v_ashrrev_i32_e32 v0, 6, v53
	s_waitcnt lgkmcnt(3)
	v_cvt_pk_bf16_f32 v2, v4, v5
	s_waitcnt lgkmcnt(2)
	v_cvt_pk_bf16_f32 v3, v10, v11
	v_lshl_add_u64 v[10:11], v[16:17], 1, v[6:7]
	v_bfi_b32 v0, -4, v0, v50
	s_waitcnt lgkmcnt(1)
	v_cvt_pk_bf16_f32 v4, v12, v13
	s_waitcnt lgkmcnt(0)
	v_cvt_pk_bf16_f32 v5, v14, v15
	global_store_dwordx4 v[10:11], v[2:5], off
	v_lshlrev_b32_e32 v16, 3, v0
	v_ashrrev_i32_e32 v17, 31, v16
	v_mad_u64_u32 v[2:3], s[4:5], v0, s2, v[8:9]
	ds_read2_b32 v[4:5], v2 offset1:65
	ds_read2_b32 v[10:11], v2 offset0:130 offset1:195
	v_add_u32_e32 v2, 0x400, v2
	ds_read2_b32 v[12:13], v2 offset0:4 offset1:69
	ds_read2_b32 v[14:15], v2 offset0:134 offset1:199
	v_ashrrev_i32_e32 v0, 6, v52
	s_waitcnt lgkmcnt(3)
	v_cvt_pk_bf16_f32 v2, v4, v5
	s_waitcnt lgkmcnt(2)
	v_cvt_pk_bf16_f32 v3, v10, v11
	v_lshl_add_u64 v[10:11], v[16:17], 1, v[6:7]
	v_bfi_b32 v0, -4, v0, v50
	s_waitcnt lgkmcnt(1)
	v_cvt_pk_bf16_f32 v4, v12, v13
	s_waitcnt lgkmcnt(0)
	v_cvt_pk_bf16_f32 v5, v14, v15
	global_store_dwordx4 v[10:11], v[2:5], off
	v_lshlrev_b32_e32 v16, 3, v0
	v_ashrrev_i32_e32 v17, 31, v16
	v_mad_u64_u32 v[2:3], s[4:5], v0, s2, v[8:9]
	ds_read2_b32 v[4:5], v2 offset1:65
	ds_read2_b32 v[10:11], v2 offset0:130 offset1:195
	v_add_u32_e32 v2, 0x400, v2
	ds_read2_b32 v[12:13], v2 offset0:4 offset1:69
	ds_read2_b32 v[14:15], v2 offset0:134 offset1:199
	v_ashrrev_i32_e32 v0, 6, v51
	v_bfi_b32 v0, -4, v0, v50
	v_mad_u64_u32 v[8:9], s[4:5], v0, s2, v[8:9]
	s_waitcnt lgkmcnt(2)
	v_cvt_pk_bf16_f32 v3, v10, v11
	v_lshl_add_u64 v[10:11], v[16:17], 1, v[6:7]
	v_add_u32_e32 v16, 0x400, v8
	v_cvt_pk_bf16_f32 v2, v4, v5
	s_waitcnt lgkmcnt(1)
	v_cvt_pk_bf16_f32 v4, v12, v13
	s_waitcnt lgkmcnt(0)
	v_cvt_pk_bf16_f32 v5, v14, v15
	ds_read2_b32 v[12:13], v8 offset1:65
	ds_read2_b32 v[14:15], v8 offset0:130 offset1:195
	ds_read2_b32 v[8:9], v16 offset0:4 offset1:69
	ds_read2_b32 v[16:17], v16 offset0:134 offset1:199
	global_store_dwordx4 v[10:11], v[2:5], off
	s_waitcnt lgkmcnt(3)
	s_nop 0
	v_cvt_pk_bf16_f32 v2, v12, v13
	s_waitcnt lgkmcnt(2)
	v_cvt_pk_bf16_f32 v3, v14, v15
	s_waitcnt lgkmcnt(1)
	v_cvt_pk_bf16_f32 v4, v8, v9
	s_waitcnt lgkmcnt(0)
	v_cvt_pk_bf16_f32 v5, v16, v17

.Lwgk_skip_0:
	s_cmp_lg_u64 s[4:5], 0
	s_cselect_b64 s[12:13], -1, 0
	s_cmp_eq_u64 s[4:5], 0
	v_add_u32_e32 v0, 0, v0
	s_cbranch_scc1 .LBB0_747
	v_ashrrev_i32_e32 v47, 31, v46
	v_lshl_add_u64 v[46:47], v[46:47], 2, s[6:7]
	v_ashrrev_i32_e32 v49, 31, v48
	s_waitcnt vmcnt(6)
	v_mov_b32_e32 v56, v60
	v_lshl_add_u64 v[46:47], v[48:49], 2, s[6:7]
	v_mov_b32_e32 v46, v61
	s_movk_i32 s4, 0x104
	v_mad_u64_u32 v[48:49], s[4:5], v45, s4, v[0:1]
	s_waitcnt vmcnt(1)
	v_mul_f32_e32 v58, v30, v56
	v_mul_f32_e32 v59, v31, v56
	v_mul_f32_e32 v57, v33, v56
	v_mul_f32_e32 v56, v32, v56
	ds_write2_b32 v48, v58, v59 offset1:1
	ds_write2_b32 v48, v56, v57 offset0:2 offset1:3
	s_cbranch_execnz .LBB0_721

.LBB0_721:
	s_movk_i32 s16, 0x104
	s_waitcnt vmcnt(7)
	v_mad_u64_u32 v[30:31], s[4:5], v43, s16, v[0:1]
	s_waitcnt vmcnt(0)
	v_mul_f32_e32 v26, v26, v46
	v_mul_f32_e32 v27, v27, v46
	ds_write2_b32 v30, v26, v27 offset1:1
	v_mul_f32_e32 v26, v28, v46
	v_mul_f32_e32 v27, v29, v46
	v_cndmask_b32_e64 v28, 0, 1, s[12:13]
	v_cmp_ne_u32_e64 s[4:5], 1, v28
	s_andn2_b64 vcc, exec, s[12:13]
	ds_write2_b32 v30, v26, v27 offset0:2 offset1:3
	s_cbranch_vccnz .LBB0_748
	v_ashrrev_i32_e32 v45, 31, v44
	v_lshl_add_u64 v[26:27], v[44:45], 2, s[6:7]
	v_ashrrev_i32_e32 v43, 31, v42
	s_waitcnt vmcnt(4)
	v_mov_b32_e32 v28, v62
	v_lshl_add_u64 v[26:27], v[42:43], 2, s[6:7]
	v_mov_b32_e32 v26, v63
	v_mad_u64_u32 v[30:31], s[12:13], v41, s16, v[0:1]
	s_movk_i32 s17, 0x104
	s_waitcnt vmcnt(1)
	v_mul_f32_e32 v32, v22, v28
	v_mul_f32_e32 v33, v23, v28
	v_mul_f32_e32 v29, v25, v28
	v_mul_f32_e32 v28, v24, v28
	ds_write2_b32 v30, v32, v33 offset1:1
	ds_write2_b32 v30, v28, v29 offset0:2 offset1:3
	s_cbranch_execnz .LBB0_724

.LBB0_724:
	v_mad_u64_u32 v[22:23], s[12:13], v39, s16, v[0:1]
	s_waitcnt vmcnt(0)
	v_mul_f32_e32 v18, v18, v26
	v_mul_f32_e32 v19, v19, v26
	ds_write2_b32 v22, v18, v19 offset1:1
	v_mul_f32_e32 v18, v20, v26
	v_mul_f32_e32 v19, v21, v26
	s_and_b64 vcc, exec, s[4:5]
	ds_write2_b32 v22, v18, v19 offset0:2 offset1:3
	s_cbranch_vccnz .LBB0_749
	v_ashrrev_i32_e32 v41, 31, v40
	v_lshl_add_u64 v[18:19], v[40:41], 2, s[6:7]
	v_ashrrev_i32_e32 v39, 31, v38
	s_waitcnt vmcnt(2)
	v_mov_b32_e32 v20, v64
	v_lshl_add_u64 v[18:19], v[38:39], 2, s[6:7]
	v_mov_b32_e32 v18, v65
	v_mad_u64_u32 v[22:23], s[12:13], v37, s16, v[0:1]
	s_waitcnt vmcnt(1)
	v_mul_f32_e32 v24, v14, v20
	v_mul_f32_e32 v25, v15, v20
	v_mul_f32_e32 v21, v17, v20
	v_mul_f32_e32 v20, v16, v20
	ds_write2_b32 v22, v24, v25 offset1:1
	ds_write2_b32 v22, v20, v21 offset0:2 offset1:3
	s_cbranch_execnz .LBB0_727

.LBB0_727:
	v_mad_u64_u32 v[14:15], s[12:13], v35, s16, v[0:1]
	s_waitcnt vmcnt(0)
	v_mul_f32_e32 v10, v10, v18
	v_mul_f32_e32 v11, v11, v18
	ds_write2_b32 v14, v10, v11 offset1:1
	v_mul_f32_e32 v10, v12, v18
	v_mul_f32_e32 v11, v13, v18
	s_and_b64 vcc, exec, s[4:5]
	ds_write2_b32 v14, v10, v11 offset0:2 offset1:3
	s_cbranch_vccnz .LBB0_750
	v_ashrrev_i32_e32 v37, 31, v36
	v_lshl_add_u64 v[10:11], v[36:37], 2, s[6:7]
	v_ashrrev_i32_e32 v35, 31, v34
	s_waitcnt vmcnt(0)
	v_mov_b32_e32 v12, v66
	v_lshl_add_u64 v[10:11], v[34:35], 2, s[6:7]
	v_mov_b32_e32 v10, v67
	v_mad_u64_u32 v[14:15], s[4:5], v55, s16, v[0:1]
	s_waitcnt vmcnt(1)
	v_mul_f32_e32 v16, v6, v12
	v_mul_f32_e32 v17, v7, v12
	v_mul_f32_e32 v13, v9, v12
	v_mul_f32_e32 v12, v8, v12
	ds_write2_b32 v14, v16, v17 offset1:1
	ds_write2_b32 v14, v12, v13 offset0:2 offset1:3
	s_cbranch_execnz .LBB0_730

.LBB0_730:
	s_movk_i32 s4, 0x104
	v_mad_u64_u32 v[6:7], s[4:5], v54, s4, v[0:1]
	s_waitcnt vmcnt(0)
	v_mul_f32_e32 v2, v2, v10
	v_mul_f32_e32 v3, v3, v10
	ds_write2_b32 v6, v2, v3 offset1:1
	v_mul_f32_e32 v2, v4, v10
	v_mul_f32_e32 v3, v5, v10
	ds_write2_b32 v6, v2, v3 offset0:2 offset1:3
	v_lshrrev_b32_e32 v2, 3, v50
	v_lshrrev_b32_e32 v0, 2, v50
	v_and_b32_e32 v2, 12, v2
	s_lshl_b32 s6, s11, 6
	v_and_b32_e32 v0, 35, v0
	v_and_or_b32 v2, v50, 16, v2
	v_or3_b32 v0, v2, v0, s6
	v_and_b32_e32 v3, 0xfc, v50
	v_lshlrev_b32_e32 v0, 11, v0
	v_add_u32_e32 v8, 0, v3
	v_lshl_add_u64 v[2:3], s[8:9], 0, v[0:1]
	s_lshl_b32 s2, s2, 1
	v_ashrrev_i32_e32 v0, 6, v50
	v_lshl_add_u64 v[2:3], v[2:3], 0, s[2:3]
	s_mov_b64 s[4:5], 0x1080000
	v_bfi_b32 v0, -4, v0, v50
	s_movk_i32 s2, 0x820
	v_lshl_add_u64 v[6:7], v[2:3], 0, s[4:5]
	v_mad_u64_u32 v[2:3], s[4:5], v0, s2, v[8:9]
	s_waitcnt lgkmcnt(0)
	s_barrier
	ds_read2_b32 v[4:5], v2 offset1:65
	ds_read2_b32 v[10:11], v2 offset0:130 offset1:195
	v_add_u32_e32 v2, 0x400, v2
	ds_read2_b32 v[12:13], v2 offset0:4 offset1:69
	ds_read2_b32 v[14:15], v2 offset0:134 offset1:199
	v_lshlrev_b32_e32 v16, 3, v0
	v_ashrrev_i32_e32 v17, 31, v16
	v_ashrrev_i32_e32 v0, 6, v53
	s_waitcnt lgkmcnt(3)
	v_cvt_pk_bf16_f32 v2, v4, v5
	s_waitcnt lgkmcnt(2)
	v_cvt_pk_bf16_f32 v3, v10, v11
	v_lshl_add_u64 v[10:11], v[16:17], 1, v[6:7]
	v_bfi_b32 v0, -4, v0, v50
	s_waitcnt lgkmcnt(1)
	v_cvt_pk_bf16_f32 v4, v12, v13
	s_waitcnt lgkmcnt(0)
	v_cvt_pk_bf16_f32 v5, v14, v15
	global_store_dwordx4 v[10:11], v[2:5], off
	v_lshlrev_b32_e32 v16, 3, v0
	v_ashrrev_i32_e32 v17, 31, v16
	v_mad_u64_u32 v[2:3], s[4:5], v0, s2, v[8:9]
	ds_read2_b32 v[4:5], v2 offset1:65
	ds_read2_b32 v[10:11], v2 offset0:130 offset1:195
	v_add_u32_e32 v2, 0x400, v2
	ds_read2_b32 v[12:13], v2 offset0:4 offset1:69
	ds_read2_b32 v[14:15], v2 offset0:134 offset1:199
	v_ashrrev_i32_e32 v0, 6, v52
	s_waitcnt lgkmcnt(3)
	v_cvt_pk_bf16_f32 v2, v4, v5
	s_waitcnt lgkmcnt(2)
	v_cvt_pk_bf16_f32 v3, v10, v11
	v_lshl_add_u64 v[10:11], v[16:17], 1, v[6:7]
	v_bfi_b32 v0, -4, v0, v50
	s_waitcnt lgkmcnt(1)
	v_cvt_pk_bf16_f32 v4, v12, v13
	s_waitcnt lgkmcnt(0)
	v_cvt_pk_bf16_f32 v5, v14, v15
	global_store_dwordx4 v[10:11], v[2:5], off
	v_lshlrev_b32_e32 v16, 3, v0
	v_ashrrev_i32_e32 v17, 31, v16
	v_mad_u64_u32 v[2:3], s[4:5], v0, s2, v[8:9]
	ds_read2_b32 v[4:5], v2 offset1:65
	ds_read2_b32 v[10:11], v2 offset0:130 offset1:195
	v_add_u32_e32 v2, 0x400, v2
	ds_read2_b32 v[12:13], v2 offset0:4 offset1:69
	ds_read2_b32 v[14:15], v2 offset0:134 offset1:199
	v_ashrrev_i32_e32 v0, 6, v51
	v_bfi_b32 v0, -4, v0, v50
	v_mad_u64_u32 v[8:9], s[4:5], v0, s2, v[8:9]
	s_waitcnt lgkmcnt(2)
	v_cvt_pk_bf16_f32 v3, v10, v11
	v_lshl_add_u64 v[10:11], v[16:17], 1, v[6:7]
	v_add_u32_e32 v16, 0x400, v8
	v_cvt_pk_bf16_f32 v2, v4, v5
	s_waitcnt lgkmcnt(1)
	v_cvt_pk_bf16_f32 v4, v12, v13
	s_waitcnt lgkmcnt(0)
	v_cvt_pk_bf16_f32 v5, v14, v15
	ds_read2_b32 v[12:13], v8 offset1:65
	ds_read2_b32 v[14:15], v8 offset0:130 offset1:195
	ds_read2_b32 v[8:9], v16 offset0:4 offset1:69
	ds_read2_b32 v[16:17], v16 offset0:134 offset1:199
	global_store_dwordx4 v[10:11], v[2:5], off
	s_waitcnt lgkmcnt(3)
	s_nop 0
	v_cvt_pk_bf16_f32 v2, v12, v13
	s_waitcnt lgkmcnt(2)
	v_cvt_pk_bf16_f32 v3, v14, v15
	s_waitcnt lgkmcnt(1)
	v_cvt_pk_bf16_f32 v4, v8, v9
	s_waitcnt lgkmcnt(0)
	v_cvt_pk_bf16_f32 v5, v16, v17

.Lwgk_skip_1:
	s_cmp_lg_u64 s[4:5], 0
	s_cselect_b64 s[18:19], -1, 0
	s_cmp_eq_u64 s[4:5], 0
	v_add_u32_e32 v0, 0, v0
	s_cbranch_scc1 .LBB0_751
	v_ashrrev_i32_e32 v47, 31, v46
	v_lshl_add_u64 v[46:47], v[46:47], 2, s[10:11]
	v_ashrrev_i32_e32 v49, 31, v48
	s_waitcnt vmcnt(6)
	v_mov_b32_e32 v56, v60
	v_lshl_add_u64 v[46:47], v[48:49], 2, s[10:11]
	v_mov_b32_e32 v46, v61
	s_movk_i32 s4, 0x104
	v_mad_u64_u32 v[48:49], s[4:5], v45, s4, v[0:1]
	s_waitcnt vmcnt(1)
	v_mul_f32_e32 v58, v30, v56
	v_mul_f32_e32 v59, v31, v56
	v_mul_f32_e32 v57, v33, v56
	v_mul_f32_e32 v56, v32, v56
	ds_write2_b32 v48, v58, v59 offset1:1
	ds_write2_b32 v48, v56, v57 offset0:2 offset1:3
	s_cbranch_execnz .LBB0_739

.LBB0_739:
	s_movk_i32 s13, 0x104
	s_waitcnt vmcnt(7)
	v_mad_u64_u32 v[30:31], s[4:5], v43, s13, v[0:1]
	s_waitcnt vmcnt(0)
	v_mul_f32_e32 v26, v26, v46
	v_mul_f32_e32 v27, v27, v46
	ds_write2_b32 v30, v26, v27 offset1:1
	v_mul_f32_e32 v26, v28, v46
	v_mul_f32_e32 v27, v29, v46
	v_cndmask_b32_e64 v28, 0, 1, s[18:19]
	v_cmp_ne_u32_e64 s[4:5], 1, v28
	s_andn2_b64 vcc, exec, s[18:19]
	ds_write2_b32 v30, v26, v27 offset0:2 offset1:3
	s_cbranch_vccnz .LBB0_752
	v_ashrrev_i32_e32 v45, 31, v44
	v_lshl_add_u64 v[26:27], v[44:45], 2, s[10:11]
	v_ashrrev_i32_e32 v43, 31, v42
	s_waitcnt vmcnt(4)
	v_mov_b32_e32 v28, v62
	v_lshl_add_u64 v[26:27], v[42:43], 2, s[10:11]
	v_mov_b32_e32 v26, v63
	v_mad_u64_u32 v[30:31], s[18:19], v41, s13, v[0:1]
	s_movk_i32 s17, 0x104
	s_waitcnt vmcnt(1)
	v_mul_f32_e32 v32, v22, v28
	v_mul_f32_e32 v33, v23, v28
	v_mul_f32_e32 v29, v25, v28
	v_mul_f32_e32 v28, v24, v28
	ds_write2_b32 v30, v32, v33 offset1:1
	ds_write2_b32 v30, v28, v29 offset0:2 offset1:3
	s_cbranch_execnz .LBB0_742

.LBB0_742:
	v_mad_u64_u32 v[22:23], s[18:19], v39, s13, v[0:1]
	s_waitcnt vmcnt(0)
	v_mul_f32_e32 v18, v18, v26
	v_mul_f32_e32 v19, v19, v26
	ds_write2_b32 v22, v18, v19 offset1:1
	v_mul_f32_e32 v18, v20, v26
	v_mul_f32_e32 v19, v21, v26
	s_and_b64 vcc, exec, s[4:5]
	ds_write2_b32 v22, v18, v19 offset0:2 offset1:3
	s_cbranch_vccnz .LBB0_753
	v_ashrrev_i32_e32 v41, 31, v40
	v_lshl_add_u64 v[18:19], v[40:41], 2, s[10:11]
	v_ashrrev_i32_e32 v39, 31, v38
	s_waitcnt vmcnt(2)
	v_mov_b32_e32 v20, v64
	v_lshl_add_u64 v[18:19], v[38:39], 2, s[10:11]
	v_mov_b32_e32 v18, v65
	v_mad_u64_u32 v[22:23], s[18:19], v37, s13, v[0:1]
	s_waitcnt vmcnt(1)
	v_mul_f32_e32 v24, v14, v20
	v_mul_f32_e32 v25, v15, v20
	v_mul_f32_e32 v21, v17, v20
	v_mul_f32_e32 v20, v16, v20
	ds_write2_b32 v22, v24, v25 offset1:1
	ds_write2_b32 v22, v20, v21 offset0:2 offset1:3
	s_cbranch_execnz .LBB0_745

.LBB0_745:
	v_mad_u64_u32 v[14:15], s[18:19], v35, s13, v[0:1]
	s_waitcnt vmcnt(0)
	v_mul_f32_e32 v10, v10, v18
	v_mul_f32_e32 v11, v11, v18
	ds_write2_b32 v14, v10, v11 offset1:1
	v_mul_f32_e32 v10, v12, v18
	v_mul_f32_e32 v11, v13, v18
	s_and_b64 vcc, exec, s[4:5]
	ds_write2_b32 v14, v10, v11 offset0:2 offset1:3
	s_cbranch_vccnz .LBB0_754
	v_ashrrev_i32_e32 v37, 31, v36
	v_lshl_add_u64 v[10:11], v[36:37], 2, s[10:11]
	v_ashrrev_i32_e32 v35, 31, v34
	s_waitcnt vmcnt(0)
	v_mov_b32_e32 v12, v66
	v_lshl_add_u64 v[10:11], v[34:35], 2, s[10:11]
	v_mov_b32_e32 v10, v67
	v_mad_u64_u32 v[14:15], s[4:5], v55, s13, v[0:1]
	s_waitcnt vmcnt(1)
	v_mul_f32_e32 v16, v6, v12
	v_mul_f32_e32 v17, v7, v12
	v_mul_f32_e32 v13, v9, v12
	v_mul_f32_e32 v12, v8, v12
	ds_write2_b32 v14, v16, v17 offset1:1
	ds_write2_b32 v14, v12, v13 offset0:2 offset1:3
	s_cbranch_execnz .LBB0_712
	s_branch .LBB0_755
